# hyena FFT source fetches: issue all of a group's filter/data loads up front into free VGPRs instead of one load+wait per element (both variants), plus row-pass gain hoist
# speedup vs baseline: 1.0368x; 1.0368x over previous
; __device__ __forceinline__ float bf2f(bf16_t b) { return __uint_as_float(((unsigned)b) << 16); }
; __device__ __forceinline__ float2 twid(float turns) { return make_float2(__builtin_amdgcn_cosf(turns), -__builtin_amdgcn_sinf(turns)); }
;   __device__ __forceinline__ float2 operator()(int i) const { const float2 wv = unpk2(Wd[i]); return half ? cmul(wv, twid((float)(i & (L - 1)) * invTurn)) : wv; }
; template <int LOGN, int R, int DLOG, bool INV, int MODE, class F>
; __device__ __forceinline__ void fft_pass(float2* X, const F& f) {
;     ...
;   auto fetch = [&](int g, c32 (&dst)[RAD]) {
;     const int base = gbase(g);
; #pragma unroll
;     for (int j = 0; j < RAD; ++j) { if constexpr (MODE == 1) { const float2 sv = f(base + (j << DLOG)); dst[j] = (c32){sv.x, sv.y}; } }
;   };
;   c32 nxt[RAD];
;   if constexpr (MODE == 1) fetch(tid0, nxt);
;   __device__ __forceinline__ float2 operator()(int i) const {
;     const int ch = i >> lshift, t = i & (L - 1);
;     const float f = bf2f(hf[ch * chstride + t]), bw = bf2f(hb[ch * chstride + (t > 0 ? L - t : 0)]);
;     const float bwm = t > 0 ? bw : 0.f;
;     if (half == 0) return make_float2(f + bwm, 0.f);
;     const float2 tw = twid((float)t * invTurn); const float d = f - bwm; return make_float2(d * tw.x, d * tw.y);
;   }
.LBB0_524:
	v_mov_b32_e32 v66, v196
	s_xor_b64 s[22:23], s[14:15], -1
	v_and_b32_e32 v26, 0x3ff, v66
	v_lshlrev_b32_e32 v32, 1, v26
	v_lshlrev_b32_e32 v207, 1, v26
	v_sub_u32_e32 v208, 0x8000, v207
	v_cmp_eq_u32_e64 s[98:99], 0, v26
	v_mov_b32_e32 v209, v207
	v_add_u32_e32 v211, 0x800, v207
	v_add_u32_e32 v213, 0x1000, v207
	v_add_u32_e32 v215, 0x1800, v207
	v_add_u32_e32 v217, 0x2000, v207
	v_add_u32_e32 v219, 0x2800, v207
	v_add_u32_e32 v221, 0x3000, v207
	v_add_u32_e32 v223, 0x3800, v207
	v_add_u32_e32 v225, 0x4000, v207
	v_add_u32_e32 v227, 0x4800, v207
	v_add_u32_e32 v229, 0x5000, v207
	v_add_u32_e32 v231, 0x5800, v207
	v_add_u32_e32 v233, 0x6000, v207
	v_add_u32_e32 v235, 0x6800, v207
	v_add_u32_e32 v237, 0x7000, v207
	v_add_u32_e32 v239, 0x7800, v207
	v_subrev_u32_e32 v212, 0x800, v208
	v_subrev_u32_e32 v214, 0x1000, v208
	v_subrev_u32_e32 v216, 0x1800, v208
	v_subrev_u32_e32 v218, 0x2000, v208
	v_subrev_u32_e32 v220, 0x2800, v208
	v_subrev_u32_e32 v222, 0x3000, v208
	v_subrev_u32_e32 v224, 0x3800, v208
	v_subrev_u32_e32 v226, 0x4000, v208
	v_subrev_u32_e32 v228, 0x4800, v208
	v_subrev_u32_e32 v230, 0x5000, v208
	v_subrev_u32_e32 v232, 0x5800, v208
	v_subrev_u32_e32 v234, 0x6000, v208
	v_subrev_u32_e32 v236, 0x6800, v208
	v_subrev_u32_e32 v238, 0x7000, v208
	v_subrev_u32_e32 v240, 0x7800, v208
	v_cndmask_b32_e64 v210, v208, 0, s[98:99]
	global_load_ushort v209, v209, s[96:97]
	global_load_ushort v210, v210, s[20:21]
	global_load_ushort v211, v211, s[96:97]
	global_load_ushort v212, v212, s[20:21]
	global_load_ushort v213, v213, s[96:97]
	global_load_ushort v214, v214, s[20:21]
	global_load_ushort v215, v215, s[96:97]
	global_load_ushort v216, v216, s[20:21]
	global_load_ushort v217, v217, s[96:97]
	global_load_ushort v218, v218, s[20:21]
	global_load_ushort v219, v219, s[96:97]
	global_load_ushort v220, v220, s[20:21]
	global_load_ushort v221, v221, s[96:97]
	global_load_ushort v222, v222, s[20:21]
	global_load_ushort v223, v223, s[96:97]
	global_load_ushort v224, v224, s[20:21]
	global_load_ushort v225, v225, s[96:97]
	global_load_ushort v226, v226, s[20:21]
	global_load_ushort v227, v227, s[96:97]
	global_load_ushort v228, v228, s[20:21]
	global_load_ushort v229, v229, s[96:97]
	global_load_ushort v230, v230, s[20:21]
	global_load_ushort v231, v231, s[96:97]
	global_load_ushort v232, v232, s[20:21]
	global_load_ushort v233, v233, s[96:97]
	global_load_ushort v234, v234, s[20:21]
	global_load_ushort v235, v235, s[96:97]
	global_load_ushort v236, v236, s[20:21]
	global_load_ushort v237, v237, s[96:97]
	global_load_ushort v238, v238, s[20:21]
	global_load_ushort v239, v239, s[96:97]
	global_load_ushort v240, v240, s[20:21]
	s_waitcnt vmcnt(31)
	v_mov_b32_e32 v0, v209
	v_cmp_eq_u32_e32 vcc, 0, v26
	s_mov_b64 s[0:1], -1
	s_waitcnt vmcnt(0)
	v_lshlrev_b32_e32 v2, 16, v0
	v_sub_u32_e32 v0, 0x4000, v26
	v_cndmask_b32_e64 v0, v0, 0, vcc
	v_lshlrev_b32_e32 v0, 1, v0
	s_waitcnt vmcnt(30)
	v_mov_b32_e32 v0, v210
	s_waitcnt vmcnt(0)
	v_lshlrev_b32_e32 v0, 16, v0
	v_cndmask_b32_e64 v3, v0, 0, vcc
	s_and_b64 vcc, exec, s[22:23]
	s_cbranch_vccz .LBB0_526
	v_cvt_f32_u32_e32 v0, v26
	v_sub_f32_e32 v5, v2, v3
	s_mov_b64 s[0:1], 0
	v_mul_f32_e32 v0, 0x38000000, v0
	v_cos_f32_e32 v1, v0
	v_sin_f32_e64 v4, -v0
	v_mul_f32_e32 v0, v1, v5
	v_mul_f32_e32 v1, v5, v4

; __device__ __forceinline__ float bf2f(bf16_t b) { return __uint_as_float(((unsigned)b) << 16); }
; __device__ __forceinline__ float2 twid(float turns) { return make_float2(__builtin_amdgcn_cosf(turns), -__builtin_amdgcn_sinf(turns)); }
;   __device__ __forceinline__ float2 operator()(int i) const { const float2 wv = unpk2(Wd[i]); return half ? cmul(wv, twid((float)(i & (L - 1)) * invTurn)) : wv; }
;   __device__ __forceinline__ float2 operator()(int i) const {
;     const int ch = i >> lshift, t = i & (L - 1);
;     const float f = bf2f(hf[ch * chstride + t]), bw = bf2f(hb[ch * chstride + (t > 0 ? L - t : 0)]);
;     const float bwm = t > 0 ? bw : 0.f;
;     if (half == 0) return make_float2(f + bwm, 0.f);
;     const float2 tw = twid((float)t * invTurn); const float d = f - bwm; return make_float2(d * tw.x, d * tw.y);
;   }
.LBB0_528:
	v_lshl_add_u64 v[4:5], s[96:97], 0, v[32:33]
	s_waitcnt vmcnt(29)
	v_mov_b32_e32 v3, v211
	v_or_b32_e32 v2, 0x400, v26
	s_mov_b64 s[0:1], -1
	s_andn2_b64 vcc, exec, s[22:23]
	s_waitcnt vmcnt(0)
	v_lshlrev_b32_e32 v4, 16, v3
	v_sub_u32_e32 v3, 0x4000, v2
	v_lshlrev_b32_e32 v3, 1, v3
	s_waitcnt vmcnt(28)
	v_mov_b32_e32 v3, v212
	s_waitcnt vmcnt(0)
	v_lshlrev_b32_e32 v5, 16, v3
	v_cndmask_b32_e64 v3, 0, 1, s[22:23]
	v_cmp_ne_u32_e64 s[40:41], 1, v3
	s_cbranch_vccnz .LBB0_530
	v_cvt_f32_u32_e32 v2, v2
	v_sub_f32_e32 v7, v4, v5
	s_mov_b64 s[0:1], 0
	v_mul_f32_e32 v2, 0x38000000, v2
	v_cos_f32_e32 v3, v2
	v_sin_f32_e64 v6, -v2
	v_mul_f32_e32 v2, v3, v7
	v_mul_f32_e32 v3, v7, v6

; __device__ __forceinline__ float bf2f(bf16_t b) { return __uint_as_float(((unsigned)b) << 16); }
; __device__ __forceinline__ float2 twid(float turns) { return make_float2(__builtin_amdgcn_cosf(turns), -__builtin_amdgcn_sinf(turns)); }
;   __device__ __forceinline__ float2 operator()(int i) const { const float2 wv = unpk2(Wd[i]); return half ? cmul(wv, twid((float)(i & (L - 1)) * invTurn)) : wv; }
;   __device__ __forceinline__ float2 operator()(int i) const {
;     const int ch = i >> lshift, t = i & (L - 1);
;     const float f = bf2f(hf[ch * chstride + t]), bw = bf2f(hb[ch * chstride + (t > 0 ? L - t : 0)]);
;     const float bwm = t > 0 ? bw : 0.f;
;     if (half == 0) return make_float2(f + bwm, 0.f);
;     const float2 tw = twid((float)t * invTurn); const float d = f - bwm; return make_float2(d * tw.x, d * tw.y);
;   }
.LBB0_532:
	v_or_b32_e32 v4, 0x800, v26
	v_lshlrev_b32_e32 v5, 1, v4
	v_sub_u32_e32 v6, 0x4000, v4
	v_lshlrev_b32_e32 v6, 1, v6
	s_waitcnt vmcnt(27)
	v_mov_b32_e32 v5, v213
	s_nop 0
	s_waitcnt vmcnt(26)
	v_mov_b32_e32 v7, v214
	s_and_b64 vcc, exec, s[40:41]
	s_mov_b64 s[0:1], -1
	s_waitcnt vmcnt(1)
	v_lshlrev_b32_e32 v6, 16, v5
	s_waitcnt vmcnt(0)
	v_lshlrev_b32_e32 v7, 16, v7
	s_cbranch_vccnz .LBB0_534
	v_cvt_f32_u32_e32 v4, v4
	v_sub_f32_e32 v9, v6, v7
	s_mov_b64 s[0:1], 0
	v_mul_f32_e32 v4, 0x38000000, v4
	v_cos_f32_e32 v5, v4
	v_sin_f32_e64 v8, -v4
	v_mul_f32_e32 v4, v5, v9
	v_mul_f32_e32 v5, v9, v8

; __device__ __forceinline__ float bf2f(bf16_t b) { return __uint_as_float(((unsigned)b) << 16); }
; __device__ __forceinline__ float2 twid(float turns) { return make_float2(__builtin_amdgcn_cosf(turns), -__builtin_amdgcn_sinf(turns)); }
;   __device__ __forceinline__ float2 operator()(int i) const { const float2 wv = unpk2(Wd[i]); return half ? cmul(wv, twid((float)(i & (L - 1)) * invTurn)) : wv; }
;   __device__ __forceinline__ float2 operator()(int i) const {
;     const int ch = i >> lshift, t = i & (L - 1);
;     const float f = bf2f(hf[ch * chstride + t]), bw = bf2f(hb[ch * chstride + (t > 0 ? L - t : 0)]);
;     const float bwm = t > 0 ? bw : 0.f;
;     if (half == 0) return make_float2(f + bwm, 0.f);
;     const float2 tw = twid((float)t * invTurn); const float d = f - bwm; return make_float2(d * tw.x, d * tw.y);
;   }
.LBB0_536:
	v_or_b32_e32 v6, 0xc00, v26
	v_lshlrev_b32_e32 v7, 1, v6
	v_sub_u32_e32 v8, 0x4000, v6
	v_lshlrev_b32_e32 v8, 1, v8
	s_waitcnt vmcnt(25)
	v_mov_b32_e32 v7, v215
	s_nop 0
	s_waitcnt vmcnt(24)
	v_mov_b32_e32 v9, v216
	s_and_b64 vcc, exec, s[40:41]
	s_mov_b64 s[0:1], -1
	s_waitcnt vmcnt(1)
	v_lshlrev_b32_e32 v8, 16, v7
	s_waitcnt vmcnt(0)
	v_lshlrev_b32_e32 v9, 16, v9
	s_cbranch_vccnz .LBB0_538
	v_cvt_f32_u32_e32 v6, v6
	v_sub_f32_e32 v11, v8, v9
	s_mov_b64 s[0:1], 0
	v_mul_f32_e32 v6, 0x38000000, v6
	v_cos_f32_e32 v7, v6
	v_sin_f32_e64 v10, -v6
	v_mul_f32_e32 v6, v7, v11
	v_mul_f32_e32 v7, v11, v10

; __device__ __forceinline__ float bf2f(bf16_t b) { return __uint_as_float(((unsigned)b) << 16); }
; __device__ __forceinline__ float2 twid(float turns) { return make_float2(__builtin_amdgcn_cosf(turns), -__builtin_amdgcn_sinf(turns)); }
;   __device__ __forceinline__ float2 operator()(int i) const { const float2 wv = unpk2(Wd[i]); return half ? cmul(wv, twid((float)(i & (L - 1)) * invTurn)) : wv; }
;   __device__ __forceinline__ float2 operator()(int i) const {
;     const int ch = i >> lshift, t = i & (L - 1);
;     const float f = bf2f(hf[ch * chstride + t]), bw = bf2f(hb[ch * chstride + (t > 0 ? L - t : 0)]);
;     const float bwm = t > 0 ? bw : 0.f;
;     if (half == 0) return make_float2(f + bwm, 0.f);
;     const float2 tw = twid((float)t * invTurn); const float d = f - bwm; return make_float2(d * tw.x, d * tw.y);
;   }
.LBB0_540:
	v_or_b32_e32 v8, 0x1000, v26
	v_lshlrev_b32_e32 v9, 1, v8
	v_sub_u32_e32 v10, 0x4000, v8
	v_lshlrev_b32_e32 v10, 1, v10
	s_waitcnt vmcnt(23)
	v_mov_b32_e32 v9, v217
	s_nop 0
	s_waitcnt vmcnt(22)
	v_mov_b32_e32 v11, v218
	s_and_b64 vcc, exec, s[40:41]
	s_mov_b64 s[0:1], -1
	s_waitcnt vmcnt(1)
	v_lshlrev_b32_e32 v10, 16, v9
	s_waitcnt vmcnt(0)
	v_lshlrev_b32_e32 v11, 16, v11
	s_cbranch_vccnz .LBB0_542
	v_cvt_f32_u32_e32 v8, v8
	v_sub_f32_e32 v13, v10, v11
	s_mov_b64 s[0:1], 0
	v_mul_f32_e32 v8, 0x38000000, v8
	v_cos_f32_e32 v9, v8
	v_sin_f32_e64 v12, -v8
	v_mul_f32_e32 v8, v9, v13
	v_mul_f32_e32 v9, v13, v12

; __device__ __forceinline__ float bf2f(bf16_t b) { return __uint_as_float(((unsigned)b) << 16); }
; __device__ __forceinline__ float2 twid(float turns) { return make_float2(__builtin_amdgcn_cosf(turns), -__builtin_amdgcn_sinf(turns)); }
;   __device__ __forceinline__ float2 operator()(int i) const { const float2 wv = unpk2(Wd[i]); return half ? cmul(wv, twid((float)(i & (L - 1)) * invTurn)) : wv; }
;   __device__ __forceinline__ float2 operator()(int i) const {
;     const int ch = i >> lshift, t = i & (L - 1);
;     const float f = bf2f(hf[ch * chstride + t]), bw = bf2f(hb[ch * chstride + (t > 0 ? L - t : 0)]);
;     const float bwm = t > 0 ? bw : 0.f;
;     if (half == 0) return make_float2(f + bwm, 0.f);
;     const float2 tw = twid((float)t * invTurn); const float d = f - bwm; return make_float2(d * tw.x, d * tw.y);
;   }
.LBB0_544:
	v_or_b32_e32 v10, 0x1400, v26
	v_lshlrev_b32_e32 v11, 1, v10
	v_sub_u32_e32 v12, 0x4000, v10
	v_lshlrev_b32_e32 v12, 1, v12
	s_waitcnt vmcnt(21)
	v_mov_b32_e32 v11, v219
	s_nop 0
	s_waitcnt vmcnt(20)
	v_mov_b32_e32 v13, v220
	s_and_b64 vcc, exec, s[40:41]
	s_mov_b64 s[0:1], -1
	s_waitcnt vmcnt(1)
	v_lshlrev_b32_e32 v12, 16, v11
	s_waitcnt vmcnt(0)
	v_lshlrev_b32_e32 v13, 16, v13
	s_cbranch_vccnz .LBB0_546
	v_cvt_f32_u32_e32 v10, v10
	v_sub_f32_e32 v15, v12, v13
	s_mov_b64 s[0:1], 0
	v_mul_f32_e32 v10, 0x38000000, v10
	v_cos_f32_e32 v11, v10
	v_sin_f32_e64 v14, -v10
	v_mul_f32_e32 v10, v11, v15
	v_mul_f32_e32 v11, v15, v14

; __device__ __forceinline__ float bf2f(bf16_t b) { return __uint_as_float(((unsigned)b) << 16); }
; __device__ __forceinline__ float2 twid(float turns) { return make_float2(__builtin_amdgcn_cosf(turns), -__builtin_amdgcn_sinf(turns)); }
;   __device__ __forceinline__ float2 operator()(int i) const { const float2 wv = unpk2(Wd[i]); return half ? cmul(wv, twid((float)(i & (L - 1)) * invTurn)) : wv; }
;   __device__ __forceinline__ float2 operator()(int i) const {
;     const int ch = i >> lshift, t = i & (L - 1);
;     const float f = bf2f(hf[ch * chstride + t]), bw = bf2f(hb[ch * chstride + (t > 0 ? L - t : 0)]);
;     const float bwm = t > 0 ? bw : 0.f;
;     if (half == 0) return make_float2(f + bwm, 0.f);
;     const float2 tw = twid((float)t * invTurn); const float d = f - bwm; return make_float2(d * tw.x, d * tw.y);
;   }
.LBB0_548:
	v_or_b32_e32 v12, 0x1800, v26
	v_lshlrev_b32_e32 v13, 1, v12
	v_sub_u32_e32 v14, 0x4000, v12
	v_lshlrev_b32_e32 v14, 1, v14
	s_waitcnt vmcnt(19)
	v_mov_b32_e32 v13, v221
	s_nop 0
	s_waitcnt vmcnt(18)
	v_mov_b32_e32 v15, v222
	s_and_b64 vcc, exec, s[40:41]
	s_mov_b64 s[0:1], -1
	s_waitcnt vmcnt(1)
	v_lshlrev_b32_e32 v14, 16, v13
	s_waitcnt vmcnt(0)
	v_lshlrev_b32_e32 v15, 16, v15
	s_cbranch_vccnz .LBB0_550
	v_cvt_f32_u32_e32 v12, v12
	v_sub_f32_e32 v17, v14, v15
	s_mov_b64 s[0:1], 0
	v_mul_f32_e32 v12, 0x38000000, v12
	v_cos_f32_e32 v13, v12
	v_sin_f32_e64 v16, -v12
	v_mul_f32_e32 v12, v13, v17
	v_mul_f32_e32 v13, v17, v16

; __device__ __forceinline__ float bf2f(bf16_t b) { return __uint_as_float(((unsigned)b) << 16); }
; __device__ __forceinline__ float2 twid(float turns) { return make_float2(__builtin_amdgcn_cosf(turns), -__builtin_amdgcn_sinf(turns)); }
;   __device__ __forceinline__ float2 operator()(int i) const { const float2 wv = unpk2(Wd[i]); return half ? cmul(wv, twid((float)(i & (L - 1)) * invTurn)) : wv; }
;   __device__ __forceinline__ float2 operator()(int i) const {
;     const int ch = i >> lshift, t = i & (L - 1);
;     const float f = bf2f(hf[ch * chstride + t]), bw = bf2f(hb[ch * chstride + (t > 0 ? L - t : 0)]);
;     const float bwm = t > 0 ? bw : 0.f;
;     if (half == 0) return make_float2(f + bwm, 0.f);
;     const float2 tw = twid((float)t * invTurn); const float d = f - bwm; return make_float2(d * tw.x, d * tw.y);
;   }
.LBB0_552:
	v_or_b32_e32 v14, 0x1c00, v26
	v_lshlrev_b32_e32 v15, 1, v14
	v_sub_u32_e32 v16, 0x4000, v14
	v_lshlrev_b32_e32 v16, 1, v16
	s_waitcnt vmcnt(17)
	v_mov_b32_e32 v15, v223
	s_nop 0
	s_waitcnt vmcnt(16)
	v_mov_b32_e32 v17, v224
	s_and_b64 vcc, exec, s[40:41]
	s_mov_b64 s[0:1], -1
	s_waitcnt vmcnt(1)
	v_lshlrev_b32_e32 v16, 16, v15
	s_waitcnt vmcnt(0)
	v_lshlrev_b32_e32 v17, 16, v17
	s_cbranch_vccnz .LBB0_554
	v_cvt_f32_u32_e32 v14, v14
	v_sub_f32_e32 v19, v16, v17
	s_mov_b64 s[0:1], 0
	v_mul_f32_e32 v14, 0x38000000, v14
	v_cos_f32_e32 v15, v14
	v_sin_f32_e64 v18, -v14
	v_mul_f32_e32 v14, v15, v19
	v_mul_f32_e32 v15, v19, v18

; __device__ __forceinline__ float bf2f(bf16_t b) { return __uint_as_float(((unsigned)b) << 16); }
; __device__ __forceinline__ float2 twid(float turns) { return make_float2(__builtin_amdgcn_cosf(turns), -__builtin_amdgcn_sinf(turns)); }
;   __device__ __forceinline__ float2 operator()(int i) const { const float2 wv = unpk2(Wd[i]); return half ? cmul(wv, twid((float)(i & (L - 1)) * invTurn)) : wv; }
;   __device__ __forceinline__ float2 operator()(int i) const {
;     const int ch = i >> lshift, t = i & (L - 1);
;     const float f = bf2f(hf[ch * chstride + t]), bw = bf2f(hb[ch * chstride + (t > 0 ? L - t : 0)]);
;     const float bwm = t > 0 ? bw : 0.f;
;     if (half == 0) return make_float2(f + bwm, 0.f);
;     const float2 tw = twid((float)t * invTurn); const float d = f - bwm; return make_float2(d * tw.x, d * tw.y);
;   }
.LBB0_556:
	v_or_b32_e32 v16, 0x2000, v26
	v_lshlrev_b32_e32 v17, 1, v16
	v_sub_u32_e32 v18, 0x4000, v16
	v_lshlrev_b32_e32 v18, 1, v18
	s_waitcnt vmcnt(15)
	v_mov_b32_e32 v17, v225
	s_nop 0
	s_waitcnt vmcnt(14)
	v_mov_b32_e32 v19, v226
	s_and_b64 vcc, exec, s[40:41]
	s_mov_b64 s[0:1], -1
	s_waitcnt vmcnt(1)
	v_lshlrev_b32_e32 v18, 16, v17
	s_waitcnt vmcnt(0)
	v_lshlrev_b32_e32 v19, 16, v19
	s_cbranch_vccnz .LBB0_558
	v_cvt_f32_u32_e32 v16, v16
	v_sub_f32_e32 v21, v18, v19
	s_mov_b64 s[0:1], 0
	v_mul_f32_e32 v16, 0x38000000, v16
	v_cos_f32_e32 v17, v16
	v_sin_f32_e64 v20, -v16
	v_mul_f32_e32 v16, v17, v21
	v_mul_f32_e32 v17, v21, v20

; __device__ __forceinline__ float bf2f(bf16_t b) { return __uint_as_float(((unsigned)b) << 16); }
; __device__ __forceinline__ float2 twid(float turns) { return make_float2(__builtin_amdgcn_cosf(turns), -__builtin_amdgcn_sinf(turns)); }
;   __device__ __forceinline__ float2 operator()(int i) const { const float2 wv = unpk2(Wd[i]); return half ? cmul(wv, twid((float)(i & (L - 1)) * invTurn)) : wv; }
;   __device__ __forceinline__ float2 operator()(int i) const {
;     const int ch = i >> lshift, t = i & (L - 1);
;     const float f = bf2f(hf[ch * chstride + t]), bw = bf2f(hb[ch * chstride + (t > 0 ? L - t : 0)]);
;     const float bwm = t > 0 ? bw : 0.f;
;     if (half == 0) return make_float2(f + bwm, 0.f);
;     const float2 tw = twid((float)t * invTurn); const float d = f - bwm; return make_float2(d * tw.x, d * tw.y);
;   }
.LBB0_560:
	v_or_b32_e32 v18, 0x2400, v26
	v_lshlrev_b32_e32 v19, 1, v18
	v_sub_u32_e32 v20, 0x4000, v18
	v_lshlrev_b32_e32 v20, 1, v20
	s_waitcnt vmcnt(13)
	v_mov_b32_e32 v19, v227
	s_nop 0
	s_waitcnt vmcnt(12)
	v_mov_b32_e32 v21, v228
	s_and_b64 vcc, exec, s[40:41]
	s_mov_b64 s[0:1], -1
	s_waitcnt vmcnt(1)
	v_lshlrev_b32_e32 v20, 16, v19
	s_waitcnt vmcnt(0)
	v_lshlrev_b32_e32 v21, 16, v21
	s_cbranch_vccnz .LBB0_562
	v_cvt_f32_u32_e32 v18, v18
	v_sub_f32_e32 v23, v20, v21
	s_mov_b64 s[0:1], 0
	v_mul_f32_e32 v18, 0x38000000, v18
	v_cos_f32_e32 v19, v18
	v_sin_f32_e64 v22, -v18
	v_mul_f32_e32 v18, v19, v23
	v_mul_f32_e32 v19, v23, v22

; __device__ __forceinline__ float bf2f(bf16_t b) { return __uint_as_float(((unsigned)b) << 16); }
; __device__ __forceinline__ float2 twid(float turns) { return make_float2(__builtin_amdgcn_cosf(turns), -__builtin_amdgcn_sinf(turns)); }
;   __device__ __forceinline__ float2 operator()(int i) const { const float2 wv = unpk2(Wd[i]); return half ? cmul(wv, twid((float)(i & (L - 1)) * invTurn)) : wv; }
;   __device__ __forceinline__ float2 operator()(int i) const {
;     const int ch = i >> lshift, t = i & (L - 1);
;     const float f = bf2f(hf[ch * chstride + t]), bw = bf2f(hb[ch * chstride + (t > 0 ? L - t : 0)]);
;     const float bwm = t > 0 ? bw : 0.f;
;     if (half == 0) return make_float2(f + bwm, 0.f);
;     const float2 tw = twid((float)t * invTurn); const float d = f - bwm; return make_float2(d * tw.x, d * tw.y);
;   }
.LBB0_564:
	v_or_b32_e32 v20, 0x2800, v26
	v_lshlrev_b32_e32 v21, 1, v20
	v_sub_u32_e32 v22, 0x4000, v20
	v_lshlrev_b32_e32 v22, 1, v22
	s_waitcnt vmcnt(11)
	v_mov_b32_e32 v21, v229
	s_nop 0
	s_waitcnt vmcnt(10)
	v_mov_b32_e32 v23, v230
	s_and_b64 vcc, exec, s[40:41]
	s_mov_b64 s[0:1], -1
	s_waitcnt vmcnt(1)
	v_lshlrev_b32_e32 v22, 16, v21
	s_waitcnt vmcnt(0)
	v_lshlrev_b32_e32 v23, 16, v23
	s_cbranch_vccnz .LBB0_566
	v_cvt_f32_u32_e32 v20, v20
	v_sub_f32_e32 v25, v22, v23
	s_mov_b64 s[0:1], 0
	v_mul_f32_e32 v20, 0x38000000, v20
	v_cos_f32_e32 v21, v20
	v_sin_f32_e64 v24, -v20
	v_mul_f32_e32 v20, v21, v25
	v_mul_f32_e32 v21, v25, v24

; __device__ __forceinline__ float bf2f(bf16_t b) { return __uint_as_float(((unsigned)b) << 16); }
; __device__ __forceinline__ float2 twid(float turns) { return make_float2(__builtin_amdgcn_cosf(turns), -__builtin_amdgcn_sinf(turns)); }
;   __device__ __forceinline__ float2 operator()(int i) const { const float2 wv = unpk2(Wd[i]); return half ? cmul(wv, twid((float)(i & (L - 1)) * invTurn)) : wv; }
;   __device__ __forceinline__ float2 operator()(int i) const {
;     const int ch = i >> lshift, t = i & (L - 1);
;     const float f = bf2f(hf[ch * chstride + t]), bw = bf2f(hb[ch * chstride + (t > 0 ? L - t : 0)]);
;     const float bwm = t > 0 ? bw : 0.f;
;     if (half == 0) return make_float2(f + bwm, 0.f);
;     const float2 tw = twid((float)t * invTurn); const float d = f - bwm; return make_float2(d * tw.x, d * tw.y);
;   }
.LBB0_568:
	v_or_b32_e32 v22, 0x2c00, v26
	v_lshlrev_b32_e32 v23, 1, v22
	v_sub_u32_e32 v24, 0x4000, v22
	v_lshlrev_b32_e32 v24, 1, v24
	s_waitcnt vmcnt(9)
	v_mov_b32_e32 v23, v231
	s_nop 0
	s_waitcnt vmcnt(8)
	v_mov_b32_e32 v25, v232
	s_and_b64 vcc, exec, s[40:41]
	s_mov_b64 s[0:1], -1
	s_waitcnt vmcnt(1)
	v_lshlrev_b32_e32 v24, 16, v23
	s_waitcnt vmcnt(0)
	v_lshlrev_b32_e32 v25, 16, v25
	s_cbranch_vccnz .LBB0_570
	v_cvt_f32_u32_e32 v22, v22
	v_sub_f32_e32 v28, v24, v25
	s_mov_b64 s[0:1], 0
	v_mul_f32_e32 v22, 0x38000000, v22
	v_cos_f32_e32 v23, v22
	v_sin_f32_e64 v27, -v22
	v_mul_f32_e32 v22, v23, v28
	v_mul_f32_e32 v23, v28, v27

; __device__ __forceinline__ float bf2f(bf16_t b) { return __uint_as_float(((unsigned)b) << 16); }
; __device__ __forceinline__ float2 twid(float turns) { return make_float2(__builtin_amdgcn_cosf(turns), -__builtin_amdgcn_sinf(turns)); }
;   __device__ __forceinline__ float2 operator()(int i) const { const float2 wv = unpk2(Wd[i]); return half ? cmul(wv, twid((float)(i & (L - 1)) * invTurn)) : wv; }
;   __device__ __forceinline__ float2 operator()(int i) const {
;     const int ch = i >> lshift, t = i & (L - 1);
;     const float f = bf2f(hf[ch * chstride + t]), bw = bf2f(hb[ch * chstride + (t > 0 ? L - t : 0)]);
;     const float bwm = t > 0 ? bw : 0.f;
;     if (half == 0) return make_float2(f + bwm, 0.f);
;     const float2 tw = twid((float)t * invTurn); const float d = f - bwm; return make_float2(d * tw.x, d * tw.y);
;   }
.LBB0_572:
	v_or_b32_e32 v24, 0x3000, v26
	v_lshlrev_b32_e32 v25, 1, v24
	v_sub_u32_e32 v27, 0x4000, v24
	v_lshlrev_b32_e32 v27, 1, v27
	s_waitcnt vmcnt(7)
	v_mov_b32_e32 v25, v233
	s_nop 0
	s_waitcnt vmcnt(6)
	v_mov_b32_e32 v28, v234
	s_and_b64 vcc, exec, s[40:41]
	s_mov_b64 s[0:1], -1
	s_waitcnt vmcnt(1)
	v_lshlrev_b32_e32 v27, 16, v25
	s_waitcnt vmcnt(0)
	v_lshlrev_b32_e32 v28, 16, v28
	s_cbranch_vccnz .LBB0_574
	v_cvt_f32_u32_e32 v24, v24
	v_sub_f32_e32 v30, v27, v28
	s_mov_b64 s[0:1], 0
	v_mul_f32_e32 v24, 0x38000000, v24
	v_cos_f32_e32 v25, v24
	v_sin_f32_e64 v29, -v24
	v_mul_f32_e32 v24, v25, v30
	v_mul_f32_e32 v25, v30, v29

; __device__ __forceinline__ float bf2f(bf16_t b) { return __uint_as_float(((unsigned)b) << 16); }
; __device__ __forceinline__ float2 twid(float turns) { return make_float2(__builtin_amdgcn_cosf(turns), -__builtin_amdgcn_sinf(turns)); }
;   __device__ __forceinline__ float2 operator()(int i) const { const float2 wv = unpk2(Wd[i]); return half ? cmul(wv, twid((float)(i & (L - 1)) * invTurn)) : wv; }
;   __device__ __forceinline__ float2 operator()(int i) const {
;     const int ch = i >> lshift, t = i & (L - 1);
;     const float f = bf2f(hf[ch * chstride + t]), bw = bf2f(hb[ch * chstride + (t > 0 ? L - t : 0)]);
;     const float bwm = t > 0 ? bw : 0.f;
;     if (half == 0) return make_float2(f + bwm, 0.f);
;     const float2 tw = twid((float)t * invTurn); const float d = f - bwm; return make_float2(d * tw.x, d * tw.y);
;   }
.LBB0_576:
	v_or_b32_e32 v28, 0x3400, v26
	v_sub_u32_e32 v29, 0x4000, v28
	v_lshlrev_b32_e32 v27, 1, v28
	v_lshlrev_b32_e32 v29, 1, v29
	s_waitcnt vmcnt(5)
	v_mov_b32_e32 v27, v235
	s_nop 0
	s_waitcnt vmcnt(4)
	v_mov_b32_e32 v29, v236
	s_and_b64 vcc, exec, s[40:41]
	s_mov_b64 s[0:1], -1
	s_waitcnt vmcnt(1)
	v_lshlrev_b32_e32 v27, 16, v27
	s_waitcnt vmcnt(0)
	v_lshlrev_b32_e32 v30, 16, v29
	s_cbranch_vccnz .LBB0_578
	v_cvt_f32_u32_e32 v28, v28
	v_sub_f32_e32 v32, v27, v30
	s_mov_b64 s[0:1], 0
	v_mul_f32_e32 v28, 0x38000000, v28
	v_cos_f32_e32 v29, v28
	v_sin_f32_e64 v31, -v28
	v_mul_f32_e32 v28, v29, v32
	v_mul_f32_e32 v29, v32, v31

; __device__ __forceinline__ float bf2f(bf16_t b) { return __uint_as_float(((unsigned)b) << 16); }
; __device__ __forceinline__ float2 twid(float turns) { return make_float2(__builtin_amdgcn_cosf(turns), -__builtin_amdgcn_sinf(turns)); }
;   __device__ __forceinline__ float2 operator()(int i) const { const float2 wv = unpk2(Wd[i]); return half ? cmul(wv, twid((float)(i & (L - 1)) * invTurn)) : wv; }
;   __device__ __forceinline__ float2 operator()(int i) const {
;     const int ch = i >> lshift, t = i & (L - 1);
;     const float f = bf2f(hf[ch * chstride + t]), bw = bf2f(hb[ch * chstride + (t > 0 ? L - t : 0)]);
;     const float bwm = t > 0 ? bw : 0.f;
;     if (half == 0) return make_float2(f + bwm, 0.f);
;     const float2 tw = twid((float)t * invTurn); const float d = f - bwm; return make_float2(d * tw.x, d * tw.y);
;   }
.LBB0_580:
	v_or_b32_e32 v30, 0x3800, v26
	v_sub_u32_e32 v31, 0x4000, v30
	v_lshlrev_b32_e32 v27, 1, v30
	v_lshlrev_b32_e32 v31, 1, v31
	s_waitcnt vmcnt(3)
	v_mov_b32_e32 v27, v237
	s_nop 0
	s_waitcnt vmcnt(2)
	v_mov_b32_e32 v31, v238
	s_and_b64 vcc, exec, s[40:41]
	s_mov_b64 s[0:1], -1
	s_waitcnt vmcnt(1)
	v_lshlrev_b32_e32 v27, 16, v27
	s_waitcnt vmcnt(0)
	v_lshlrev_b32_e32 v32, 16, v31
	s_cbranch_vccnz .LBB0_582
	v_cvt_f32_u32_e32 v30, v30
	v_sub_f32_e32 v35, v27, v32
	s_mov_b64 s[0:1], 0
	v_mul_f32_e32 v30, 0x38000000, v30
	v_cos_f32_e32 v31, v30
	v_sin_f32_e64 v34, -v30
	v_mul_f32_e32 v30, v31, v35
	v_mul_f32_e32 v31, v35, v34

; __device__ __forceinline__ float bf2f(bf16_t b) { return __uint_as_float(((unsigned)b) << 16); }
; __device__ __forceinline__ float2 twid(float turns) { return make_float2(__builtin_amdgcn_cosf(turns), -__builtin_amdgcn_sinf(turns)); }
;   __device__ __forceinline__ float2 operator()(int i) const { const float2 wv = unpk2(Wd[i]); return half ? cmul(wv, twid((float)(i & (L - 1)) * invTurn)) : wv; }
;   __device__ __forceinline__ float2 operator()(int i) const {
;     const int ch = i >> lshift, t = i & (L - 1);
;     const float f = bf2f(hf[ch * chstride + t]), bw = bf2f(hb[ch * chstride + (t > 0 ? L - t : 0)]);
;     const float bwm = t > 0 ? bw : 0.f;
;     if (half == 0) return make_float2(f + bwm, 0.f);
;     const float2 tw = twid((float)t * invTurn); const float d = f - bwm; return make_float2(d * tw.x, d * tw.y);
;   }
.LBB0_584:
	v_or_b32_e32 v32, 0x3c00, v26
	v_sub_u32_e32 v27, 0x4000, v32
	v_lshlrev_b32_e32 v26, 1, v32
	v_lshlrev_b32_e32 v27, 1, v27
	s_waitcnt vmcnt(1)
	v_mov_b32_e32 v26, v239
	s_nop 0
	s_waitcnt vmcnt(0)
	v_mov_b32_e32 v27, v240
	s_and_b64 vcc, exec, s[40:41]
	s_mov_b64 s[0:1], -1
	s_waitcnt vmcnt(1)
	v_lshlrev_b32_e32 v26, 16, v26
	s_waitcnt vmcnt(0)
	v_lshlrev_b32_e32 v27, 16, v27
	s_cbranch_vccnz .LBB0_587
	v_cvt_f32_u32_e32 v32, v32
	v_sub_f32_e32 v35, v26, v27
	v_mul_f32_e32 v32, 0x38000000, v32
	v_cos_f32_e32 v34, v32
	v_sin_f32_e64 v32, -v32
	v_mul_f32_e32 v34, v34, v35
	v_mul_f32_e32 v35, v35, v32
	s_cbranch_execz .LBB0_588

; __device__ __forceinline__ float bf2f(bf16_t b) { return __uint_as_float(((unsigned)b) << 16); }
; __device__ __forceinline__ float2 twid(float turns) { return make_float2(__builtin_amdgcn_cosf(turns), -__builtin_amdgcn_sinf(turns)); }
;   __device__ __forceinline__ float2 operator()(int i) const { const float2 wv = unpk2(Wd[i]); return half ? cmul(wv, twid((float)(i & (L - 1)) * invTurn)) : wv; }
; template <int LOGN, int R, int DLOG, bool INV, int MODE, class F>
; __device__ __forceinline__ void fft_pass(float2* X, const F& f) {
;     ...
;   for (int g = tid0; g < NGR; g += 512) {
;     const int lo = g & (dmin - 1), base = gbase(g), pb = phys(base);
;     c32 v[RAD];
;     if constexpr (MODE == 1) {
; #pragma unroll
;       for (int j = 0; j < RAD; ++j) v[j] = nxt[j];
;       if (g + 512 < NGR) fetch(g + 512, nxt);
;   __device__ __forceinline__ float2 operator()(int i) const {
;     const int ch = i >> lshift, t = i & (L - 1);
;     const float f = bf2f(hf[ch * chstride + t]), bw = bf2f(hb[ch * chstride + (t > 0 ? L - t : 0)]);
;     const float bwm = t > 0 ? bw : 0.f;
;     if (half == 0) return make_float2(f + bwm, 0.f);
;     const float2 tw = twid((float)t * invTurn); const float d = f - bwm; return make_float2(d * tw.x, d * tw.y);
;   }
.LBB0_591:
	v_add_u32_e32 v68, 0x200, v66
	v_cmp_gt_i32_e32 vcc, s33, v66
	v_cmp_lt_i32_e64 s[42:43], s12, v66
	s_and_saveexec_b64 s[24:25], vcc
	s_cbranch_execz .LBB0_590
	v_and_b32_e32 v64, 0x3ff, v68
	v_lshlrev_b32_e32 v32, 1, v64
	v_lshlrev_b32_e32 v207, 1, v64
	v_sub_u32_e32 v208, 0x8000, v207
	v_cmp_eq_u32_e64 s[98:99], 0, v64
	v_mov_b32_e32 v209, v207
	v_add_u32_e32 v211, 0x800, v207
	v_add_u32_e32 v213, 0x1000, v207
	v_add_u32_e32 v215, 0x1800, v207
	v_add_u32_e32 v217, 0x2000, v207
	v_add_u32_e32 v219, 0x2800, v207
	v_add_u32_e32 v221, 0x3000, v207
	v_add_u32_e32 v223, 0x3800, v207
	v_add_u32_e32 v225, 0x4000, v207
	v_add_u32_e32 v227, 0x4800, v207
	v_add_u32_e32 v229, 0x5000, v207
	v_add_u32_e32 v231, 0x5800, v207
	v_add_u32_e32 v233, 0x6000, v207
	v_add_u32_e32 v235, 0x6800, v207
	v_add_u32_e32 v237, 0x7000, v207
	v_add_u32_e32 v239, 0x7800, v207
	v_subrev_u32_e32 v212, 0x800, v208
	v_subrev_u32_e32 v214, 0x1000, v208
	v_subrev_u32_e32 v216, 0x1800, v208
	v_subrev_u32_e32 v218, 0x2000, v208
	v_subrev_u32_e32 v220, 0x2800, v208
	v_subrev_u32_e32 v222, 0x3000, v208
	v_subrev_u32_e32 v224, 0x3800, v208
	v_subrev_u32_e32 v226, 0x4000, v208
	v_subrev_u32_e32 v228, 0x4800, v208
	v_subrev_u32_e32 v230, 0x5000, v208
	v_subrev_u32_e32 v232, 0x5800, v208
	v_subrev_u32_e32 v234, 0x6000, v208
	v_subrev_u32_e32 v236, 0x6800, v208
	v_subrev_u32_e32 v238, 0x7000, v208
	v_subrev_u32_e32 v240, 0x7800, v208
	v_cndmask_b32_e64 v210, v208, 0, s[98:99]
	global_load_ushort v209, v209, s[96:97]
	global_load_ushort v210, v210, s[20:21]
	global_load_ushort v211, v211, s[96:97]
	global_load_ushort v212, v212, s[20:21]
	global_load_ushort v213, v213, s[96:97]
	global_load_ushort v214, v214, s[20:21]
	global_load_ushort v215, v215, s[96:97]
	global_load_ushort v216, v216, s[20:21]
	global_load_ushort v217, v217, s[96:97]
	global_load_ushort v218, v218, s[20:21]
	global_load_ushort v219, v219, s[96:97]
	global_load_ushort v220, v220, s[20:21]
	global_load_ushort v221, v221, s[96:97]
	global_load_ushort v222, v222, s[20:21]
	global_load_ushort v223, v223, s[96:97]
	global_load_ushort v224, v224, s[20:21]
	global_load_ushort v225, v225, s[96:97]
	global_load_ushort v226, v226, s[20:21]
	global_load_ushort v227, v227, s[96:97]
	global_load_ushort v228, v228, s[20:21]
	global_load_ushort v229, v229, s[96:97]
	global_load_ushort v230, v230, s[20:21]
	global_load_ushort v231, v231, s[96:97]
	global_load_ushort v232, v232, s[20:21]
	global_load_ushort v233, v233, s[96:97]
	global_load_ushort v234, v234, s[20:21]
	global_load_ushort v235, v235, s[96:97]
	global_load_ushort v236, v236, s[20:21]
	global_load_ushort v237, v237, s[96:97]
	global_load_ushort v238, v238, s[20:21]
	global_load_ushort v239, v239, s[96:97]
	global_load_ushort v240, v240, s[20:21]
	s_waitcnt vmcnt(31)
	v_mov_b32_e32 v26, v209
	v_cmp_eq_u32_e32 vcc, 0, v64
	s_mov_b64 s[26:27], -1
	s_waitcnt vmcnt(0)
	v_lshlrev_b32_e32 v36, 16, v26
	v_sub_u32_e32 v26, 0x4000, v64
	v_cndmask_b32_e64 v26, v26, 0, vcc
	v_lshlrev_b32_e32 v26, 1, v26
	s_waitcnt vmcnt(30)
	v_mov_b32_e32 v26, v210
	s_waitcnt vmcnt(0)
	v_lshlrev_b32_e32 v26, 16, v26
	v_cndmask_b32_e64 v37, v26, 0, vcc
	s_and_b64 vcc, exec, s[22:23]
	s_cbranch_vccz .LBB0_594
	v_cvt_f32_u32_e32 v26, v64
	v_sub_f32_e32 v39, v36, v37
	s_mov_b64 s[26:27], 0
	v_mul_f32_e32 v26, 0x38000000, v26
	v_cos_f32_e32 v27, v26
	v_sin_f32_e64 v38, -v26
	v_mul_f32_e32 v26, v27, v39
	v_mul_f32_e32 v27, v39, v38

; __device__ __forceinline__ float bf2f(bf16_t b) { return __uint_as_float(((unsigned)b) << 16); }
; __device__ __forceinline__ float2 twid(float turns) { return make_float2(__builtin_amdgcn_cosf(turns), -__builtin_amdgcn_sinf(turns)); }
;   __device__ __forceinline__ float2 operator()(int i) const { const float2 wv = unpk2(Wd[i]); return half ? cmul(wv, twid((float)(i & (L - 1)) * invTurn)) : wv; }
;   __device__ __forceinline__ float2 operator()(int i) const {
;     const int ch = i >> lshift, t = i & (L - 1);
;     const float f = bf2f(hf[ch * chstride + t]), bw = bf2f(hb[ch * chstride + (t > 0 ? L - t : 0)]);
;     const float bwm = t > 0 ? bw : 0.f;
;     if (half == 0) return make_float2(f + bwm, 0.f);
;     const float2 tw = twid((float)t * invTurn); const float d = f - bwm; return make_float2(d * tw.x, d * tw.y);
;   }
.LBB0_596:
	v_or_b32_e32 v36, 0x400, v64
	v_sub_u32_e32 v37, 0x4000, v36
	v_lshl_add_u64 v[38:39], s[96:97], 0, v[32:33]
	v_lshlrev_b32_e32 v37, 1, v37
	s_waitcnt vmcnt(29)
	v_mov_b32_e32 v32, v211
	s_mov_b64 s[26:27], -1
	s_waitcnt vmcnt(28)
	v_mov_b32_e32 v37, v212
	s_and_b64 vcc, exec, s[40:41]
	s_waitcnt vmcnt(1)
	v_lshlrev_b32_e32 v32, 16, v32
	s_waitcnt vmcnt(0)
	v_lshlrev_b32_e32 v38, 16, v37
	s_cbranch_vccnz .LBB0_598
	v_cvt_f32_u32_e32 v36, v36
	v_sub_f32_e32 v40, v32, v38
	s_mov_b64 s[26:27], 0
	v_mul_f32_e32 v36, 0x38000000, v36
	v_cos_f32_e32 v37, v36
	v_sin_f32_e64 v39, -v36
	v_mul_f32_e32 v36, v37, v40
	v_mul_f32_e32 v37, v40, v39

; __device__ __forceinline__ float bf2f(bf16_t b) { return __uint_as_float(((unsigned)b) << 16); }
; __device__ __forceinline__ float2 twid(float turns) { return make_float2(__builtin_amdgcn_cosf(turns), -__builtin_amdgcn_sinf(turns)); }
;   __device__ __forceinline__ float2 operator()(int i) const { const float2 wv = unpk2(Wd[i]); return half ? cmul(wv, twid((float)(i & (L - 1)) * invTurn)) : wv; }
;   __device__ __forceinline__ float2 operator()(int i) const {
;     const int ch = i >> lshift, t = i & (L - 1);
;     const float f = bf2f(hf[ch * chstride + t]), bw = bf2f(hb[ch * chstride + (t > 0 ? L - t : 0)]);
;     const float bwm = t > 0 ? bw : 0.f;
;     if (half == 0) return make_float2(f + bwm, 0.f);
;     const float2 tw = twid((float)t * invTurn); const float d = f - bwm; return make_float2(d * tw.x, d * tw.y);
;   }
.LBB0_600:
	v_or_b32_e32 v38, 0x800, v64
	v_sub_u32_e32 v39, 0x4000, v38
	v_lshlrev_b32_e32 v32, 1, v38
	v_lshlrev_b32_e32 v39, 1, v39
	s_waitcnt vmcnt(27)
	v_mov_b32_e32 v32, v213
	s_nop 0
	s_waitcnt vmcnt(26)
	v_mov_b32_e32 v39, v214
	s_and_b64 vcc, exec, s[40:41]
	s_mov_b64 s[26:27], -1
	s_waitcnt vmcnt(1)
	v_lshlrev_b32_e32 v32, 16, v32
	s_waitcnt vmcnt(0)
	v_lshlrev_b32_e32 v40, 16, v39
	s_cbranch_vccnz .LBB0_602
	v_cvt_f32_u32_e32 v38, v38
	v_sub_f32_e32 v42, v32, v40
	s_mov_b64 s[26:27], 0
	v_mul_f32_e32 v38, 0x38000000, v38
	v_cos_f32_e32 v39, v38
	v_sin_f32_e64 v41, -v38
	v_mul_f32_e32 v38, v39, v42
	v_mul_f32_e32 v39, v42, v41

; __device__ __forceinline__ float bf2f(bf16_t b) { return __uint_as_float(((unsigned)b) << 16); }
; __device__ __forceinline__ float2 twid(float turns) { return make_float2(__builtin_amdgcn_cosf(turns), -__builtin_amdgcn_sinf(turns)); }
;   __device__ __forceinline__ float2 operator()(int i) const { const float2 wv = unpk2(Wd[i]); return half ? cmul(wv, twid((float)(i & (L - 1)) * invTurn)) : wv; }
;   __device__ __forceinline__ float2 operator()(int i) const {
;     const int ch = i >> lshift, t = i & (L - 1);
;     const float f = bf2f(hf[ch * chstride + t]), bw = bf2f(hb[ch * chstride + (t > 0 ? L - t : 0)]);
;     const float bwm = t > 0 ? bw : 0.f;
;     if (half == 0) return make_float2(f + bwm, 0.f);
;     const float2 tw = twid((float)t * invTurn); const float d = f - bwm; return make_float2(d * tw.x, d * tw.y);
;   }
.LBB0_604:
	v_or_b32_e32 v40, 0xc00, v64
	v_sub_u32_e32 v41, 0x4000, v40
	v_lshlrev_b32_e32 v32, 1, v40
	v_lshlrev_b32_e32 v41, 1, v41
	s_waitcnt vmcnt(25)
	v_mov_b32_e32 v32, v215
	s_nop 0
	s_waitcnt vmcnt(24)
	v_mov_b32_e32 v41, v216
	s_and_b64 vcc, exec, s[40:41]
	s_mov_b64 s[26:27], -1
	s_waitcnt vmcnt(1)
	v_lshlrev_b32_e32 v32, 16, v32
	s_waitcnt vmcnt(0)
	v_lshlrev_b32_e32 v42, 16, v41
	s_cbranch_vccnz .LBB0_606
	v_cvt_f32_u32_e32 v40, v40
	v_sub_f32_e32 v44, v32, v42
	s_mov_b64 s[26:27], 0
	v_mul_f32_e32 v40, 0x38000000, v40
	v_cos_f32_e32 v41, v40
	v_sin_f32_e64 v43, -v40
	v_mul_f32_e32 v40, v41, v44
	v_mul_f32_e32 v41, v44, v43

; __device__ __forceinline__ float bf2f(bf16_t b) { return __uint_as_float(((unsigned)b) << 16); }
; __device__ __forceinline__ float2 twid(float turns) { return make_float2(__builtin_amdgcn_cosf(turns), -__builtin_amdgcn_sinf(turns)); }
;   __device__ __forceinline__ float2 operator()(int i) const { const float2 wv = unpk2(Wd[i]); return half ? cmul(wv, twid((float)(i & (L - 1)) * invTurn)) : wv; }
;   __device__ __forceinline__ float2 operator()(int i) const {
;     const int ch = i >> lshift, t = i & (L - 1);
;     const float f = bf2f(hf[ch * chstride + t]), bw = bf2f(hb[ch * chstride + (t > 0 ? L - t : 0)]);
;     const float bwm = t > 0 ? bw : 0.f;
;     if (half == 0) return make_float2(f + bwm, 0.f);
;     const float2 tw = twid((float)t * invTurn); const float d = f - bwm; return make_float2(d * tw.x, d * tw.y);
;   }
.LBB0_608:
	v_or_b32_e32 v42, 0x1000, v64
	v_sub_u32_e32 v43, 0x4000, v42
	v_lshlrev_b32_e32 v32, 1, v42
	v_lshlrev_b32_e32 v43, 1, v43
	s_waitcnt vmcnt(23)
	v_mov_b32_e32 v32, v217
	s_nop 0
	s_waitcnt vmcnt(22)
	v_mov_b32_e32 v43, v218
	s_and_b64 vcc, exec, s[40:41]
	s_mov_b64 s[26:27], -1
	s_waitcnt vmcnt(1)
	v_lshlrev_b32_e32 v32, 16, v32
	s_waitcnt vmcnt(0)
	v_lshlrev_b32_e32 v44, 16, v43
	s_cbranch_vccnz .LBB0_610
	v_cvt_f32_u32_e32 v42, v42
	v_sub_f32_e32 v46, v32, v44
	s_mov_b64 s[26:27], 0
	v_mul_f32_e32 v42, 0x38000000, v42
	v_cos_f32_e32 v43, v42
	v_sin_f32_e64 v45, -v42
	v_mul_f32_e32 v42, v43, v46
	v_mul_f32_e32 v43, v46, v45

; __device__ __forceinline__ float bf2f(bf16_t b) { return __uint_as_float(((unsigned)b) << 16); }
; __device__ __forceinline__ float2 twid(float turns) { return make_float2(__builtin_amdgcn_cosf(turns), -__builtin_amdgcn_sinf(turns)); }
;   __device__ __forceinline__ float2 operator()(int i) const { const float2 wv = unpk2(Wd[i]); return half ? cmul(wv, twid((float)(i & (L - 1)) * invTurn)) : wv; }
;   __device__ __forceinline__ float2 operator()(int i) const {
;     const int ch = i >> lshift, t = i & (L - 1);
;     const float f = bf2f(hf[ch * chstride + t]), bw = bf2f(hb[ch * chstride + (t > 0 ? L - t : 0)]);
;     const float bwm = t > 0 ? bw : 0.f;
;     if (half == 0) return make_float2(f + bwm, 0.f);
;     const float2 tw = twid((float)t * invTurn); const float d = f - bwm; return make_float2(d * tw.x, d * tw.y);
;   }
.LBB0_612:
	v_or_b32_e32 v44, 0x1400, v64
	v_sub_u32_e32 v45, 0x4000, v44
	v_lshlrev_b32_e32 v32, 1, v44
	v_lshlrev_b32_e32 v45, 1, v45
	s_waitcnt vmcnt(21)
	v_mov_b32_e32 v32, v219
	s_nop 0
	s_waitcnt vmcnt(20)
	v_mov_b32_e32 v45, v220
	s_and_b64 vcc, exec, s[40:41]
	s_mov_b64 s[26:27], -1
	s_waitcnt vmcnt(1)
	v_lshlrev_b32_e32 v32, 16, v32
	s_waitcnt vmcnt(0)
	v_lshlrev_b32_e32 v46, 16, v45
	s_cbranch_vccnz .LBB0_614
	v_cvt_f32_u32_e32 v44, v44
	v_sub_f32_e32 v48, v32, v46
	s_mov_b64 s[26:27], 0
	v_mul_f32_e32 v44, 0x38000000, v44
	v_cos_f32_e32 v45, v44
	v_sin_f32_e64 v47, -v44
	v_mul_f32_e32 v44, v45, v48
	v_mul_f32_e32 v45, v48, v47

; __device__ __forceinline__ float bf2f(bf16_t b) { return __uint_as_float(((unsigned)b) << 16); }
; __device__ __forceinline__ float2 twid(float turns) { return make_float2(__builtin_amdgcn_cosf(turns), -__builtin_amdgcn_sinf(turns)); }
;   __device__ __forceinline__ float2 operator()(int i) const { const float2 wv = unpk2(Wd[i]); return half ? cmul(wv, twid((float)(i & (L - 1)) * invTurn)) : wv; }
;   __device__ __forceinline__ float2 operator()(int i) const {
;     const int ch = i >> lshift, t = i & (L - 1);
;     const float f = bf2f(hf[ch * chstride + t]), bw = bf2f(hb[ch * chstride + (t > 0 ? L - t : 0)]);
;     const float bwm = t > 0 ? bw : 0.f;
;     if (half == 0) return make_float2(f + bwm, 0.f);
;     const float2 tw = twid((float)t * invTurn); const float d = f - bwm; return make_float2(d * tw.x, d * tw.y);
;   }
.LBB0_616:
	v_or_b32_e32 v46, 0x1800, v64
	v_sub_u32_e32 v47, 0x4000, v46
	v_lshlrev_b32_e32 v32, 1, v46
	v_lshlrev_b32_e32 v47, 1, v47
	s_waitcnt vmcnt(19)
	v_mov_b32_e32 v32, v221
	s_nop 0
	s_waitcnt vmcnt(18)
	v_mov_b32_e32 v47, v222
	s_and_b64 vcc, exec, s[40:41]
	s_mov_b64 s[26:27], -1
	s_waitcnt vmcnt(1)
	v_lshlrev_b32_e32 v32, 16, v32
	s_waitcnt vmcnt(0)
	v_lshlrev_b32_e32 v48, 16, v47
	s_cbranch_vccnz .LBB0_618
	v_cvt_f32_u32_e32 v46, v46
	v_sub_f32_e32 v50, v32, v48
	s_mov_b64 s[26:27], 0
	v_mul_f32_e32 v46, 0x38000000, v46
	v_cos_f32_e32 v47, v46
	v_sin_f32_e64 v49, -v46
	v_mul_f32_e32 v46, v47, v50
	v_mul_f32_e32 v47, v50, v49

; __device__ __forceinline__ float bf2f(bf16_t b) { return __uint_as_float(((unsigned)b) << 16); }
; __device__ __forceinline__ float2 twid(float turns) { return make_float2(__builtin_amdgcn_cosf(turns), -__builtin_amdgcn_sinf(turns)); }
;   __device__ __forceinline__ float2 operator()(int i) const { const float2 wv = unpk2(Wd[i]); return half ? cmul(wv, twid((float)(i & (L - 1)) * invTurn)) : wv; }
;   __device__ __forceinline__ float2 operator()(int i) const {
;     const int ch = i >> lshift, t = i & (L - 1);
;     const float f = bf2f(hf[ch * chstride + t]), bw = bf2f(hb[ch * chstride + (t > 0 ? L - t : 0)]);
;     const float bwm = t > 0 ? bw : 0.f;
;     if (half == 0) return make_float2(f + bwm, 0.f);
;     const float2 tw = twid((float)t * invTurn); const float d = f - bwm; return make_float2(d * tw.x, d * tw.y);
;   }
.LBB0_620:
	v_or_b32_e32 v48, 0x1c00, v64
	v_sub_u32_e32 v49, 0x4000, v48
	v_lshlrev_b32_e32 v32, 1, v48
	v_lshlrev_b32_e32 v49, 1, v49
	s_waitcnt vmcnt(17)
	v_mov_b32_e32 v32, v223
	s_nop 0
	s_waitcnt vmcnt(16)
	v_mov_b32_e32 v49, v224
	s_and_b64 vcc, exec, s[40:41]
	s_mov_b64 s[26:27], -1
	s_waitcnt vmcnt(1)
	v_lshlrev_b32_e32 v32, 16, v32
	s_waitcnt vmcnt(0)
	v_lshlrev_b32_e32 v50, 16, v49
	s_cbranch_vccnz .LBB0_622
	v_cvt_f32_u32_e32 v48, v48
	v_sub_f32_e32 v52, v32, v50
	s_mov_b64 s[26:27], 0
	v_mul_f32_e32 v48, 0x38000000, v48
	v_cos_f32_e32 v49, v48
	v_sin_f32_e64 v51, -v48
	v_mul_f32_e32 v48, v49, v52
	v_mul_f32_e32 v49, v52, v51

; __device__ __forceinline__ float bf2f(bf16_t b) { return __uint_as_float(((unsigned)b) << 16); }
; __device__ __forceinline__ float2 twid(float turns) { return make_float2(__builtin_amdgcn_cosf(turns), -__builtin_amdgcn_sinf(turns)); }
;   __device__ __forceinline__ float2 operator()(int i) const { const float2 wv = unpk2(Wd[i]); return half ? cmul(wv, twid((float)(i & (L - 1)) * invTurn)) : wv; }
;   __device__ __forceinline__ float2 operator()(int i) const {
;     const int ch = i >> lshift, t = i & (L - 1);
;     const float f = bf2f(hf[ch * chstride + t]), bw = bf2f(hb[ch * chstride + (t > 0 ? L - t : 0)]);
;     const float bwm = t > 0 ? bw : 0.f;
;     if (half == 0) return make_float2(f + bwm, 0.f);
;     const float2 tw = twid((float)t * invTurn); const float d = f - bwm; return make_float2(d * tw.x, d * tw.y);
;   }
.LBB0_624:
	v_or_b32_e32 v50, 0x2000, v64
	v_sub_u32_e32 v51, 0x4000, v50
	v_lshlrev_b32_e32 v32, 1, v50
	v_lshlrev_b32_e32 v51, 1, v51
	s_waitcnt vmcnt(15)
	v_mov_b32_e32 v32, v225
	s_nop 0
	s_waitcnt vmcnt(14)
	v_mov_b32_e32 v51, v226
	s_and_b64 vcc, exec, s[40:41]
	s_mov_b64 s[26:27], -1
	s_waitcnt vmcnt(1)
	v_lshlrev_b32_e32 v32, 16, v32
	s_waitcnt vmcnt(0)
	v_lshlrev_b32_e32 v52, 16, v51
	s_cbranch_vccnz .LBB0_626
	v_cvt_f32_u32_e32 v50, v50
	v_sub_f32_e32 v54, v32, v52
	s_mov_b64 s[26:27], 0
	v_mul_f32_e32 v50, 0x38000000, v50
	v_cos_f32_e32 v51, v50
	v_sin_f32_e64 v53, -v50
	v_mul_f32_e32 v50, v51, v54
	v_mul_f32_e32 v51, v54, v53

; __device__ __forceinline__ float bf2f(bf16_t b) { return __uint_as_float(((unsigned)b) << 16); }
; __device__ __forceinline__ float2 twid(float turns) { return make_float2(__builtin_amdgcn_cosf(turns), -__builtin_amdgcn_sinf(turns)); }
;   __device__ __forceinline__ float2 operator()(int i) const { const float2 wv = unpk2(Wd[i]); return half ? cmul(wv, twid((float)(i & (L - 1)) * invTurn)) : wv; }
;   __device__ __forceinline__ float2 operator()(int i) const {
;     const int ch = i >> lshift, t = i & (L - 1);
;     const float f = bf2f(hf[ch * chstride + t]), bw = bf2f(hb[ch * chstride + (t > 0 ? L - t : 0)]);
;     const float bwm = t > 0 ? bw : 0.f;
;     if (half == 0) return make_float2(f + bwm, 0.f);
;     const float2 tw = twid((float)t * invTurn); const float d = f - bwm; return make_float2(d * tw.x, d * tw.y);
;   }
.LBB0_628:
	v_or_b32_e32 v52, 0x2400, v64
	v_sub_u32_e32 v53, 0x4000, v52
	v_lshlrev_b32_e32 v32, 1, v52
	v_lshlrev_b32_e32 v53, 1, v53
	s_waitcnt vmcnt(13)
	v_mov_b32_e32 v32, v227
	s_nop 0
	s_waitcnt vmcnt(12)
	v_mov_b32_e32 v53, v228
	s_and_b64 vcc, exec, s[40:41]
	s_mov_b64 s[26:27], -1
	s_waitcnt vmcnt(1)
	v_lshlrev_b32_e32 v32, 16, v32
	s_waitcnt vmcnt(0)
	v_lshlrev_b32_e32 v54, 16, v53
	s_cbranch_vccnz .LBB0_630
	v_cvt_f32_u32_e32 v52, v52
	v_sub_f32_e32 v56, v32, v54
	s_mov_b64 s[26:27], 0
	v_mul_f32_e32 v52, 0x38000000, v52
	v_cos_f32_e32 v53, v52
	v_sin_f32_e64 v55, -v52
	v_mul_f32_e32 v52, v53, v56
	v_mul_f32_e32 v53, v56, v55

; __device__ __forceinline__ float bf2f(bf16_t b) { return __uint_as_float(((unsigned)b) << 16); }
; __device__ __forceinline__ float2 twid(float turns) { return make_float2(__builtin_amdgcn_cosf(turns), -__builtin_amdgcn_sinf(turns)); }
;   __device__ __forceinline__ float2 operator()(int i) const { const float2 wv = unpk2(Wd[i]); return half ? cmul(wv, twid((float)(i & (L - 1)) * invTurn)) : wv; }
;   __device__ __forceinline__ float2 operator()(int i) const {
;     const int ch = i >> lshift, t = i & (L - 1);
;     const float f = bf2f(hf[ch * chstride + t]), bw = bf2f(hb[ch * chstride + (t > 0 ? L - t : 0)]);
;     const float bwm = t > 0 ? bw : 0.f;
;     if (half == 0) return make_float2(f + bwm, 0.f);
;     const float2 tw = twid((float)t * invTurn); const float d = f - bwm; return make_float2(d * tw.x, d * tw.y);
;   }
.LBB0_632:
	v_or_b32_e32 v54, 0x2800, v64
	v_sub_u32_e32 v55, 0x4000, v54
	v_lshlrev_b32_e32 v32, 1, v54
	v_lshlrev_b32_e32 v55, 1, v55
	s_waitcnt vmcnt(11)
	v_mov_b32_e32 v32, v229
	s_nop 0
	s_waitcnt vmcnt(10)
	v_mov_b32_e32 v55, v230
	s_and_b64 vcc, exec, s[40:41]
	s_mov_b64 s[26:27], -1
	s_waitcnt vmcnt(1)
	v_lshlrev_b32_e32 v32, 16, v32
	s_waitcnt vmcnt(0)
	v_lshlrev_b32_e32 v56, 16, v55
	s_cbranch_vccnz .LBB0_634
	v_cvt_f32_u32_e32 v54, v54
	v_sub_f32_e32 v58, v32, v56
	s_mov_b64 s[26:27], 0
	v_mul_f32_e32 v54, 0x38000000, v54
	v_cos_f32_e32 v55, v54
	v_sin_f32_e64 v57, -v54
	v_mul_f32_e32 v54, v55, v58
	v_mul_f32_e32 v55, v58, v57

; __device__ __forceinline__ float bf2f(bf16_t b) { return __uint_as_float(((unsigned)b) << 16); }
; __device__ __forceinline__ float2 twid(float turns) { return make_float2(__builtin_amdgcn_cosf(turns), -__builtin_amdgcn_sinf(turns)); }
;   __device__ __forceinline__ float2 operator()(int i) const { const float2 wv = unpk2(Wd[i]); return half ? cmul(wv, twid((float)(i & (L - 1)) * invTurn)) : wv; }
;   __device__ __forceinline__ float2 operator()(int i) const {
;     const int ch = i >> lshift, t = i & (L - 1);
;     const float f = bf2f(hf[ch * chstride + t]), bw = bf2f(hb[ch * chstride + (t > 0 ? L - t : 0)]);
;     const float bwm = t > 0 ? bw : 0.f;
;     if (half == 0) return make_float2(f + bwm, 0.f);
;     const float2 tw = twid((float)t * invTurn); const float d = f - bwm; return make_float2(d * tw.x, d * tw.y);
;   }
.LBB0_636:
	v_or_b32_e32 v56, 0x2c00, v64
	v_sub_u32_e32 v57, 0x4000, v56
	v_lshlrev_b32_e32 v32, 1, v56
	v_lshlrev_b32_e32 v57, 1, v57
	s_waitcnt vmcnt(9)
	v_mov_b32_e32 v32, v231
	s_nop 0
	s_waitcnt vmcnt(8)
	v_mov_b32_e32 v57, v232
	s_and_b64 vcc, exec, s[40:41]
	s_mov_b64 s[26:27], -1
	s_waitcnt vmcnt(1)
	v_lshlrev_b32_e32 v32, 16, v32
	s_waitcnt vmcnt(0)
	v_lshlrev_b32_e32 v58, 16, v57
	s_cbranch_vccnz .LBB0_638
	v_cvt_f32_u32_e32 v56, v56
	v_sub_f32_e32 v60, v32, v58
	s_mov_b64 s[26:27], 0
	v_mul_f32_e32 v56, 0x38000000, v56
	v_cos_f32_e32 v57, v56
	v_sin_f32_e64 v59, -v56
	v_mul_f32_e32 v56, v57, v60
	v_mul_f32_e32 v57, v60, v59

; __device__ __forceinline__ float bf2f(bf16_t b) { return __uint_as_float(((unsigned)b) << 16); }
; __device__ __forceinline__ float2 twid(float turns) { return make_float2(__builtin_amdgcn_cosf(turns), -__builtin_amdgcn_sinf(turns)); }
;   __device__ __forceinline__ float2 operator()(int i) const { const float2 wv = unpk2(Wd[i]); return half ? cmul(wv, twid((float)(i & (L - 1)) * invTurn)) : wv; }
;   __device__ __forceinline__ float2 operator()(int i) const {
;     const int ch = i >> lshift, t = i & (L - 1);
;     const float f = bf2f(hf[ch * chstride + t]), bw = bf2f(hb[ch * chstride + (t > 0 ? L - t : 0)]);
;     const float bwm = t > 0 ? bw : 0.f;
;     if (half == 0) return make_float2(f + bwm, 0.f);
;     const float2 tw = twid((float)t * invTurn); const float d = f - bwm; return make_float2(d * tw.x, d * tw.y);
;   }
.LBB0_640:
	v_or_b32_e32 v58, 0x3000, v64
	v_sub_u32_e32 v59, 0x4000, v58
	v_lshlrev_b32_e32 v32, 1, v58
	v_lshlrev_b32_e32 v59, 1, v59
	s_waitcnt vmcnt(7)
	v_mov_b32_e32 v32, v233
	s_nop 0
	s_waitcnt vmcnt(6)
	v_mov_b32_e32 v59, v234
	s_and_b64 vcc, exec, s[40:41]
	s_mov_b64 s[26:27], -1
	s_waitcnt vmcnt(1)
	v_lshlrev_b32_e32 v32, 16, v32
	s_waitcnt vmcnt(0)
	v_lshlrev_b32_e32 v60, 16, v59
	s_cbranch_vccnz .LBB0_642
	v_cvt_f32_u32_e32 v58, v58
	v_sub_f32_e32 v62, v32, v60
	s_mov_b64 s[26:27], 0
	v_mul_f32_e32 v58, 0x38000000, v58
	v_cos_f32_e32 v59, v58
	v_sin_f32_e64 v61, -v58
	v_mul_f32_e32 v58, v59, v62
	v_mul_f32_e32 v59, v62, v61

; __device__ __forceinline__ float bf2f(bf16_t b) { return __uint_as_float(((unsigned)b) << 16); }
; __device__ __forceinline__ float2 twid(float turns) { return make_float2(__builtin_amdgcn_cosf(turns), -__builtin_amdgcn_sinf(turns)); }
;   __device__ __forceinline__ float2 operator()(int i) const { const float2 wv = unpk2(Wd[i]); return half ? cmul(wv, twid((float)(i & (L - 1)) * invTurn)) : wv; }
;   __device__ __forceinline__ float2 operator()(int i) const {
;     const int ch = i >> lshift, t = i & (L - 1);
;     const float f = bf2f(hf[ch * chstride + t]), bw = bf2f(hb[ch * chstride + (t > 0 ? L - t : 0)]);
;     const float bwm = t > 0 ? bw : 0.f;
;     if (half == 0) return make_float2(f + bwm, 0.f);
;     const float2 tw = twid((float)t * invTurn); const float d = f - bwm; return make_float2(d * tw.x, d * tw.y);
;   }
.LBB0_644:
	v_or_b32_e32 v60, 0x3400, v64
	v_sub_u32_e32 v61, 0x4000, v60
	v_lshlrev_b32_e32 v32, 1, v60
	v_lshlrev_b32_e32 v61, 1, v61
	s_waitcnt vmcnt(5)
	v_mov_b32_e32 v32, v235
	s_nop 0
	s_waitcnt vmcnt(4)
	v_mov_b32_e32 v61, v236
	s_and_b64 vcc, exec, s[40:41]
	s_mov_b64 s[26:27], -1
	s_waitcnt vmcnt(1)
	v_lshlrev_b32_e32 v32, 16, v32
	s_waitcnt vmcnt(0)
	v_lshlrev_b32_e32 v62, 16, v61
	s_cbranch_vccnz .LBB0_646
	v_cvt_f32_u32_e32 v60, v60
	v_sub_f32_e32 v65, v32, v62
	s_mov_b64 s[26:27], 0
	v_mul_f32_e32 v60, 0x38000000, v60
	v_cos_f32_e32 v61, v60
	v_sin_f32_e64 v63, -v60
	v_mul_f32_e32 v60, v61, v65
	v_mul_f32_e32 v61, v65, v63

; __device__ __forceinline__ float bf2f(bf16_t b) { return __uint_as_float(((unsigned)b) << 16); }
; __device__ __forceinline__ float2 twid(float turns) { return make_float2(__builtin_amdgcn_cosf(turns), -__builtin_amdgcn_sinf(turns)); }
;   __device__ __forceinline__ float2 operator()(int i) const { const float2 wv = unpk2(Wd[i]); return half ? cmul(wv, twid((float)(i & (L - 1)) * invTurn)) : wv; }
;   __device__ __forceinline__ float2 operator()(int i) const {
;     const int ch = i >> lshift, t = i & (L - 1);
;     const float f = bf2f(hf[ch * chstride + t]), bw = bf2f(hb[ch * chstride + (t > 0 ? L - t : 0)]);
;     const float bwm = t > 0 ? bw : 0.f;
;     if (half == 0) return make_float2(f + bwm, 0.f);
;     const float2 tw = twid((float)t * invTurn); const float d = f - bwm; return make_float2(d * tw.x, d * tw.y);
;   }
.LBB0_648:
	v_or_b32_e32 v62, 0x3800, v64
	v_sub_u32_e32 v63, 0x4000, v62
	v_lshlrev_b32_e32 v32, 1, v62
	v_lshlrev_b32_e32 v63, 1, v63
	s_waitcnt vmcnt(3)
	v_mov_b32_e32 v32, v237
	s_nop 0
	s_waitcnt vmcnt(2)
	v_mov_b32_e32 v63, v238
	s_and_b64 vcc, exec, s[40:41]
	s_mov_b64 s[26:27], -1
	s_waitcnt vmcnt(1)
	v_lshlrev_b32_e32 v32, 16, v32
	s_waitcnt vmcnt(0)
	v_lshlrev_b32_e32 v65, 16, v63
	s_cbranch_vccnz .LBB0_650
	v_cvt_f32_u32_e32 v62, v62
	v_sub_f32_e32 v70, v32, v65
	s_mov_b64 s[26:27], 0
	v_mul_f32_e32 v62, 0x38000000, v62
	v_cos_f32_e32 v63, v62
	v_sin_f32_e64 v69, -v62
	v_mul_f32_e32 v62, v63, v70
	v_mul_f32_e32 v63, v70, v69

; __device__ __forceinline__ float bf2f(bf16_t b) { return __uint_as_float(((unsigned)b) << 16); }
; __device__ __forceinline__ float2 twid(float turns) { return make_float2(__builtin_amdgcn_cosf(turns), -__builtin_amdgcn_sinf(turns)); }
;   __device__ __forceinline__ float2 operator()(int i) const { const float2 wv = unpk2(Wd[i]); return half ? cmul(wv, twid((float)(i & (L - 1)) * invTurn)) : wv; }
;   __device__ __forceinline__ float2 operator()(int i) const {
;     const int ch = i >> lshift, t = i & (L - 1);
;     const float f = bf2f(hf[ch * chstride + t]), bw = bf2f(hb[ch * chstride + (t > 0 ? L - t : 0)]);
;     const float bwm = t > 0 ? bw : 0.f;
;     if (half == 0) return make_float2(f + bwm, 0.f);
;     const float2 tw = twid((float)t * invTurn); const float d = f - bwm; return make_float2(d * tw.x, d * tw.y);
;   }
.LBB0_652:
	v_or_b32_e32 v64, 0x3c00, v64
	v_sub_u32_e32 v65, 0x4000, v64
	v_lshlrev_b32_e32 v32, 1, v64
	v_lshlrev_b32_e32 v65, 1, v65
	s_waitcnt vmcnt(1)
	v_mov_b32_e32 v32, v239
	s_nop 0
	s_waitcnt vmcnt(0)
	v_mov_b32_e32 v65, v240
	s_and_b64 vcc, exec, s[40:41]
	s_mov_b64 s[26:27], -1
	s_waitcnt vmcnt(1)
	v_lshlrev_b32_e32 v32, 16, v32
	s_waitcnt vmcnt(0)
	v_lshlrev_b32_e32 v69, 16, v65
	s_cbranch_vccnz .LBB0_654
	v_cvt_f32_u32_e32 v64, v64
	v_sub_f32_e32 v71, v32, v69
	s_mov_b64 s[26:27], 0
	v_mul_f32_e32 v64, 0x38000000, v64
	v_cos_f32_e32 v65, v64
	v_sin_f32_e64 v70, -v64
	v_mul_f32_e32 v64, v65, v71
	v_mul_f32_e32 v65, v71, v70

; __device__ __forceinline__ float2 cmul(float2 a, float2 b) { return make_float2(a.x * b.x - a.y * b.y, a.x * b.y + a.y * b.x); }
; __device__ __forceinline__ float2 twid(float turns) { return make_float2(__builtin_amdgcn_cosf(turns), -__builtin_amdgcn_sinf(turns)); }
; template <int R, bool INV>
; __device__ __forceinline__ void butterflies(c32 (&v)[1 << R], float turns0) {
;   constexpr int RAD = 1 << R;
;   constexpr float TC[16] = {1.0f, 0.98078528040f, 0.92387953251f, 0.83146961230f, 0.70710678119f, 0.55557023302f, 0.38268343237f, 0.19509032202f,
;                             0.0f, -0.19509032202f, -0.38268343237f, -0.55557023302f, -0.70710678119f, -0.83146961230f, -0.92387953251f, -0.98078528040f};
;   constexpr float TS[16] = {0.0f, 0.19509032202f, 0.38268343237f, 0.55557023302f, 0.70710678119f, 0.83146961230f, 0.92387953251f, 0.98078528040f,
;                             1.0f, 0.98078528040f, 0.92387953251f, 0.83146961230f, 0.70710678119f, 0.55557023302f, 0.38268343237f, 0.19509032202f};
;   float2 tbs[R];
;   tbs[0] = twid(turns0);
;   if (INV) tbs[0].y = -tbs[0].y;
; #pragma unroll
;   for (int k = 1; k < R; ++k) tbs[k] = cmul(tbs[k - 1], tbs[k - 1]);
; #pragma unroll
;   for (int kk = 0; kk < R; ++kk) {
;     const int k = INV ? (R - 1 - kk) : kk;
;     const int hd = RAD >> (k + 1);
; #pragma unroll
;     for (int j = 0; j < RAD; ++j) {
;       if ((j & hd) == 0) {
;         const int m = (j & (hd - 1)) * (16 / hd);
;         const float2 c = make_float2(TC[m], INV ? TS[m] : -TS[m]);
;         const float2 twf = cmul(tbs[k], c);
;         const c32 tw = {twf.x, twf.y};
;         const c32 a = v[j], b = v[j + hd];
;         if (!INV) { v[j] = a + b; v[j + hd] = cmul_pk(a - b, tw); }
;         else { const c32 bt = cmul_pk(b, tw); v[j] = a + bt; v[j + hd] = a - bt; }
;       }
;     }
;   }
; }
; template <int LOGN>
; __device__ __forceinline__ void fft_last_to_regs(const float2* X, c32 (&kf)[32]) {
;   static_assert(LOGN == 14, "one radix-32 group per thread");
;   const c32* Xc = (const c32*)X;
;   int tid0 = threadIdx.x; asm volatile("" : "+v"(tid0));
;   const int pb = tid0 * 33;
;   c32 v[32];
; #pragma unroll
;   for (int j = 0; j < 32; ++j) v[j] = Xc[pb + j];
;   butterflies<5, false>(v, 0.f);
; #pragma unroll
;   for (int j = 0; j < 32; ++j) kf[j] = v[j];
;   __syncthreads();
; }
.LBB0_659:
	s_or_b64 exec, exec, s[0:1]
	v_mov_b32_e32 v0, v196
	s_waitcnt lgkmcnt(0)
	s_barrier
	s_mov_b32 s7, s95
	v_mul_lo_u32 v0, v0, s56
	v_add_u32_e32 v32, 0, v0
	ds_read2_b64 v[0:3], v32 offset1:1
	ds_read2_b64 v[4:7], v32 offset0:2 offset1:3
	ds_read2_b64 v[8:11], v32 offset0:4 offset1:5
	ds_read2_b64 v[12:15], v32 offset0:6 offset1:7
	ds_read2_b64 v[16:19], v32 offset0:8 offset1:9
	ds_read2_b64 v[20:23], v32 offset0:10 offset1:11
	ds_read2_b64 v[24:27], v32 offset0:12 offset1:13
	ds_read2_b64 v[28:31], v32 offset0:14 offset1:15
	ds_read2_b64 v[34:37], v32 offset0:16 offset1:17
	ds_read2_b64 v[38:41], v32 offset0:18 offset1:19
	ds_read2_b64 v[42:45], v32 offset0:20 offset1:21
	ds_read2_b64 v[46:49], v32 offset0:22 offset1:23
	ds_read2_b64 v[50:53], v32 offset0:24 offset1:25
	ds_read2_b64 v[54:57], v32 offset0:26 offset1:27
	ds_read2_b64 v[58:61], v32 offset0:28 offset1:29
	ds_read2_b64 v[62:65], v32 offset0:30 offset1:31
	s_waitcnt lgkmcnt(7)
	v_pk_add_f32 v[66:67], v[0:1], v[34:35]
	v_pk_add_f32 v[34:35], v[0:1], v[34:35] neg_lo:[0,1] neg_hi:[0,1]
	v_mov_b64_e32 v[0:1], s[6:7]
	v_pk_mul_f32 v[68:69], v[34:35], v[0:1] op_sel:[0,0] op_sel_hi:[0,1]
	s_mov_b32 s0, s19
	s_mov_b32 s1, s30
	v_pk_fma_f32 v[34:35], v[34:35], v[0:1], v[68:69] op_sel:[1,1,0] op_sel_hi:[1,0,1] neg_lo:[0,1,0]
	v_pk_add_f32 v[68:69], v[2:3], v[36:37]
	v_pk_add_f32 v[2:3], v[2:3], v[36:37] neg_lo:[0,1] neg_hi:[0,1]
	v_mov_b64_e32 v[36:37], s[0:1]
	v_pk_mul_f32 v[70:71], v[2:3], v[36:37] op_sel:[0,0] op_sel_hi:[0,1]
	s_mov_b32 s0, s9
	s_mov_b32 s1, s76
	v_pk_fma_f32 v[36:37], v[2:3], v[36:37], v[70:71] op_sel:[1,1,0] op_sel_hi:[1,0,1] neg_lo:[0,1,0]
	s_waitcnt lgkmcnt(6)
	v_pk_add_f32 v[70:71], v[4:5], v[38:39]
	v_pk_add_f32 v[2:3], v[4:5], v[38:39] neg_lo:[0,1] neg_hi:[0,1]
	v_mov_b64_e32 v[4:5], s[0:1]
	v_pk_mul_f32 v[38:39], v[2:3], v[4:5] op_sel:[0,0] op_sel_hi:[0,1]
	s_mov_b32 s0, s55
	s_mov_b32 s1, s68
	v_pk_fma_f32 v[38:39], v[2:3], v[4:5], v[38:39] op_sel:[1,1,0] op_sel_hi:[1,0,1] neg_lo:[0,1,0]
	v_pk_add_f32 v[72:73], v[6:7], v[40:41]
	v_pk_add_f32 v[2:3], v[6:7], v[40:41] neg_lo:[0,1] neg_hi:[0,1]
	v_mov_b64_e32 v[6:7], s[0:1]
	v_pk_mul_f32 v[40:41], v[2:3], v[6:7] op_sel:[0,0] op_sel_hi:[0,1]
	s_mov_b32 s0, s73
	s_mov_b32 s1, s72
	v_pk_fma_f32 v[6:7], v[2:3], v[6:7], v[40:41] op_sel:[1,1,0] op_sel_hi:[1,0,1] neg_lo:[0,1,0]
	s_waitcnt lgkmcnt(5)
	v_pk_add_f32 v[40:41], v[8:9], v[42:43]
	v_pk_add_f32 v[2:3], v[8:9], v[42:43] neg_lo:[0,1] neg_hi:[0,1]
	v_mov_b64_e32 v[8:9], s[0:1]
	v_pk_mul_f32 v[42:43], v[2:3], v[8:9] op_sel:[0,0] op_sel_hi:[0,1]
	s_mov_b32 s0, s54
	s_mov_b32 s1, s16
	v_pk_fma_f32 v[42:43], v[2:3], v[8:9], v[42:43] op_sel:[1,1,0] op_sel_hi:[1,0,1] neg_lo:[0,1,0]
	v_pk_add_f32 v[74:75], v[10:11], v[44:45]
	v_pk_add_f32 v[2:3], v[10:11], v[44:45] neg_lo:[0,1] neg_hi:[0,1]
	v_mov_b64_e32 v[10:11], s[0:1]
	v_pk_mul_f32 v[44:45], v[2:3], v[10:11] op_sel:[0,0] op_sel_hi:[0,1]
	s_mov_b32 s0, s8
	s_mov_b32 s1, s10
	v_pk_fma_f32 v[10:11], v[2:3], v[10:11], v[44:45] op_sel:[1,1,0] op_sel_hi:[1,0,1] neg_lo:[0,1,0]
	s_waitcnt lgkmcnt(4)
	v_pk_add_f32 v[44:45], v[12:13], v[46:47]
	v_pk_add_f32 v[2:3], v[12:13], v[46:47] neg_lo:[0,1] neg_hi:[0,1]
	v_mov_b64_e32 v[12:13], s[0:1]
	v_pk_mul_f32 v[46:47], v[2:3], v[12:13] op_sel:[0,0] op_sel_hi:[0,1]
	s_mov_b32 s0, s18
	s_mov_b32 s1, s4
	v_pk_fma_f32 v[46:47], v[2:3], v[12:13], v[46:47] op_sel:[1,1,0] op_sel_hi:[1,0,1] neg_lo:[0,1,0]
	v_pk_add_f32 v[76:77], v[14:15], v[48:49]
	v_pk_add_f32 v[2:3], v[14:15], v[48:49] neg_lo:[0,1] neg_hi:[0,1]
	v_mov_b64_e32 v[14:15], s[0:1]
	v_pk_mul_f32 v[48:49], v[2:3], v[14:15] op_sel:[0,0] op_sel_hi:[0,1]
	s_mov_b32 s88, s94
	v_pk_fma_f32 v[14:15], v[2:3], v[14:15], v[48:49] op_sel:[1,1,0] op_sel_hi:[1,0,1] neg_lo:[0,1,0]
	s_waitcnt lgkmcnt(3)
	v_pk_add_f32 v[48:49], v[16:17], v[50:51]
	v_pk_add_f32 v[16:17], v[16:17], v[50:51] neg_lo:[0,1] neg_hi:[0,1]
	v_mov_b64_e32 v[2:3], s[88:89]
	v_pk_mul_f32 v[50:51], v[16:17], v[2:3] op_sel:[0,0] op_sel_hi:[0,1]
	s_mov_b32 s31, s4
	v_pk_fma_f32 v[16:17], v[16:17], v[2:3], v[50:51] op_sel:[1,1,0] op_sel_hi:[1,0,1] neg_lo:[0,1,0]
	v_pk_add_f32 v[50:51], v[18:19], v[52:53]
	v_pk_add_f32 v[18:19], v[18:19], v[52:53] neg_lo:[0,1] neg_hi:[0,1]
	v_mov_b64_e32 v[52:53], s[30:31]
	v_pk_mul_f32 v[78:79], v[18:19], v[52:53] op_sel:[0,0] op_sel_hi:[0,1]
	s_mov_b32 s77, s10
	v_pk_fma_f32 v[18:19], v[18:19], v[52:53], v[78:79] op_sel:[1,1,0] op_sel_hi:[1,0,1] neg_lo:[0,1,0]
	s_waitcnt lgkmcnt(2)
	v_pk_add_f32 v[52:53], v[20:21], v[54:55]
	v_pk_add_f32 v[20:21], v[20:21], v[54:55] neg_lo:[0,1] neg_hi:[0,1]
	v_mov_b64_e32 v[54:55], s[76:77]
	v_pk_mul_f32 v[78:79], v[20:21], v[54:55] op_sel:[0,0] op_sel_hi:[0,1]
	s_mov_b32 s69, s16
	v_pk_fma_f32 v[20:21], v[20:21], v[54:55], v[78:79] op_sel:[1,1,0] op_sel_hi:[1,0,1] neg_lo:[0,1,0]
	v_pk_add_f32 v[78:79], v[22:23], v[56:57]
	v_pk_add_f32 v[22:23], v[22:23], v[56:57] neg_lo:[0,1] neg_hi:[0,1]
	v_mov_b64_e32 v[56:57], s[68:69]
	v_pk_mul_f32 v[80:81], v[22:23], v[56:57] op_sel:[0,0] op_sel_hi:[0,1]
	s_mov_b32 s0, s72
	s_mov_b32 s1, s72
	v_pk_fma_f32 v[22:23], v[22:23], v[56:57], v[80:81] op_sel:[1,1,0] op_sel_hi:[1,0,1] neg_lo:[0,1,0]
	s_waitcnt lgkmcnt(1)
	v_pk_add_f32 v[56:57], v[24:25], v[58:59]
	v_pk_add_f32 v[24:25], v[24:25], v[58:59] neg_lo:[0,1] neg_hi:[0,1]
	v_mov_b64_e32 v[58:59], s[0:1]
	v_pk_mul_f32 v[80:81], v[24:25], v[58:59] op_sel:[0,0] op_sel_hi:[0,1]
	s_mov_b32 s17, s68
	v_pk_fma_f32 v[24:25], v[24:25], v[58:59], v[80:81] op_sel:[1,1,0] op_sel_hi:[1,0,1] neg_lo:[0,1,0]
	v_pk_add_f32 v[80:81], v[26:27], v[60:61]
	v_pk_add_f32 v[26:27], v[26:27], v[60:61] neg_lo:[0,1] neg_hi:[0,1]
	v_mov_b64_e32 v[60:61], s[16:17]
	v_pk_mul_f32 v[82:83], v[26:27], v[60:61] op_sel:[0,0] op_sel_hi:[0,1]
	s_mov_b32 s11, s76
	v_pk_fma_f32 v[26:27], v[26:27], v[60:61], v[82:83] op_sel:[1,1,0] op_sel_hi:[1,0,1] neg_lo:[0,1,0]
	s_waitcnt lgkmcnt(0)
	v_pk_add_f32 v[60:61], v[28:29], v[62:63]
	v_pk_add_f32 v[28:29], v[28:29], v[62:63] neg_lo:[0,1] neg_hi:[0,1]
	v_mov_b64_e32 v[62:63], s[10:11]
	v_pk_mul_f32 v[82:83], v[28:29], v[62:63] op_sel:[0,0] op_sel_hi:[0,1]
	s_mov_b32 s5, s30
	v_pk_fma_f32 v[28:29], v[28:29], v[62:63], v[82:83] op_sel:[1,1,0] op_sel_hi:[1,0,1] neg_lo:[0,1,0]
	v_pk_add_f32 v[82:83], v[30:31], v[64:65]
	v_pk_add_f32 v[30:31], v[30:31], v[64:65] neg_lo:[0,1] neg_hi:[0,1]
	v_mov_b64_e32 v[64:65], s[4:5]
	v_pk_mul_f32 v[84:85], v[30:31], v[64:65] op_sel:[0,0] op_sel_hi:[0,1]
	v_mov_b32_e32 v167, v196
	v_pk_fma_f32 v[30:31], v[30:31], v[64:65], v[84:85] op_sel:[1,1,0] op_sel_hi:[1,0,1] neg_lo:[0,1,0]
	v_pk_add_f32 v[64:65], v[66:67], v[48:49]
	v_pk_add_f32 v[48:49], v[66:67], v[48:49] neg_lo:[0,1] neg_hi:[0,1]
	s_nop 0
	v_pk_mul_f32 v[66:67], v[48:49], v[0:1] op_sel:[0,0] op_sel_hi:[0,1]
	s_barrier
; __device__ __forceinline__ float2 cmul(float2 a, float2 b) { return make_float2(a.x * b.x - a.y * b.y, a.x * b.y + a.y * b.x); }
; template <int R, bool INV>
; __device__ __forceinline__ void butterflies(c32 (&v)[1 << R], float turns0) {
;     ...
; #pragma unroll
;   for (int k = 1; k < R; ++k) tbs[k] = cmul(tbs[k - 1], tbs[k - 1]);
; #pragma unroll
;   for (int kk = 0; kk < R; ++kk) {
;     const int k = INV ? (R - 1 - kk) : kk;
;     const int hd = RAD >> (k + 1);
; #pragma unroll
;     for (int j = 0; j < RAD; ++j) {
;       if ((j & hd) == 0) {
;         const int m = (j & (hd - 1)) * (16 / hd);
;         const float2 c = make_float2(TC[m], INV ? TS[m] : -TS[m]);
;         const float2 twf = cmul(tbs[k], c);
;         const c32 tw = {twf.x, twf.y};
;         const c32 a = v[j], b = v[j + hd];
;         if (!INV) { v[j] = a + b; v[j + hd] = cmul_pk(a - b, tw); }
;         else { const c32 bt = cmul_pk(b, tw); v[j] = a + bt; v[j + hd] = a - bt; }
;       }
;     }
;   }
	v_pk_fma_f32 v[48:49], v[48:49], v[0:1], v[66:67] op_sel:[1,1,0] op_sel_hi:[1,0,1] neg_lo:[0,1,0]
	v_pk_add_f32 v[66:67], v[68:69], v[50:51]
	v_pk_add_f32 v[50:51], v[68:69], v[50:51] neg_lo:[0,1] neg_hi:[0,1]
	s_nop 0
	v_pk_mul_f32 v[68:69], v[50:51], v[4:5] op_sel:[0,0] op_sel_hi:[0,1]
	s_and_b64 vcc, exec, s[40:41]
	v_pk_fma_f32 v[50:51], v[50:51], v[4:5], v[68:69] op_sel:[1,1,0] op_sel_hi:[1,0,1] neg_lo:[0,1,0]
	v_pk_add_f32 v[68:69], v[70:71], v[52:53]
	v_pk_add_f32 v[52:53], v[70:71], v[52:53] neg_lo:[0,1] neg_hi:[0,1]
	v_and_b32_e32 v124, 0x3ff, v167
	v_pk_mul_f32 v[70:71], v[52:53], v[8:9] op_sel:[0,0] op_sel_hi:[0,1]
	v_lshlrev_b32_e32 v32, 4, v167
	v_pk_fma_f32 v[52:53], v[52:53], v[8:9], v[70:71] op_sel:[1,1,0] op_sel_hi:[1,0,1] neg_lo:[0,1,0]
	v_pk_add_f32 v[70:71], v[72:73], v[78:79]
	v_pk_add_f32 v[72:73], v[72:73], v[78:79] neg_lo:[0,1] neg_hi:[0,1]
	s_nop 0
	v_pk_mul_f32 v[78:79], v[72:73], v[12:13] op_sel:[0,0] op_sel_hi:[0,1]
	s_nop 0
	v_pk_fma_f32 v[72:73], v[72:73], v[12:13], v[78:79] op_sel:[1,1,0] op_sel_hi:[1,0,1] neg_lo:[0,1,0]
	v_pk_add_f32 v[78:79], v[40:41], v[56:57]
	v_pk_add_f32 v[40:41], v[40:41], v[56:57] neg_lo:[0,1] neg_hi:[0,1]
	s_nop 0
	v_pk_mul_f32 v[56:57], v[40:41], v[2:3] op_sel:[0,0] op_sel_hi:[0,1]
	s_nop 0
	v_pk_fma_f32 v[40:41], v[40:41], v[2:3], v[56:57] op_sel:[1,1,0] op_sel_hi:[1,0,1] neg_lo:[0,1,0]
	v_pk_add_f32 v[56:57], v[74:75], v[80:81]
	v_pk_add_f32 v[74:75], v[74:75], v[80:81] neg_lo:[0,1] neg_hi:[0,1]
	s_nop 0
	v_pk_mul_f32 v[80:81], v[74:75], v[54:55] op_sel:[0,0] op_sel_hi:[0,1]
	s_nop 0
	v_pk_fma_f32 v[74:75], v[74:75], v[54:55], v[80:81] op_sel:[1,1,0] op_sel_hi:[1,0,1] neg_lo:[0,1,0]
	v_pk_add_f32 v[80:81], v[44:45], v[60:61]
	v_pk_add_f32 v[44:45], v[44:45], v[60:61] neg_lo:[0,1] neg_hi:[0,1]
	s_nop 0
	v_pk_mul_f32 v[60:61], v[44:45], v[58:59] op_sel:[0,0] op_sel_hi:[0,1]
	s_nop 0
	v_pk_fma_f32 v[44:45], v[44:45], v[58:59], v[60:61] op_sel:[1,1,0] op_sel_hi:[1,0,1] neg_lo:[0,1,0]
	v_pk_add_f32 v[60:61], v[76:77], v[82:83]
	v_pk_add_f32 v[76:77], v[76:77], v[82:83] neg_lo:[0,1] neg_hi:[0,1]
	s_nop 0
	v_pk_mul_f32 v[82:83], v[76:77], v[62:63] op_sel:[0,0] op_sel_hi:[0,1]
	s_nop 0
	v_pk_fma_f32 v[76:77], v[76:77], v[62:63], v[82:83] op_sel:[1,1,0] op_sel_hi:[1,0,1] neg_lo:[0,1,0]
	v_pk_add_f32 v[82:83], v[34:35], v[16:17]
	v_pk_add_f32 v[16:17], v[34:35], v[16:17] neg_lo:[0,1] neg_hi:[0,1]
	v_pk_add_f32 v[84:85], v[72:73], v[76:77]
	v_pk_mul_f32 v[34:35], v[16:17], v[0:1] op_sel:[0,0] op_sel_hi:[0,1]
	s_nop 0
	v_pk_fma_f32 v[16:17], v[16:17], v[0:1], v[34:35] op_sel:[1,1,0] op_sel_hi:[1,0,1] neg_lo:[0,1,0]
	v_pk_add_f32 v[34:35], v[36:37], v[18:19]
	v_pk_add_f32 v[18:19], v[36:37], v[18:19] neg_lo:[0,1] neg_hi:[0,1]
	s_nop 0
	v_pk_mul_f32 v[36:37], v[18:19], v[4:5] op_sel:[0,0] op_sel_hi:[0,1]
	s_nop 0
	v_pk_fma_f32 v[4:5], v[18:19], v[4:5], v[36:37] op_sel:[1,1,0] op_sel_hi:[1,0,1] neg_lo:[0,1,0]
	v_pk_add_f32 v[18:19], v[38:39], v[20:21]
	v_pk_add_f32 v[20:21], v[38:39], v[20:21] neg_lo:[0,1] neg_hi:[0,1]
	s_nop 0
	v_pk_mul_f32 v[36:37], v[20:21], v[8:9] op_sel:[0,0] op_sel_hi:[0,1]
	s_nop 0
	v_pk_fma_f32 v[20:21], v[20:21], v[8:9], v[36:37] op_sel:[1,1,0] op_sel_hi:[1,0,1] neg_lo:[0,1,0]
	v_pk_add_f32 v[36:37], v[6:7], v[22:23]
	v_pk_add_f32 v[6:7], v[6:7], v[22:23] neg_lo:[0,1] neg_hi:[0,1]
	s_nop 0
	v_pk_mul_f32 v[22:23], v[6:7], v[12:13] op_sel:[0,0] op_sel_hi:[0,1]
	s_nop 0
	v_pk_fma_f32 v[6:7], v[6:7], v[12:13], v[22:23] op_sel:[1,1,0] op_sel_hi:[1,0,1] neg_lo:[0,1,0]
	v_pk_add_f32 v[12:13], v[42:43], v[24:25]
	v_pk_add_f32 v[22:23], v[42:43], v[24:25] neg_lo:[0,1] neg_hi:[0,1]
	v_pk_add_f32 v[42:43], v[64:65], v[78:79] neg_lo:[0,1] neg_hi:[0,1]
	v_pk_mul_f32 v[24:25], v[22:23], v[2:3] op_sel:[0,0] op_sel_hi:[0,1]
	s_nop 0
	v_pk_fma_f32 v[22:23], v[22:23], v[2:3], v[24:25] op_sel:[1,1,0] op_sel_hi:[1,0,1] neg_lo:[0,1,0]
	v_pk_add_f32 v[24:25], v[10:11], v[26:27]
	v_pk_add_f32 v[10:11], v[10:11], v[26:27] neg_lo:[0,1] neg_hi:[0,1]
	v_pk_add_f32 v[90:91], v[16:17], v[22:23]
	v_pk_mul_f32 v[26:27], v[10:11], v[54:55] op_sel:[0,0] op_sel_hi:[0,1]
	v_pk_add_f32 v[16:17], v[16:17], v[22:23] neg_lo:[0,1] neg_hi:[0,1]
	v_pk_fma_f32 v[10:11], v[10:11], v[54:55], v[26:27] op_sel:[1,1,0] op_sel_hi:[1,0,1] neg_lo:[0,1,0]
	v_pk_add_f32 v[26:27], v[46:47], v[28:29]
	v_pk_add_f32 v[28:29], v[46:47], v[28:29] neg_lo:[0,1] neg_hi:[0,1]
	v_pk_mul_f32 v[46:47], v[42:43], v[0:1] op_sel:[0,0] op_sel_hi:[0,1]
	v_pk_add_f32 v[54:55], v[66:67], v[56:57] neg_lo:[0,1] neg_hi:[0,1]
	v_pk_mul_f32 v[38:39], v[28:29], v[58:59] op_sel:[0,0] op_sel_hi:[0,1]
	v_pk_fma_f32 v[46:47], v[42:43], v[0:1], v[46:47] op_sel:[1,1,0] op_sel_hi:[1,0,1] neg_lo:[0,1,0]
	v_pk_add_f32 v[42:43], v[66:67], v[56:57]
	v_pk_fma_f32 v[28:29], v[28:29], v[58:59], v[38:39] op_sel:[1,1,0] op_sel_hi:[1,0,1] neg_lo:[0,1,0]
	v_pk_add_f32 v[38:39], v[14:15], v[30:31]
	v_pk_add_f32 v[14:15], v[14:15], v[30:31] neg_lo:[0,1] neg_hi:[0,1]
	v_pk_mul_f32 v[56:57], v[54:55], v[8:9] op_sel:[0,0] op_sel_hi:[0,1]
	v_pk_mul_f32 v[22:23], v[16:17], v[0:1] op_sel:[0,0] op_sel_hi:[0,1]
	v_pk_add_f32 v[86:87], v[18:19], v[26:27]
	v_pk_mul_f32 v[30:31], v[14:15], v[62:63] op_sel:[0,0] op_sel_hi:[0,1]
	v_pk_fma_f32 v[54:55], v[54:55], v[8:9], v[56:57] op_sel:[1,1,0] op_sel_hi:[1,0,1] neg_lo:[0,1,0]
	v_pk_add_f32 v[56:57], v[68:69], v[80:81]
	v_pk_fma_f32 v[14:15], v[14:15], v[62:63], v[30:31] op_sel:[1,1,0] op_sel_hi:[1,0,1] neg_lo:[0,1,0]
	v_pk_add_f32 v[30:31], v[64:65], v[78:79]
	v_pk_add_f32 v[62:63], v[68:69], v[80:81] neg_lo:[0,1] neg_hi:[0,1]
	v_pk_add_f32 v[78:79], v[52:53], v[44:45]
	v_pk_mul_f32 v[64:65], v[62:63], v[2:3] op_sel:[0,0] op_sel_hi:[0,1]
; __device__ __forceinline__ float2 cmul(float2 a, float2 b) { return make_float2(a.x * b.x - a.y * b.y, a.x * b.y + a.y * b.x); }
; template <int R, bool INV>
; __device__ __forceinline__ void butterflies(c32 (&v)[1 << R], float turns0) {
;     ...
; #pragma unroll
;   for (int k = 1; k < R; ++k) tbs[k] = cmul(tbs[k - 1], tbs[k - 1]);
; #pragma unroll
;   for (int kk = 0; kk < R; ++kk) {
;     const int k = INV ? (R - 1 - kk) : kk;
;     const int hd = RAD >> (k + 1);
; #pragma unroll
;     for (int j = 0; j < RAD; ++j) {
;       if ((j & hd) == 0) {
;         const int m = (j & (hd - 1)) * (16 / hd);
;         const float2 c = make_float2(TC[m], INV ? TS[m] : -TS[m]);
;         const float2 twf = cmul(tbs[k], c);
;         const c32 tw = {twf.x, twf.y};
;         const c32 a = v[j], b = v[j + hd];
;         if (!INV) { v[j] = a + b; v[j + hd] = cmul_pk(a - b, tw); }
;         else { const c32 bt = cmul_pk(b, tw); v[j] = a + bt; v[j + hd] = a - bt; }
;       }
;     }
;   }
	v_pk_fma_f32 v[16:17], v[16:17], v[0:1], v[22:23] op_sel:[1,1,0] op_sel_hi:[1,0,1] neg_lo:[0,1,0]
	v_pk_add_f32 v[22:23], v[4:5], v[10:11]
	v_pk_fma_f32 v[62:63], v[62:63], v[2:3], v[64:65] op_sel:[1,1,0] op_sel_hi:[1,0,1] neg_lo:[0,1,0]
	v_pk_add_f32 v[64:65], v[70:71], v[60:61]
	v_pk_add_f32 v[60:61], v[70:71], v[60:61] neg_lo:[0,1] neg_hi:[0,1]
	v_pk_add_f32 v[70:71], v[50:51], v[74:75]
	v_pk_mul_f32 v[66:67], v[60:61], v[58:59] op_sel:[0,0] op_sel_hi:[0,1]
	v_pk_add_f32 v[4:5], v[4:5], v[10:11] neg_lo:[0,1] neg_hi:[0,1]
	v_pk_fma_f32 v[60:61], v[60:61], v[58:59], v[66:67] op_sel:[1,1,0] op_sel_hi:[1,0,1] neg_lo:[0,1,0]
	v_pk_add_f32 v[66:67], v[48:49], v[40:41]
	v_pk_add_f32 v[40:41], v[48:49], v[40:41] neg_lo:[0,1] neg_hi:[0,1]
	v_pk_mul_f32 v[10:11], v[4:5], v[8:9] op_sel:[0,0] op_sel_hi:[0,1]
	v_pk_add_f32 v[18:19], v[18:19], v[26:27] neg_lo:[0,1] neg_hi:[0,1]
	v_pk_mul_f32 v[48:49], v[40:41], v[0:1] op_sel:[0,0] op_sel_hi:[0,1]
	v_pk_fma_f32 v[4:5], v[4:5], v[8:9], v[10:11] op_sel:[1,1,0] op_sel_hi:[1,0,1] neg_lo:[0,1,0]
	v_pk_add_f32 v[10:11], v[20:21], v[28:29] neg_lo:[0,1] neg_hi:[0,1]
	v_pk_fma_f32 v[68:69], v[40:41], v[0:1], v[48:49] op_sel:[1,1,0] op_sel_hi:[1,0,1] neg_lo:[0,1,0]
	v_pk_add_f32 v[40:41], v[50:51], v[74:75] neg_lo:[0,1] neg_hi:[0,1]
	v_pk_mul_f32 v[26:27], v[18:19], v[2:3] op_sel:[0,0] op_sel_hi:[0,1]
	s_nop 0
	v_pk_mul_f32 v[48:49], v[40:41], v[8:9] op_sel:[0,0] op_sel_hi:[0,1]
	v_pk_fma_f32 v[18:19], v[18:19], v[2:3], v[26:27] op_sel:[1,1,0] op_sel_hi:[1,0,1] neg_lo:[0,1,0]
	v_pk_add_f32 v[26:27], v[36:37], v[38:39]
	v_pk_fma_f32 v[74:75], v[40:41], v[8:9], v[48:49] op_sel:[1,1,0] op_sel_hi:[1,0,1] neg_lo:[0,1,0]
	v_pk_add_f32 v[40:41], v[52:53], v[44:45] neg_lo:[0,1] neg_hi:[0,1]
	v_pk_add_f32 v[48:49], v[66:67], v[78:79]
	v_pk_mul_f32 v[44:45], v[40:41], v[2:3] op_sel:[0,0] op_sel_hi:[0,1]
	s_nop 0
	v_pk_fma_f32 v[80:81], v[40:41], v[2:3], v[44:45] op_sel:[1,1,0] op_sel_hi:[1,0,1] neg_lo:[0,1,0]
	v_pk_add_f32 v[40:41], v[72:73], v[76:77] neg_lo:[0,1] neg_hi:[0,1]
	v_pk_add_f32 v[76:77], v[82:83], v[12:13]
	v_pk_add_f32 v[12:13], v[82:83], v[12:13] neg_lo:[0,1] neg_hi:[0,1]
	v_pk_add_f32 v[82:83], v[34:35], v[24:25]
	v_pk_add_f32 v[24:25], v[34:35], v[24:25] neg_lo:[0,1] neg_hi:[0,1]
	v_pk_mul_f32 v[44:45], v[40:41], v[58:59] op_sel:[0,0] op_sel_hi:[0,1]
	s_nop 0
	v_pk_mul_f32 v[34:35], v[24:25], v[8:9] op_sel:[0,0] op_sel_hi:[0,1]
	v_pk_fma_f32 v[72:73], v[40:41], v[58:59], v[44:45] op_sel:[1,1,0] op_sel_hi:[1,0,1] neg_lo:[0,1,0]
	v_pk_mul_f32 v[40:41], v[12:13], v[0:1] op_sel:[0,0] op_sel_hi:[0,1]
	s_nop 0
	v_pk_fma_f32 v[24:25], v[24:25], v[8:9], v[34:35] op_sel:[1,1,0] op_sel_hi:[1,0,1] neg_lo:[0,1,0]
	v_pk_add_f32 v[8:9], v[20:21], v[28:29]
	v_pk_mul_f32 v[20:21], v[10:11], v[2:3] op_sel:[0,0] op_sel_hi:[0,1]
	v_pk_add_f32 v[34:35], v[36:37], v[38:39] neg_lo:[0,1] neg_hi:[0,1]
	v_pk_fma_f32 v[10:11], v[10:11], v[2:3], v[20:21] op_sel:[1,1,0] op_sel_hi:[1,0,1] neg_lo:[0,1,0]
	v_pk_add_f32 v[20:21], v[6:7], v[14:15]
	v_pk_add_f32 v[6:7], v[6:7], v[14:15] neg_lo:[0,1] neg_hi:[0,1]
	v_pk_mul_f32 v[36:37], v[34:35], v[58:59] op_sel:[0,0] op_sel_hi:[0,1]
	v_pk_add_f32 v[38:39], v[42:43], v[64:65]
	v_pk_mul_f32 v[14:15], v[6:7], v[58:59] op_sel:[0,0] op_sel_hi:[0,1]
	v_pk_fma_f32 v[88:89], v[34:35], v[58:59], v[36:37] op_sel:[1,1,0] op_sel_hi:[1,0,1] neg_lo:[0,1,0]
	v_pk_fma_f32 v[12:13], v[12:13], v[0:1], v[40:41] op_sel:[1,1,0] op_sel_hi:[1,0,1] neg_lo:[0,1,0]
	v_pk_add_f32 v[40:41], v[46:47], v[62:63]
	v_pk_fma_f32 v[6:7], v[6:7], v[58:59], v[14:15] op_sel:[1,1,0] op_sel_hi:[1,0,1] neg_lo:[0,1,0]
	v_pk_add_f32 v[14:15], v[30:31], v[56:57] neg_lo:[0,1] neg_hi:[0,1]
	v_pk_add_f32 v[34:35], v[30:31], v[56:57]
	v_pk_mul_f32 v[28:29], v[14:15], v[0:1] op_sel:[0,0] op_sel_hi:[0,1]
	v_pk_add_f32 v[56:57], v[68:69], v[80:81]
	v_pk_fma_f32 v[36:37], v[14:15], v[0:1], v[28:29] op_sel:[1,1,0] op_sel_hi:[1,0,1] neg_lo:[0,1,0]
	v_pk_add_f32 v[14:15], v[42:43], v[64:65] neg_lo:[0,1] neg_hi:[0,1]
	v_pk_add_f32 v[64:65], v[76:77], v[86:87]
	v_pk_mul_f32 v[28:29], v[14:15], v[2:3] op_sel:[0,0] op_sel_hi:[0,1]
	v_pk_add_f32 v[94:95], v[4:5], v[6:7]
	v_pk_fma_f32 v[42:43], v[14:15], v[2:3], v[28:29] op_sel:[1,1,0] op_sel_hi:[1,0,1] neg_lo:[0,1,0]
	v_pk_add_f32 v[14:15], v[46:47], v[62:63] neg_lo:[0,1] neg_hi:[0,1]
	v_pk_add_f32 v[46:47], v[54:55], v[60:61]
	v_pk_mul_f32 v[28:29], v[14:15], v[0:1] op_sel:[0,0] op_sel_hi:[0,1]
	v_pk_add_f32 v[62:63], v[74:75], v[72:73]
	v_pk_fma_f32 v[44:45], v[14:15], v[0:1], v[28:29] op_sel:[1,1,0] op_sel_hi:[1,0,1] neg_lo:[0,1,0]
	v_pk_add_f32 v[14:15], v[54:55], v[60:61] neg_lo:[0,1] neg_hi:[0,1]
	v_pk_add_f32 v[54:55], v[70:71], v[84:85]
	v_pk_mul_f32 v[28:29], v[14:15], v[2:3] op_sel:[0,0] op_sel_hi:[0,1]
	v_pk_add_f32 v[4:5], v[4:5], v[6:7] neg_lo:[0,1] neg_hi:[0,1]
	v_pk_fma_f32 v[50:51], v[14:15], v[2:3], v[28:29] op_sel:[1,1,0] op_sel_hi:[1,0,1] neg_lo:[0,1,0]
	v_pk_add_f32 v[14:15], v[66:67], v[78:79] neg_lo:[0,1] neg_hi:[0,1]
	v_pk_mul_f32 v[6:7], v[4:5], v[2:3] op_sel:[0,0] op_sel_hi:[0,1]
	v_pk_add_f32 v[78:79], v[24:25], v[88:89]
	v_pk_mul_f32 v[28:29], v[14:15], v[0:1] op_sel:[0,0] op_sel_hi:[0,1]
	v_pk_fma_f32 v[96:97], v[4:5], v[2:3], v[6:7] op_sel:[1,1,0] op_sel_hi:[1,0,1] neg_lo:[0,1,0]
	s_nop 0
	v_pk_fma_f32 v[52:53], v[14:15], v[0:1], v[28:29] op_sel:[1,1,0] op_sel_hi:[1,0,1] neg_lo:[0,1,0]
	v_pk_add_f32 v[14:15], v[70:71], v[84:85] neg_lo:[0,1] neg_hi:[0,1]
	v_pk_add_f32 v[70:71], v[82:83], v[26:27]
	v_pk_mul_f32 v[28:29], v[14:15], v[2:3] op_sel:[0,0] op_sel_hi:[0,1]
	s_nop 0
	v_pk_fma_f32 v[58:59], v[14:15], v[2:3], v[28:29] op_sel:[1,1,0] op_sel_hi:[1,0,1] neg_lo:[0,1,0]
; __device__ __forceinline__ float2 cmul(float2 a, float2 b) { return make_float2(a.x * b.x - a.y * b.y, a.x * b.y + a.y * b.x); }
; template <int R, bool INV>
; __device__ __forceinline__ void butterflies(c32 (&v)[1 << R], float turns0) {
;     ...
; #pragma unroll
;   for (int k = 1; k < R; ++k) tbs[k] = cmul(tbs[k - 1], tbs[k - 1]);
; #pragma unroll
;   for (int kk = 0; kk < R; ++kk) {
;     const int k = INV ? (R - 1 - kk) : kk;
;     const int hd = RAD >> (k + 1);
; #pragma unroll
;     for (int j = 0; j < RAD; ++j) {
;       if ((j & hd) == 0) {
;         const int m = (j & (hd - 1)) * (16 / hd);
;         const float2 c = make_float2(TC[m], INV ? TS[m] : -TS[m]);
;         const float2 twf = cmul(tbs[k], c);
;         const c32 tw = {twf.x, twf.y};
;         const c32 a = v[j], b = v[j + hd];
;         if (!INV) { v[j] = a + b; v[j + hd] = cmul_pk(a - b, tw); }
;         else { const c32 bt = cmul_pk(b, tw); v[j] = a + bt; v[j + hd] = a - bt; }
;       }
;     }
;   }
	v_pk_add_f32 v[14:15], v[68:69], v[80:81] neg_lo:[0,1] neg_hi:[0,1]
	v_pk_add_f32 v[80:81], v[90:91], v[8:9]
	v_pk_mul_f32 v[28:29], v[14:15], v[0:1] op_sel:[0,0] op_sel_hi:[0,1]
	v_pk_add_f32 v[8:9], v[90:91], v[8:9] neg_lo:[0,1] neg_hi:[0,1]
	v_pk_fma_f32 v[60:61], v[14:15], v[0:1], v[28:29] op_sel:[1,1,0] op_sel_hi:[1,0,1] neg_lo:[0,1,0]
	v_pk_add_f32 v[14:15], v[74:75], v[72:73] neg_lo:[0,1] neg_hi:[0,1]
	v_pk_add_f32 v[72:73], v[12:13], v[18:19]
	v_pk_mul_f32 v[28:29], v[14:15], v[2:3] op_sel:[0,0] op_sel_hi:[0,1]
	v_pk_add_f32 v[12:13], v[12:13], v[18:19] neg_lo:[0,1] neg_hi:[0,1]
	v_pk_fma_f32 v[66:67], v[14:15], v[2:3], v[28:29] op_sel:[1,1,0] op_sel_hi:[1,0,1] neg_lo:[0,1,0]
	v_pk_add_f32 v[14:15], v[76:77], v[86:87] neg_lo:[0,1] neg_hi:[0,1]
	v_pk_add_f32 v[86:87], v[22:23], v[20:21]
	v_pk_mul_f32 v[28:29], v[14:15], v[0:1] op_sel:[0,0] op_sel_hi:[0,1]
	s_nop 0
	v_pk_fma_f32 v[68:69], v[14:15], v[0:1], v[28:29] op_sel:[1,1,0] op_sel_hi:[1,0,1] neg_lo:[0,1,0]
	v_pk_add_f32 v[14:15], v[82:83], v[26:27] neg_lo:[0,1] neg_hi:[0,1]
	s_nop 0
	v_pk_mul_f32 v[26:27], v[14:15], v[2:3] op_sel:[0,0] op_sel_hi:[0,1]
	s_nop 0
	v_pk_fma_f32 v[74:75], v[14:15], v[2:3], v[26:27] op_sel:[1,1,0] op_sel_hi:[1,0,1] neg_lo:[0,1,0]
	v_pk_mul_f32 v[14:15], v[12:13], v[0:1] op_sel:[0,0] op_sel_hi:[0,1]
	s_nop 0
	v_pk_fma_f32 v[76:77], v[12:13], v[0:1], v[14:15] op_sel:[1,1,0] op_sel_hi:[1,0,1] neg_lo:[0,1,0]
	v_pk_add_f32 v[12:13], v[24:25], v[88:89] neg_lo:[0,1] neg_hi:[0,1]
	v_pk_add_f32 v[88:89], v[16:17], v[10:11]
	v_pk_mul_f32 v[14:15], v[12:13], v[2:3] op_sel:[0,0] op_sel_hi:[0,1]
	s_nop 0
	v_pk_fma_f32 v[82:83], v[12:13], v[2:3], v[14:15] op_sel:[1,1,0] op_sel_hi:[1,0,1] neg_lo:[0,1,0]
	v_pk_mul_f32 v[12:13], v[8:9], v[0:1] op_sel:[0,0] op_sel_hi:[0,1]
	s_nop 0
	v_pk_fma_f32 v[84:85], v[8:9], v[0:1], v[12:13] op_sel:[1,1,0] op_sel_hi:[1,0,1] neg_lo:[0,1,0]
	v_pk_add_f32 v[8:9], v[22:23], v[20:21] neg_lo:[0,1] neg_hi:[0,1]
	s_nop 0
	v_pk_mul_f32 v[12:13], v[8:9], v[2:3] op_sel:[0,0] op_sel_hi:[0,1]
	s_nop 0
	v_pk_fma_f32 v[90:91], v[8:9], v[2:3], v[12:13] op_sel:[1,1,0] op_sel_hi:[1,0,1] neg_lo:[0,1,0]
	v_pk_add_f32 v[2:3], v[34:35], v[38:39] neg_lo:[0,1] neg_hi:[0,1]
	v_pk_add_f32 v[8:9], v[16:17], v[10:11] neg_lo:[0,1] neg_hi:[0,1]
	v_pk_mul_f32 v[4:5], v[2:3], v[0:1] op_sel:[0,0] op_sel_hi:[0,1]
	s_nop 0
	v_pk_fma_f32 v[30:31], v[2:3], v[0:1], v[4:5] op_sel:[1,1,0] op_sel_hi:[1,0,1] neg_lo:[0,1,0]
	v_pk_add_f32 v[2:3], v[36:37], v[42:43] neg_lo:[0,1] neg_hi:[0,1]
	v_pk_mul_f32 v[10:11], v[8:9], v[0:1] op_sel:[0,0] op_sel_hi:[0,1]
	s_nop 0
	v_pk_mul_f32 v[4:5], v[2:3], v[0:1] op_sel:[0,0] op_sel_hi:[0,1]
	v_pk_fma_f32 v[92:93], v[8:9], v[0:1], v[10:11] op_sel:[1,1,0] op_sel_hi:[1,0,1] neg_lo:[0,1,0]
	s_nop 0
	v_pk_fma_f32 v[28:29], v[2:3], v[0:1], v[4:5] op_sel:[1,1,0] op_sel_hi:[1,0,1] neg_lo:[0,1,0]
	v_pk_add_f32 v[2:3], v[40:41], v[46:47] neg_lo:[0,1] neg_hi:[0,1]
	s_nop 0
	v_pk_mul_f32 v[4:5], v[2:3], v[0:1] op_sel:[0,0] op_sel_hi:[0,1]
	s_nop 0
	v_pk_fma_f32 v[26:27], v[2:3], v[0:1], v[4:5] op_sel:[1,1,0] op_sel_hi:[1,0,1] neg_lo:[0,1,0]
	v_pk_add_f32 v[2:3], v[44:45], v[50:51] neg_lo:[0,1] neg_hi:[0,1]
	s_nop 0
	v_pk_mul_f32 v[4:5], v[2:3], v[0:1] op_sel:[0,0] op_sel_hi:[0,1]
	s_nop 0
	v_pk_fma_f32 v[24:25], v[2:3], v[0:1], v[4:5] op_sel:[1,1,0] op_sel_hi:[1,0,1] neg_lo:[0,1,0]
	v_pk_add_f32 v[2:3], v[48:49], v[54:55] neg_lo:[0,1] neg_hi:[0,1]
	s_nop 0
	v_pk_mul_f32 v[4:5], v[2:3], v[0:1] op_sel:[0,0] op_sel_hi:[0,1]
	s_nop 0
	v_pk_fma_f32 v[22:23], v[2:3], v[0:1], v[4:5] op_sel:[1,1,0] op_sel_hi:[1,0,1] neg_lo:[0,1,0]
	v_pk_add_f32 v[2:3], v[52:53], v[58:59] neg_lo:[0,1] neg_hi:[0,1]
	s_nop 0
	v_pk_mul_f32 v[4:5], v[2:3], v[0:1] op_sel:[0,0] op_sel_hi:[0,1]
	s_nop 0
	v_pk_fma_f32 v[20:21], v[2:3], v[0:1], v[4:5] op_sel:[1,1,0] op_sel_hi:[1,0,1] neg_lo:[0,1,0]
	v_pk_add_f32 v[2:3], v[56:57], v[62:63] neg_lo:[0,1] neg_hi:[0,1]
	s_nop 0
	v_pk_mul_f32 v[4:5], v[2:3], v[0:1] op_sel:[0,0] op_sel_hi:[0,1]
	s_nop 0
	v_pk_fma_f32 v[18:19], v[2:3], v[0:1], v[4:5] op_sel:[1,1,0] op_sel_hi:[1,0,1] neg_lo:[0,1,0]
	v_pk_add_f32 v[2:3], v[60:61], v[66:67] neg_lo:[0,1] neg_hi:[0,1]
	s_nop 0
	v_pk_mul_f32 v[4:5], v[2:3], v[0:1] op_sel:[0,0] op_sel_hi:[0,1]
	s_nop 0
	v_pk_fma_f32 v[16:17], v[2:3], v[0:1], v[4:5] op_sel:[1,1,0] op_sel_hi:[1,0,1] neg_lo:[0,1,0]
	v_pk_add_f32 v[2:3], v[64:65], v[70:71] neg_lo:[0,1] neg_hi:[0,1]
	s_nop 0
	v_pk_mul_f32 v[4:5], v[2:3], v[0:1] op_sel:[0,0] op_sel_hi:[0,1]
	s_nop 0
	v_pk_fma_f32 v[14:15], v[2:3], v[0:1], v[4:5] op_sel:[1,1,0] op_sel_hi:[1,0,1] neg_lo:[0,1,0]
	v_pk_add_f32 v[2:3], v[68:69], v[74:75] neg_lo:[0,1] neg_hi:[0,1]
	s_nop 0
	v_pk_mul_f32 v[4:5], v[2:3], v[0:1] op_sel:[0,0] op_sel_hi:[0,1]
	s_nop 0
	v_pk_fma_f32 v[12:13], v[2:3], v[0:1], v[4:5] op_sel:[1,1,0] op_sel_hi:[1,0,1] neg_lo:[0,1,0]
	v_pk_add_f32 v[2:3], v[72:73], v[78:79] neg_lo:[0,1] neg_hi:[0,1]
	s_nop 0
	v_pk_mul_f32 v[4:5], v[2:3], v[0:1] op_sel:[0,0] op_sel_hi:[0,1]
	s_nop 0
	v_pk_fma_f32 v[10:11], v[2:3], v[0:1], v[4:5] op_sel:[1,1,0] op_sel_hi:[1,0,1] neg_lo:[0,1,0]
	v_pk_add_f32 v[2:3], v[76:77], v[82:83] neg_lo:[0,1] neg_hi:[0,1]
	s_nop 0
	v_pk_mul_f32 v[4:5], v[2:3], v[0:1] op_sel:[0,0] op_sel_hi:[0,1]
	s_nop 0
	v_pk_fma_f32 v[8:9], v[2:3], v[0:1], v[4:5] op_sel:[1,1,0] op_sel_hi:[1,0,1] neg_lo:[0,1,0]
	v_pk_add_f32 v[2:3], v[80:81], v[86:87] neg_lo:[0,1] neg_hi:[0,1]
	s_nop 0
	v_pk_mul_f32 v[4:5], v[2:3], v[0:1] op_sel:[0,0] op_sel_hi:[0,1]
	s_nop 0
	v_pk_fma_f32 v[6:7], v[2:3], v[0:1], v[4:5] op_sel:[1,1,0] op_sel_hi:[1,0,1] neg_lo:[0,1,0]
	v_pk_add_f32 v[2:3], v[84:85], v[90:91] neg_lo:[0,1] neg_hi:[0,1]
	s_nop 0
; __device__ __forceinline__ float2 cmul(float2 a, float2 b) { return make_float2(a.x * b.x - a.y * b.y, a.x * b.y + a.y * b.x); }
; __device__ __forceinline__ float2 twid(float turns) { return make_float2(__builtin_amdgcn_cosf(turns), -__builtin_amdgcn_sinf(turns)); }
; __device__ __forceinline__ float2 unpk2(unsigned w) { return make_float2(bflo(w), bfhi(w)); }
; template <int LOGN, int R, int DLOG, bool INV, int MODE, class F>
; __device__ __forceinline__ void fft_pass(float2* X, const F& f) {
;     ...
;   auto fetch = [&](int g, c32 (&dst)[RAD]) {
;     const int base = gbase(g);
; #pragma unroll
;     for (int j = 0; j < RAD; ++j) { if constexpr (MODE == 1) { const float2 sv = f(base + (j << DLOG)); dst[j] = (c32){sv.x, sv.y}; } }
;   };
;   c32 nxt[RAD];
;   if constexpr (MODE == 1) fetch(tid0, nxt);
;   __device__ __forceinline__ float2 operator()(int i) const { const float2 wv = unpk2(Wd[i]); return half ? cmul(wv, twid((float)(i & (L - 1)) * invTurn)) : wv; }
	v_pk_mul_f32 v[4:5], v[2:3], v[0:1] op_sel:[0,0] op_sel_hi:[0,1]
	s_nop 0
	v_pk_fma_f32 v[4:5], v[2:3], v[0:1], v[4:5] op_sel:[1,1,0] op_sel_hi:[1,0,1] neg_lo:[0,1,0]
	v_pk_add_f32 v[2:3], v[88:89], v[94:95] neg_lo:[0,1] neg_hi:[0,1]
	s_nop 0
	v_pk_mul_f32 v[98:99], v[2:3], v[0:1] op_sel:[0,0] op_sel_hi:[0,1]
	s_nop 0
	v_pk_fma_f32 v[2:3], v[2:3], v[0:1], v[98:99] op_sel:[1,1,0] op_sel_hi:[1,0,1] neg_lo:[0,1,0]
	v_pk_add_f32 v[98:99], v[92:93], v[96:97] neg_lo:[0,1] neg_hi:[0,1]
	s_nop 0
	v_pk_mul_f32 v[100:101], v[98:99], v[0:1] op_sel:[0,0] op_sel_hi:[0,1]
	s_nop 0
	v_pk_fma_f32 v[0:1], v[98:99], v[0:1], v[100:101] op_sel:[1,1,0] op_sel_hi:[1,0,1] neg_lo:[0,1,0]
	v_and_or_b32 v98, v32, s71, v124
	v_ashrrev_i32_e32 v99, 31, v98
	v_lshl_add_u64 v[120:121], v[98:99], 2, s[34:35]
	v_lshlrev_b32_e32 v207, 2, v98
	v_add_u32_e32 v208, 0x1000, v207
	v_add_u32_e32 v209, 0x2000, v207
	v_add_u32_e32 v210, 0x3000, v207
	v_add_u32_e32 v211, 0x4000, v207
	v_add_u32_e32 v212, 0x5000, v207
	v_add_u32_e32 v213, 0x6000, v207
	v_add_u32_e32 v214, 0x7000, v207
	v_add_u32_e32 v215, 0x8000, v207
	v_add_u32_e32 v216, 0x9000, v207
	v_add_u32_e32 v217, 0xa000, v207
	v_add_u32_e32 v218, 0xb000, v207
	v_add_u32_e32 v219, 0xc000, v207
	v_add_u32_e32 v220, 0xd000, v207
	v_add_u32_e32 v221, 0xe000, v207
	v_add_u32_e32 v222, 0xf000, v207
	global_load_dword v207, v207, s[34:35]
	global_load_dword v208, v208, s[34:35]
	global_load_dword v209, v209, s[34:35]
	global_load_dword v210, v210, s[34:35]
	global_load_dword v211, v211, s[34:35]
	global_load_dword v212, v212, s[34:35]
	global_load_dword v213, v213, s[34:35]
	global_load_dword v214, v214, s[34:35]
	global_load_dword v215, v215, s[34:35]
	global_load_dword v216, v216, s[34:35]
	global_load_dword v217, v217, s[34:35]
	global_load_dword v218, v218, s[34:35]
	global_load_dword v219, v219, s[34:35]
	global_load_dword v220, v220, s[34:35]
	global_load_dword v221, v221, s[34:35]
	global_load_dword v222, v222, s[34:35]
	s_waitcnt vmcnt(15)
	v_mov_b32_e32 v99, v207
	s_waitcnt vmcnt(0)
	v_lshlrev_b32_e32 v98, 16, v99
	v_and_b32_e32 v99, 0xffff0000, v99
	s_cbranch_vccnz .LBB0_661
	v_cvt_f32_u32_e32 v100, v124
	v_mul_f32_e32 v101, 0x38000000, v100
	v_sin_f32_e32 v100, v101
	v_cos_f32_e32 v102, v101
	v_pk_mul_f32 v[100:101], v[100:101], v[98:99] op_sel:[0,1] op_sel_hi:[0,0]
	v_pk_fma_f32 v[104:105], v[102:103], v[98:99], v[100:101]
	v_pk_fma_f32 v[98:99], v[102:103], v[98:99], v[100:101] op_sel_hi:[0,1,1] neg_lo:[0,0,1] neg_hi:[0,0,1]
	v_mov_b32_e32 v105, v99
	v_mov_b64_e32 v[98:99], v[104:105]
.LBB0_661:
	v_add_co_u32_e32 v100, vcc, 0x1000, v120
	s_nop 1
	v_addc_co_u32_e32 v101, vcc, 0, v121, vcc
	s_waitcnt vmcnt(14)
	v_mov_b32_e32 v101, v208
	s_and_b64 vcc, exec, s[40:41]
	s_waitcnt vmcnt(0)
	v_lshlrev_b32_e32 v100, 16, v101
	v_and_b32_e32 v101, 0xffff0000, v101
	s_cbranch_vccnz .LBB0_663
	v_or_b32_e32 v102, 0x400, v124
	v_cvt_f32_u32_e32 v102, v102
	v_mul_f32_e32 v103, 0x38000000, v102
	v_sin_f32_e32 v102, v103
	v_cos_f32_e32 v104, v103
	v_pk_mul_f32 v[102:103], v[102:103], v[100:101] op_sel:[0,1] op_sel_hi:[0,0]
	v_pk_fma_f32 v[106:107], v[104:105], v[100:101], v[102:103]
	v_pk_fma_f32 v[100:101], v[104:105], v[100:101], v[102:103] op_sel_hi:[0,1,1] neg_lo:[0,0,1] neg_hi:[0,0,1]
	v_mov_b32_e32 v107, v101
	v_mov_b64_e32 v[100:101], v[106:107]
.LBB0_663:
	v_add_co_u32_e32 v102, vcc, 0x2000, v120
	s_nop 1
	v_addc_co_u32_e32 v103, vcc, 0, v121, vcc
	s_waitcnt vmcnt(13)
	v_mov_b32_e32 v103, v209
	s_and_b64 vcc, exec, s[40:41]
	s_waitcnt vmcnt(0)
	v_lshlrev_b32_e32 v102, 16, v103
	v_and_b32_e32 v103, 0xffff0000, v103
	s_cbranch_vccnz .LBB0_665
	v_or_b32_e32 v104, 0x800, v124
	v_cvt_f32_u32_e32 v104, v104
	v_mul_f32_e32 v105, 0x38000000, v104
	v_sin_f32_e32 v104, v105
	v_cos_f32_e32 v106, v105
	v_pk_mul_f32 v[104:105], v[104:105], v[102:103] op_sel:[0,1] op_sel_hi:[0,0]
	v_pk_fma_f32 v[108:109], v[106:107], v[102:103], v[104:105]
	v_pk_fma_f32 v[102:103], v[106:107], v[102:103], v[104:105] op_sel_hi:[0,1,1] neg_lo:[0,0,1] neg_hi:[0,0,1]
	v_mov_b32_e32 v109, v103
	v_mov_b64_e32 v[102:103], v[108:109]
.LBB0_665:
	v_add_co_u32_e32 v104, vcc, 0x3000, v120
	s_nop 1
	v_addc_co_u32_e32 v105, vcc, 0, v121, vcc
	s_waitcnt vmcnt(12)
	v_mov_b32_e32 v105, v210
	s_and_b64 vcc, exec, s[40:41]
	s_waitcnt vmcnt(0)
	v_lshlrev_b32_e32 v104, 16, v105
	v_and_b32_e32 v105, 0xffff0000, v105
	s_cbranch_vccnz .LBB0_667
	v_or_b32_e32 v106, 0xc00, v124
	v_cvt_f32_u32_e32 v106, v106
	v_mul_f32_e32 v107, 0x38000000, v106
	v_sin_f32_e32 v106, v107
	v_cos_f32_e32 v108, v107
	v_pk_mul_f32 v[106:107], v[106:107], v[104:105] op_sel:[0,1] op_sel_hi:[0,0]
	v_pk_fma_f32 v[110:111], v[108:109], v[104:105], v[106:107]
	v_pk_fma_f32 v[104:105], v[108:109], v[104:105], v[106:107] op_sel_hi:[0,1,1] neg_lo:[0,0,1] neg_hi:[0,0,1]
	v_mov_b32_e32 v111, v105
	v_mov_b64_e32 v[104:105], v[110:111]
.LBB0_667:
	v_add_co_u32_e32 v106, vcc, 0x4000, v120
	s_nop 1
	v_addc_co_u32_e32 v107, vcc, 0, v121, vcc
	s_waitcnt vmcnt(11)
	v_mov_b32_e32 v107, v211
	s_and_b64 vcc, exec, s[40:41]
	s_waitcnt vmcnt(0)
	v_lshlrev_b32_e32 v106, 16, v107
	v_and_b32_e32 v107, 0xffff0000, v107
	s_cbranch_vccnz .LBB0_669
	v_or_b32_e32 v108, 0x1000, v124
	v_cvt_f32_u32_e32 v108, v108
	v_mul_f32_e32 v109, 0x38000000, v108
	v_sin_f32_e32 v108, v109
	v_cos_f32_e32 v110, v109
	v_pk_mul_f32 v[108:109], v[108:109], v[106:107] op_sel:[0,1] op_sel_hi:[0,0]
	v_pk_fma_f32 v[112:113], v[110:111], v[106:107], v[108:109]
	v_pk_fma_f32 v[106:107], v[110:111], v[106:107], v[108:109] op_sel_hi:[0,1,1] neg_lo:[0,0,1] neg_hi:[0,0,1]
	v_mov_b32_e32 v113, v107
	v_mov_b64_e32 v[106:107], v[112:113]
; __device__ __forceinline__ float2 cmul(float2 a, float2 b) { return make_float2(a.x * b.x - a.y * b.y, a.x * b.y + a.y * b.x); }
; __device__ __forceinline__ float2 twid(float turns) { return make_float2(__builtin_amdgcn_cosf(turns), -__builtin_amdgcn_sinf(turns)); }
; __device__ __forceinline__ float2 unpk2(unsigned w) { return make_float2(bflo(w), bfhi(w)); }
;   __device__ __forceinline__ float2 operator()(int i) const { const float2 wv = unpk2(Wd[i]); return half ? cmul(wv, twid((float)(i & (L - 1)) * invTurn)) : wv; }
.LBB0_669:
	v_add_co_u32_e32 v108, vcc, 0x5000, v120
	s_nop 1
	v_addc_co_u32_e32 v109, vcc, 0, v121, vcc
	s_waitcnt vmcnt(10)
	v_mov_b32_e32 v109, v212
	s_and_b64 vcc, exec, s[40:41]
	s_waitcnt vmcnt(0)
	v_lshlrev_b32_e32 v108, 16, v109
	v_and_b32_e32 v109, 0xffff0000, v109
	s_cbranch_vccnz .LBB0_671
	v_or_b32_e32 v110, 0x1400, v124
	v_cvt_f32_u32_e32 v110, v110
	v_mul_f32_e32 v111, 0x38000000, v110
	v_sin_f32_e32 v110, v111
	v_cos_f32_e32 v112, v111
	v_pk_mul_f32 v[110:111], v[110:111], v[108:109] op_sel:[0,1] op_sel_hi:[0,0]
	v_pk_fma_f32 v[114:115], v[112:113], v[108:109], v[110:111]
	v_pk_fma_f32 v[108:109], v[112:113], v[108:109], v[110:111] op_sel_hi:[0,1,1] neg_lo:[0,0,1] neg_hi:[0,0,1]
	v_mov_b32_e32 v115, v109
	v_mov_b64_e32 v[108:109], v[114:115]
.LBB0_671:
	v_add_co_u32_e32 v110, vcc, 0x6000, v120
	s_nop 1
	v_addc_co_u32_e32 v111, vcc, 0, v121, vcc
	s_waitcnt vmcnt(9)
	v_mov_b32_e32 v110, v213
	s_and_b64 vcc, exec, s[40:41]
	s_waitcnt vmcnt(0)
	v_lshlrev_b32_e32 v112, 16, v110
	v_and_b32_e32 v113, 0xffff0000, v110
	s_cbranch_vccnz .LBB0_673
	v_or_b32_e32 v110, 0x1800, v124
	v_cvt_f32_u32_e32 v110, v110
	v_mul_f32_e32 v111, 0x38000000, v110
	v_sin_f32_e32 v110, v111
	v_cos_f32_e32 v114, v111
	v_pk_mul_f32 v[110:111], v[110:111], v[112:113] op_sel:[0,1] op_sel_hi:[0,0]
	v_pk_fma_f32 v[116:117], v[114:115], v[112:113], v[110:111]
	v_pk_fma_f32 v[110:111], v[114:115], v[112:113], v[110:111] op_sel_hi:[0,1,1] neg_lo:[0,0,1] neg_hi:[0,0,1]
	v_mov_b32_e32 v117, v111
	v_mov_b64_e32 v[112:113], v[116:117]
.LBB0_673:
	v_add_co_u32_e32 v110, vcc, 0x7000, v120
	s_nop 1
	v_addc_co_u32_e32 v111, vcc, 0, v121, vcc
	s_waitcnt vmcnt(8)
	v_mov_b32_e32 v111, v214
	s_and_b64 vcc, exec, s[40:41]
	s_waitcnt vmcnt(0)
	v_lshlrev_b32_e32 v110, 16, v111
	v_and_b32_e32 v111, 0xffff0000, v111
	s_cbranch_vccnz .LBB0_675
	v_or_b32_e32 v114, 0x1c00, v124
	v_cvt_f32_u32_e32 v114, v114
	v_mul_f32_e32 v115, 0x38000000, v114
	v_sin_f32_e32 v114, v115
	v_cos_f32_e32 v116, v115
	v_pk_mul_f32 v[114:115], v[114:115], v[110:111] op_sel:[0,1] op_sel_hi:[0,0]
	v_pk_fma_f32 v[118:119], v[116:117], v[110:111], v[114:115]
	v_pk_fma_f32 v[110:111], v[116:117], v[110:111], v[114:115] op_sel_hi:[0,1,1] neg_lo:[0,0,1] neg_hi:[0,0,1]
	v_mov_b32_e32 v119, v111
	v_mov_b64_e32 v[110:111], v[118:119]
.LBB0_675:
	v_add_co_u32_e32 v114, vcc, 0x8000, v120
	s_nop 1
	v_addc_co_u32_e32 v115, vcc, 0, v121, vcc
	s_waitcnt vmcnt(7)
	v_mov_b32_e32 v115, v215
	s_and_b64 vcc, exec, s[40:41]
	s_waitcnt vmcnt(0)
	v_lshlrev_b32_e32 v114, 16, v115
	v_and_b32_e32 v115, 0xffff0000, v115
	s_cbranch_vccnz .LBB0_677
	v_or_b32_e32 v116, 0x2000, v124
	v_cvt_f32_u32_e32 v116, v116
	v_mul_f32_e32 v117, 0x38000000, v116
	v_sin_f32_e32 v116, v117
	v_cos_f32_e32 v118, v117
	v_pk_mul_f32 v[116:117], v[116:117], v[114:115] op_sel:[0,1] op_sel_hi:[0,0]
	v_pk_fma_f32 v[122:123], v[118:119], v[114:115], v[116:117]
	v_pk_fma_f32 v[114:115], v[118:119], v[114:115], v[116:117] op_sel_hi:[0,1,1] neg_lo:[0,0,1] neg_hi:[0,0,1]
	v_mov_b32_e32 v123, v115
	v_mov_b64_e32 v[114:115], v[122:123]
.LBB0_677:
	v_add_co_u32_e32 v116, vcc, 0x9000, v120
	s_nop 1
	v_addc_co_u32_e32 v117, vcc, 0, v121, vcc
	s_waitcnt vmcnt(6)
	v_mov_b32_e32 v117, v216
	s_and_b64 vcc, exec, s[40:41]
	s_waitcnt vmcnt(0)
	v_lshlrev_b32_e32 v116, 16, v117
	v_and_b32_e32 v117, 0xffff0000, v117
	s_cbranch_vccnz .LBB0_679
	v_or_b32_e32 v118, 0x2400, v124
	v_cvt_f32_u32_e32 v118, v118
	v_mul_f32_e32 v119, 0x38000000, v118
	v_sin_f32_e32 v118, v119
	v_cos_f32_e32 v122, v119
	v_pk_mul_f32 v[118:119], v[118:119], v[116:117] op_sel:[0,1] op_sel_hi:[0,0]
	v_pk_fma_f32 v[126:127], v[122:123], v[116:117], v[118:119]
	v_pk_fma_f32 v[116:117], v[122:123], v[116:117], v[118:119] op_sel_hi:[0,1,1] neg_lo:[0,0,1] neg_hi:[0,0,1]
	v_mov_b32_e32 v127, v117
	v_mov_b64_e32 v[116:117], v[126:127]
; __device__ __forceinline__ float2 cmul(float2 a, float2 b) { return make_float2(a.x * b.x - a.y * b.y, a.x * b.y + a.y * b.x); }
; __device__ __forceinline__ float2 twid(float turns) { return make_float2(__builtin_amdgcn_cosf(turns), -__builtin_amdgcn_sinf(turns)); }
; __device__ __forceinline__ float2 unpk2(unsigned w) { return make_float2(bflo(w), bfhi(w)); }
;   __device__ __forceinline__ float2 operator()(int i) const { const float2 wv = unpk2(Wd[i]); return half ? cmul(wv, twid((float)(i & (L - 1)) * invTurn)) : wv; }
.LBB0_679:
	v_add_co_u32_e32 v118, vcc, 0xa000, v120
	s_nop 1
	v_addc_co_u32_e32 v119, vcc, 0, v121, vcc
	s_waitcnt vmcnt(5)
	v_mov_b32_e32 v119, v217
	s_and_b64 vcc, exec, s[40:41]
	s_waitcnt vmcnt(0)
	v_lshlrev_b32_e32 v118, 16, v119
	v_and_b32_e32 v119, 0xffff0000, v119
	s_cbranch_vccnz .LBB0_681
	v_or_b32_e32 v122, 0x2800, v124
	v_cvt_f32_u32_e32 v122, v122
	v_mul_f32_e32 v123, 0x38000000, v122
	v_sin_f32_e32 v122, v123
	v_cos_f32_e32 v126, v123
	v_pk_mul_f32 v[122:123], v[122:123], v[118:119] op_sel:[0,1] op_sel_hi:[0,0]
	v_pk_fma_f32 v[128:129], v[126:127], v[118:119], v[122:123]
	v_pk_fma_f32 v[118:119], v[126:127], v[118:119], v[122:123] op_sel_hi:[0,1,1] neg_lo:[0,0,1] neg_hi:[0,0,1]
	v_mov_b32_e32 v129, v119
	v_mov_b64_e32 v[118:119], v[128:129]
.LBB0_681:
	v_add_co_u32_e32 v122, vcc, 0xb000, v120
	s_nop 1
	v_addc_co_u32_e32 v123, vcc, 0, v121, vcc
	s_waitcnt vmcnt(4)
	v_mov_b32_e32 v123, v218
	s_and_b64 vcc, exec, s[40:41]
	s_waitcnt vmcnt(0)
	v_lshlrev_b32_e32 v122, 16, v123
	v_and_b32_e32 v123, 0xffff0000, v123
	s_cbranch_vccnz .LBB0_683
	v_or_b32_e32 v125, 0x2c00, v124
	v_cvt_f32_u32_e32 v125, v125
	v_mul_f32_e32 v125, 0x38000000, v125
	v_sin_f32_e32 v126, v125
	v_cos_f32_e32 v128, v125
	v_pk_mul_f32 v[126:127], v[126:127], v[122:123] op_sel:[0,1] op_sel_hi:[0,0]
	v_pk_fma_f32 v[130:131], v[128:129], v[122:123], v[126:127]
	v_pk_fma_f32 v[122:123], v[128:129], v[122:123], v[126:127] op_sel_hi:[0,1,1] neg_lo:[0,0,1] neg_hi:[0,0,1]
	v_mov_b32_e32 v131, v123
	v_mov_b64_e32 v[122:123], v[130:131]
.LBB0_683:
	v_add_co_u32_e32 v126, vcc, 0xc000, v120
	s_nop 1
	v_addc_co_u32_e32 v127, vcc, 0, v121, vcc
	s_waitcnt vmcnt(3)
	v_mov_b32_e32 v125, v219
	s_and_b64 vcc, exec, s[40:41]
	s_waitcnt vmcnt(0)
	v_lshlrev_b32_e32 v126, 16, v125
	v_and_b32_e32 v127, 0xffff0000, v125
	s_cbranch_vccnz .LBB0_685
	v_or_b32_e32 v125, 0x3000, v124
	v_cvt_f32_u32_e32 v125, v125
	v_mul_f32_e32 v125, 0x38000000, v125
	v_sin_f32_e32 v128, v125
	v_cos_f32_e32 v130, v125
	v_pk_mul_f32 v[128:129], v[128:129], v[126:127] op_sel:[0,1] op_sel_hi:[0,0]
	v_pk_fma_f32 v[132:133], v[130:131], v[126:127], v[128:129]
	v_pk_fma_f32 v[126:127], v[130:131], v[126:127], v[128:129] op_sel_hi:[0,1,1] neg_lo:[0,0,1] neg_hi:[0,0,1]
	v_mov_b32_e32 v133, v127
	v_mov_b64_e32 v[126:127], v[132:133]
.LBB0_685:
	v_add_co_u32_e32 v128, vcc, 0xd000, v120
	s_nop 1
	v_addc_co_u32_e32 v129, vcc, 0, v121, vcc
	s_waitcnt vmcnt(2)
	v_mov_b32_e32 v125, v220
	s_and_b64 vcc, exec, s[40:41]
	s_waitcnt vmcnt(0)
	v_lshlrev_b32_e32 v130, 16, v125
	v_and_b32_e32 v131, 0xffff0000, v125
	s_cbranch_vccnz .LBB0_687
	v_or_b32_e32 v125, 0x3400, v124
	v_cvt_f32_u32_e32 v125, v125
	v_mul_f32_e32 v125, 0x38000000, v125
	v_sin_f32_e32 v128, v125
	v_cos_f32_e32 v132, v125
	v_pk_mul_f32 v[128:129], v[128:129], v[130:131] op_sel:[0,1] op_sel_hi:[0,0]
	v_pk_fma_f32 v[134:135], v[132:133], v[130:131], v[128:129]
	v_pk_fma_f32 v[128:129], v[132:133], v[130:131], v[128:129] op_sel_hi:[0,1,1] neg_lo:[0,0,1] neg_hi:[0,0,1]
	v_mov_b32_e32 v135, v129
	v_mov_b64_e32 v[130:131], v[134:135]
.LBB0_687:
	v_add_co_u32_e32 v128, vcc, 0xe000, v120
	s_nop 1
	v_addc_co_u32_e32 v129, vcc, 0, v121, vcc
	s_waitcnt vmcnt(1)
	v_mov_b32_e32 v125, v221
	s_and_b64 vcc, exec, s[40:41]
	s_waitcnt vmcnt(0)
	v_lshlrev_b32_e32 v132, 16, v125
	v_and_b32_e32 v133, 0xffff0000, v125
	s_cbranch_vccnz .LBB0_689
	v_or_b32_e32 v125, 0x3800, v124
	v_cvt_f32_u32_e32 v125, v125
	v_mul_f32_e32 v125, 0x38000000, v125
	v_sin_f32_e32 v128, v125
	v_cos_f32_e32 v134, v125
	v_pk_mul_f32 v[128:129], v[128:129], v[132:133] op_sel:[0,1] op_sel_hi:[0,0]
	v_pk_fma_f32 v[136:137], v[134:135], v[132:133], v[128:129]
	v_pk_fma_f32 v[128:129], v[134:135], v[132:133], v[128:129] op_sel_hi:[0,1,1] neg_lo:[0,0,1] neg_hi:[0,0,1]
	v_mov_b32_e32 v137, v129
	v_mov_b64_e32 v[132:133], v[136:137]
.LBB0_689:
	v_add_co_u32_e32 v120, vcc, 0xf000, v120
	s_nop 1
	v_addc_co_u32_e32 v121, vcc, 0, v121, vcc
	s_waitcnt vmcnt(0)
	v_mov_b32_e32 v120, v222
	s_and_b64 vcc, exec, s[40:41]
	s_waitcnt vmcnt(0)
	v_lshlrev_b32_e32 v134, 16, v120
	v_and_b32_e32 v135, 0xffff0000, v120
	s_cbranch_vccnz .LBB0_691
	v_or_b32_e32 v120, 0x3c00, v124
	v_cvt_f32_u32_e32 v120, v120
	v_mul_f32_e32 v121, 0x38000000, v120
	v_sin_f32_e32 v120, v121
	v_cos_f32_e32 v124, v121
	v_pk_mul_f32 v[120:121], v[120:121], v[134:135] op_sel:[0,1] op_sel_hi:[0,0]
	v_pk_fma_f32 v[128:129], v[124:125], v[134:135], v[120:121]
	v_pk_fma_f32 v[134:135], v[124:125], v[134:135], v[120:121] op_sel_hi:[0,1,1] neg_lo:[0,0,1] neg_hi:[0,0,1]
	v_mov_b32_e32 v134, v128

; __device__ __forceinline__ float2 cmul(float2 a, float2 b) { return make_float2(a.x * b.x - a.y * b.y, a.x * b.y + a.y * b.x); }
; __device__ __forceinline__ float2 twid(float turns) { return make_float2(__builtin_amdgcn_cosf(turns), -__builtin_amdgcn_sinf(turns)); }
; __device__ __forceinline__ float2 unpk2(unsigned w) { return make_float2(bflo(w), bfhi(w)); }
; template <int LOGN, int R, int DLOG, bool INV, int MODE, class F>
; __device__ __forceinline__ void fft_pass(float2* X, const F& f) {
;     ...
;   for (int g = tid0; g < NGR; g += 512) {
;     const int lo = g & (dmin - 1), base = gbase(g), pb = phys(base);
;     c32 v[RAD];
;     if constexpr (MODE == 1) {
; #pragma unroll
;       for (int j = 0; j < RAD; ++j) v[j] = nxt[j];
;       if (g + 512 < NGR) fetch(g + 512, nxt);
;   __device__ __forceinline__ float2 operator()(int i) const { const float2 wv = unpk2(Wd[i]); return half ? cmul(wv, twid((float)(i & (L - 1)) * invTurn)) : wv; }
.LBB0_694:
	v_cmp_lt_i32_e64 s[0:1], s12, v167
	v_add_u32_e32 v169, 0x2000, v32
	s_and_saveexec_b64 s[26:27], s[0:1]
	s_xor_b64 s[26:27], exec, s[26:27]
	v_add_u32_e32 v169, 0x2000, v32
	s_or_saveexec_b64 s[26:27], s[26:27]
	v_add_u32_e32 v168, 0x200, v167
	v_mov_b32_e32 v153, v135
	v_mov_b32_e32 v152, v134
	v_mov_b64_e32 v[120:121], v[98:99]
	v_mov_b64_e32 v[124:125], v[100:101]
	v_mov_b64_e32 v[128:129], v[102:103]
	v_mov_b64_e32 v[136:137], v[104:105]
	v_mov_b64_e32 v[138:139], v[106:107]
	v_mov_b64_e32 v[140:141], v[108:109]
	v_mov_b64_e32 v[142:143], v[112:113]
	v_mov_b64_e32 v[144:145], v[110:111]
	v_mov_b64_e32 v[146:147], v[114:115]
	v_mov_b64_e32 v[148:149], v[116:117]
	v_mov_b64_e32 v[150:151], v[118:119]
	v_mov_b64_e32 v[154:155], v[122:123]
	v_mov_b64_e32 v[156:157], v[126:127]
	v_mov_b64_e32 v[158:159], v[130:131]
	v_mov_b64_e32 v[160:161], v[132:133]
	s_xor_b64 exec, exec, s[26:27]
	s_cbranch_execz .LBB0_693
	v_and_b32_e32 v170, 0x3ff, v168
	v_and_or_b32 v120, v169, s71, v170
	v_ashrrev_i32_e32 v121, 31, v120
	v_lshl_add_u64 v[152:153], v[120:121], 2, s[34:35]
	v_lshlrev_b32_e32 v207, 2, v120
	v_add_u32_e32 v208, 0x1000, v207
	v_add_u32_e32 v209, 0x2000, v207
	v_add_u32_e32 v210, 0x3000, v207
	v_add_u32_e32 v211, 0x4000, v207
	v_add_u32_e32 v212, 0x5000, v207
	v_add_u32_e32 v213, 0x6000, v207
	v_add_u32_e32 v214, 0x7000, v207
	v_add_u32_e32 v215, 0x8000, v207
	v_add_u32_e32 v216, 0x9000, v207
	v_add_u32_e32 v217, 0xa000, v207
	v_add_u32_e32 v218, 0xb000, v207
	v_add_u32_e32 v219, 0xc000, v207
	v_add_u32_e32 v220, 0xd000, v207
	v_add_u32_e32 v221, 0xe000, v207
	v_add_u32_e32 v222, 0xf000, v207
	global_load_dword v207, v207, s[34:35]
	global_load_dword v208, v208, s[34:35]
	global_load_dword v209, v209, s[34:35]
	global_load_dword v210, v210, s[34:35]
	global_load_dword v211, v211, s[34:35]
	global_load_dword v212, v212, s[34:35]
	global_load_dword v213, v213, s[34:35]
	global_load_dword v214, v214, s[34:35]
	global_load_dword v215, v215, s[34:35]
	global_load_dword v216, v216, s[34:35]
	global_load_dword v217, v217, s[34:35]
	global_load_dword v218, v218, s[34:35]
	global_load_dword v219, v219, s[34:35]
	global_load_dword v220, v220, s[34:35]
	global_load_dword v221, v221, s[34:35]
	global_load_dword v222, v222, s[34:35]
	s_waitcnt vmcnt(15)
	v_mov_b32_e32 v121, v207
	s_and_b64 vcc, exec, s[40:41]
	s_waitcnt vmcnt(0)
	v_lshlrev_b32_e32 v120, 16, v121
	v_and_b32_e32 v121, 0xffff0000, v121
	s_cbranch_vccnz .LBB0_699
	v_cvt_f32_u32_e32 v124, v170
	v_mul_f32_e32 v125, 0x38000000, v124
	v_sin_f32_e32 v124, v125
	v_cos_f32_e32 v128, v125
	v_pk_mul_f32 v[124:125], v[124:125], v[120:121] op_sel:[0,1] op_sel_hi:[0,0]
	v_pk_fma_f32 v[136:137], v[128:129], v[120:121], v[124:125]
	v_pk_fma_f32 v[120:121], v[128:129], v[120:121], v[124:125] op_sel_hi:[0,1,1] neg_lo:[0,0,1] neg_hi:[0,0,1]
	v_mov_b32_e32 v137, v121
	v_mov_b64_e32 v[120:121], v[136:137]
.LBB0_699:
	v_add_co_u32_e32 v124, vcc, 0x1000, v152
	s_nop 1
	v_addc_co_u32_e32 v125, vcc, 0, v153, vcc
	s_waitcnt vmcnt(14)
	v_mov_b32_e32 v125, v208
	s_and_b64 vcc, exec, s[40:41]
	s_waitcnt vmcnt(0)
	v_lshlrev_b32_e32 v124, 16, v125
	v_and_b32_e32 v125, 0xffff0000, v125
	s_cbranch_vccnz .LBB0_701
	v_or_b32_e32 v128, 0x400, v170
	v_cvt_f32_u32_e32 v128, v128
	v_mul_f32_e32 v129, 0x38000000, v128
	v_sin_f32_e32 v128, v129
	v_cos_f32_e32 v136, v129
	v_pk_mul_f32 v[128:129], v[128:129], v[124:125] op_sel:[0,1] op_sel_hi:[0,0]
	v_pk_fma_f32 v[138:139], v[136:137], v[124:125], v[128:129]
	v_pk_fma_f32 v[124:125], v[136:137], v[124:125], v[128:129] op_sel_hi:[0,1,1] neg_lo:[0,0,1] neg_hi:[0,0,1]
	v_mov_b32_e32 v139, v125
	v_mov_b64_e32 v[124:125], v[138:139]
.LBB0_701:
	v_add_co_u32_e32 v128, vcc, 0x2000, v152
	s_nop 1
	v_addc_co_u32_e32 v129, vcc, 0, v153, vcc
	s_waitcnt vmcnt(13)
	v_mov_b32_e32 v129, v209
	s_and_b64 vcc, exec, s[40:41]
	s_waitcnt vmcnt(0)
	v_lshlrev_b32_e32 v128, 16, v129
	v_and_b32_e32 v129, 0xffff0000, v129
	s_cbranch_vccnz .LBB0_703
	v_or_b32_e32 v136, 0x800, v170
	v_cvt_f32_u32_e32 v136, v136
	v_mul_f32_e32 v137, 0x38000000, v136
	v_sin_f32_e32 v136, v137
	v_cos_f32_e32 v138, v137
	v_pk_mul_f32 v[136:137], v[136:137], v[128:129] op_sel:[0,1] op_sel_hi:[0,0]
	v_pk_fma_f32 v[140:141], v[138:139], v[128:129], v[136:137]
	v_pk_fma_f32 v[128:129], v[138:139], v[128:129], v[136:137] op_sel_hi:[0,1,1] neg_lo:[0,0,1] neg_hi:[0,0,1]
	v_mov_b32_e32 v141, v129
	v_mov_b64_e32 v[128:129], v[140:141]
.LBB0_703:
	v_add_co_u32_e32 v136, vcc, 0x3000, v152
	s_nop 1
	v_addc_co_u32_e32 v137, vcc, 0, v153, vcc
	s_waitcnt vmcnt(12)
	v_mov_b32_e32 v137, v210
	s_and_b64 vcc, exec, s[40:41]
	s_waitcnt vmcnt(0)
	v_lshlrev_b32_e32 v136, 16, v137
	v_and_b32_e32 v137, 0xffff0000, v137
	s_cbranch_vccnz .LBB0_705
	v_or_b32_e32 v138, 0xc00, v170
	v_cvt_f32_u32_e32 v138, v138
	v_mul_f32_e32 v139, 0x38000000, v138
	v_sin_f32_e32 v138, v139
	v_cos_f32_e32 v140, v139
	v_pk_mul_f32 v[138:139], v[138:139], v[136:137] op_sel:[0,1] op_sel_hi:[0,0]
	v_pk_fma_f32 v[142:143], v[140:141], v[136:137], v[138:139]
	v_pk_fma_f32 v[136:137], v[140:141], v[136:137], v[138:139] op_sel_hi:[0,1,1] neg_lo:[0,0,1] neg_hi:[0,0,1]
	v_mov_b32_e32 v143, v137
	v_mov_b64_e32 v[136:137], v[142:143]
.LBB0_705:
	v_add_co_u32_e32 v138, vcc, 0x4000, v152
	s_nop 1
	v_addc_co_u32_e32 v139, vcc, 0, v153, vcc
	s_waitcnt vmcnt(11)
	v_mov_b32_e32 v139, v211
	s_and_b64 vcc, exec, s[40:41]
	s_waitcnt vmcnt(0)
	v_lshlrev_b32_e32 v138, 16, v139
	v_and_b32_e32 v139, 0xffff0000, v139
	s_cbranch_vccnz .LBB0_707
	v_or_b32_e32 v140, 0x1000, v170
	v_cvt_f32_u32_e32 v140, v140
	v_mul_f32_e32 v141, 0x38000000, v140
	v_sin_f32_e32 v140, v141
	v_cos_f32_e32 v142, v141
	v_pk_mul_f32 v[140:141], v[140:141], v[138:139] op_sel:[0,1] op_sel_hi:[0,0]
	v_pk_fma_f32 v[144:145], v[142:143], v[138:139], v[140:141]
	v_pk_fma_f32 v[138:139], v[142:143], v[138:139], v[140:141] op_sel_hi:[0,1,1] neg_lo:[0,0,1] neg_hi:[0,0,1]
	v_mov_b32_e32 v145, v139
	v_mov_b64_e32 v[138:139], v[144:145]
; __device__ __forceinline__ float2 cmul(float2 a, float2 b) { return make_float2(a.x * b.x - a.y * b.y, a.x * b.y + a.y * b.x); }
; __device__ __forceinline__ float2 twid(float turns) { return make_float2(__builtin_amdgcn_cosf(turns), -__builtin_amdgcn_sinf(turns)); }
; __device__ __forceinline__ float2 unpk2(unsigned w) { return make_float2(bflo(w), bfhi(w)); }
;   __device__ __forceinline__ float2 operator()(int i) const { const float2 wv = unpk2(Wd[i]); return half ? cmul(wv, twid((float)(i & (L - 1)) * invTurn)) : wv; }
.LBB0_707:
	v_add_co_u32_e32 v140, vcc, 0x5000, v152
	s_nop 1
	v_addc_co_u32_e32 v141, vcc, 0, v153, vcc
	s_waitcnt vmcnt(10)
	v_mov_b32_e32 v141, v212
	s_and_b64 vcc, exec, s[40:41]
	s_waitcnt vmcnt(0)
	v_lshlrev_b32_e32 v140, 16, v141
	v_and_b32_e32 v141, 0xffff0000, v141
	s_cbranch_vccnz .LBB0_709
	v_or_b32_e32 v142, 0x1400, v170
	v_cvt_f32_u32_e32 v142, v142
	v_mul_f32_e32 v143, 0x38000000, v142
	v_sin_f32_e32 v142, v143
	v_cos_f32_e32 v144, v143
	v_pk_mul_f32 v[142:143], v[142:143], v[140:141] op_sel:[0,1] op_sel_hi:[0,0]
	v_pk_fma_f32 v[146:147], v[144:145], v[140:141], v[142:143]
	v_pk_fma_f32 v[140:141], v[144:145], v[140:141], v[142:143] op_sel_hi:[0,1,1] neg_lo:[0,0,1] neg_hi:[0,0,1]
	v_mov_b32_e32 v147, v141
	v_mov_b64_e32 v[140:141], v[146:147]
.LBB0_709:
	v_add_co_u32_e32 v142, vcc, 0x6000, v152
	s_nop 1
	v_addc_co_u32_e32 v143, vcc, 0, v153, vcc
	s_waitcnt vmcnt(9)
	v_mov_b32_e32 v143, v213
	s_and_b64 vcc, exec, s[40:41]
	s_waitcnt vmcnt(0)
	v_lshlrev_b32_e32 v142, 16, v143
	v_and_b32_e32 v143, 0xffff0000, v143
	s_cbranch_vccnz .LBB0_711
	v_or_b32_e32 v144, 0x1800, v170
	v_cvt_f32_u32_e32 v144, v144
	v_mul_f32_e32 v145, 0x38000000, v144
	v_sin_f32_e32 v144, v145
	v_cos_f32_e32 v146, v145
	v_pk_mul_f32 v[144:145], v[144:145], v[142:143] op_sel:[0,1] op_sel_hi:[0,0]
	v_pk_fma_f32 v[148:149], v[146:147], v[142:143], v[144:145]
	v_pk_fma_f32 v[142:143], v[146:147], v[142:143], v[144:145] op_sel_hi:[0,1,1] neg_lo:[0,0,1] neg_hi:[0,0,1]
	v_mov_b32_e32 v149, v143
	v_mov_b64_e32 v[142:143], v[148:149]
.LBB0_711:
	v_add_co_u32_e32 v144, vcc, 0x7000, v152
	s_nop 1
	v_addc_co_u32_e32 v145, vcc, 0, v153, vcc
	s_waitcnt vmcnt(8)
	v_mov_b32_e32 v145, v214
	s_and_b64 vcc, exec, s[40:41]
	s_waitcnt vmcnt(0)
	v_lshlrev_b32_e32 v144, 16, v145
	v_and_b32_e32 v145, 0xffff0000, v145
	s_cbranch_vccnz .LBB0_713
	v_or_b32_e32 v146, 0x1c00, v170
	v_cvt_f32_u32_e32 v146, v146
	v_mul_f32_e32 v147, 0x38000000, v146
	v_sin_f32_e32 v146, v147
	v_cos_f32_e32 v148, v147
	v_pk_mul_f32 v[146:147], v[146:147], v[144:145] op_sel:[0,1] op_sel_hi:[0,0]
	v_pk_fma_f32 v[150:151], v[148:149], v[144:145], v[146:147]
	v_pk_fma_f32 v[144:145], v[148:149], v[144:145], v[146:147] op_sel_hi:[0,1,1] neg_lo:[0,0,1] neg_hi:[0,0,1]
	v_mov_b32_e32 v151, v145
	v_mov_b64_e32 v[144:145], v[150:151]
.LBB0_713:
	v_add_co_u32_e32 v146, vcc, 0x8000, v152
	s_nop 1
	v_addc_co_u32_e32 v147, vcc, 0, v153, vcc
	s_waitcnt vmcnt(7)
	v_mov_b32_e32 v147, v215
	s_and_b64 vcc, exec, s[40:41]
	s_waitcnt vmcnt(0)
	v_lshlrev_b32_e32 v146, 16, v147
	v_and_b32_e32 v147, 0xffff0000, v147
	s_cbranch_vccnz .LBB0_715
	v_or_b32_e32 v148, 0x2000, v170
	v_cvt_f32_u32_e32 v148, v148
	v_mul_f32_e32 v149, 0x38000000, v148
	v_sin_f32_e32 v148, v149
	v_cos_f32_e32 v150, v149
	v_pk_mul_f32 v[148:149], v[148:149], v[146:147] op_sel:[0,1] op_sel_hi:[0,0]
	v_pk_fma_f32 v[154:155], v[150:151], v[146:147], v[148:149]
	v_pk_fma_f32 v[146:147], v[150:151], v[146:147], v[148:149] op_sel_hi:[0,1,1] neg_lo:[0,0,1] neg_hi:[0,0,1]
	v_mov_b32_e32 v155, v147
	v_mov_b64_e32 v[146:147], v[154:155]
.LBB0_715:
	v_add_co_u32_e32 v148, vcc, 0x9000, v152
	s_nop 1
	v_addc_co_u32_e32 v149, vcc, 0, v153, vcc
	s_waitcnt vmcnt(6)
	v_mov_b32_e32 v149, v216
	s_and_b64 vcc, exec, s[40:41]
	s_waitcnt vmcnt(0)
	v_lshlrev_b32_e32 v148, 16, v149
	v_and_b32_e32 v149, 0xffff0000, v149
	s_cbranch_vccnz .LBB0_717
	v_or_b32_e32 v150, 0x2400, v170
	v_cvt_f32_u32_e32 v150, v150
	v_mul_f32_e32 v151, 0x38000000, v150
	v_sin_f32_e32 v150, v151
	v_cos_f32_e32 v154, v151
	v_pk_mul_f32 v[150:151], v[150:151], v[148:149] op_sel:[0,1] op_sel_hi:[0,0]
	v_pk_fma_f32 v[156:157], v[154:155], v[148:149], v[150:151]
	v_pk_fma_f32 v[148:149], v[154:155], v[148:149], v[150:151] op_sel_hi:[0,1,1] neg_lo:[0,0,1] neg_hi:[0,0,1]
	v_mov_b32_e32 v157, v149
	v_mov_b64_e32 v[148:149], v[156:157]
; __device__ __forceinline__ float2 cmul(float2 a, float2 b) { return make_float2(a.x * b.x - a.y * b.y, a.x * b.y + a.y * b.x); }
; __device__ __forceinline__ float2 twid(float turns) { return make_float2(__builtin_amdgcn_cosf(turns), -__builtin_amdgcn_sinf(turns)); }
; __device__ __forceinline__ float2 unpk2(unsigned w) { return make_float2(bflo(w), bfhi(w)); }
;   __device__ __forceinline__ float2 operator()(int i) const { const float2 wv = unpk2(Wd[i]); return half ? cmul(wv, twid((float)(i & (L - 1)) * invTurn)) : wv; }
.LBB0_717:
	v_add_co_u32_e32 v150, vcc, 0xa000, v152
	s_nop 1
	v_addc_co_u32_e32 v151, vcc, 0, v153, vcc
	s_waitcnt vmcnt(5)
	v_mov_b32_e32 v151, v217
	s_and_b64 vcc, exec, s[40:41]
	s_waitcnt vmcnt(0)
	v_lshlrev_b32_e32 v150, 16, v151
	v_and_b32_e32 v151, 0xffff0000, v151
	s_cbranch_vccnz .LBB0_719
	v_or_b32_e32 v154, 0x2800, v170
	v_cvt_f32_u32_e32 v154, v154
	v_mul_f32_e32 v155, 0x38000000, v154
	v_sin_f32_e32 v154, v155
	v_cos_f32_e32 v156, v155
	v_pk_mul_f32 v[154:155], v[154:155], v[150:151] op_sel:[0,1] op_sel_hi:[0,0]
	v_pk_fma_f32 v[158:159], v[156:157], v[150:151], v[154:155]
	v_pk_fma_f32 v[150:151], v[156:157], v[150:151], v[154:155] op_sel_hi:[0,1,1] neg_lo:[0,0,1] neg_hi:[0,0,1]
	v_mov_b32_e32 v159, v151
	v_mov_b64_e32 v[150:151], v[158:159]
.LBB0_719:
	v_add_co_u32_e32 v154, vcc, 0xb000, v152
	s_nop 1
	v_addc_co_u32_e32 v155, vcc, 0, v153, vcc
	s_waitcnt vmcnt(4)
	v_mov_b32_e32 v155, v218
	s_and_b64 vcc, exec, s[40:41]
	s_waitcnt vmcnt(0)
	v_lshlrev_b32_e32 v154, 16, v155
	v_and_b32_e32 v155, 0xffff0000, v155
	s_cbranch_vccnz .LBB0_721
	v_or_b32_e32 v156, 0x2c00, v170
	v_cvt_f32_u32_e32 v156, v156
	v_mul_f32_e32 v157, 0x38000000, v156
	v_sin_f32_e32 v156, v157
	v_cos_f32_e32 v158, v157
	v_pk_mul_f32 v[156:157], v[156:157], v[154:155] op_sel:[0,1] op_sel_hi:[0,0]
	v_pk_fma_f32 v[160:161], v[158:159], v[154:155], v[156:157]
	v_pk_fma_f32 v[154:155], v[158:159], v[154:155], v[156:157] op_sel_hi:[0,1,1] neg_lo:[0,0,1] neg_hi:[0,0,1]
	v_mov_b32_e32 v161, v155
	v_mov_b64_e32 v[154:155], v[160:161]
.LBB0_721:
	v_add_co_u32_e32 v156, vcc, 0xc000, v152
	s_nop 1
	v_addc_co_u32_e32 v157, vcc, 0, v153, vcc
	s_waitcnt vmcnt(3)
	v_mov_b32_e32 v157, v219
	s_and_b64 vcc, exec, s[40:41]
	s_waitcnt vmcnt(0)
	v_lshlrev_b32_e32 v156, 16, v157
	v_and_b32_e32 v157, 0xffff0000, v157
	s_cbranch_vccnz .LBB0_723
	v_or_b32_e32 v158, 0x3000, v170
	v_cvt_f32_u32_e32 v158, v158
	v_mul_f32_e32 v159, 0x38000000, v158
	v_sin_f32_e32 v158, v159
	v_cos_f32_e32 v160, v159
	v_pk_mul_f32 v[158:159], v[158:159], v[156:157] op_sel:[0,1] op_sel_hi:[0,0]
	v_pk_fma_f32 v[172:173], v[160:161], v[156:157], v[158:159]
	v_pk_fma_f32 v[156:157], v[160:161], v[156:157], v[158:159] op_sel_hi:[0,1,1] neg_lo:[0,0,1] neg_hi:[0,0,1]
	v_mov_b32_e32 v173, v157
	v_mov_b64_e32 v[156:157], v[172:173]
.LBB0_723:
	v_add_co_u32_e32 v158, vcc, 0xd000, v152
	s_nop 1
	v_addc_co_u32_e32 v159, vcc, 0, v153, vcc
	s_waitcnt vmcnt(2)
	v_mov_b32_e32 v159, v220
	s_and_b64 vcc, exec, s[40:41]
	s_waitcnt vmcnt(0)
	v_lshlrev_b32_e32 v158, 16, v159
	v_and_b32_e32 v159, 0xffff0000, v159
	s_cbranch_vccnz .LBB0_725
	v_or_b32_e32 v160, 0x3400, v170
	v_cvt_f32_u32_e32 v160, v160
	v_mul_f32_e32 v161, 0x38000000, v160
	v_sin_f32_e32 v160, v161
	v_cos_f32_e32 v172, v161
	v_pk_mul_f32 v[160:161], v[160:161], v[158:159] op_sel:[0,1] op_sel_hi:[0,0]
	v_pk_fma_f32 v[174:175], v[172:173], v[158:159], v[160:161]
	v_pk_fma_f32 v[158:159], v[172:173], v[158:159], v[160:161] op_sel_hi:[0,1,1] neg_lo:[0,0,1] neg_hi:[0,0,1]
	v_mov_b32_e32 v175, v159
	v_mov_b64_e32 v[158:159], v[174:175]
.LBB0_725:
	v_add_co_u32_e32 v160, vcc, 0xe000, v152
	s_nop 1
	v_addc_co_u32_e32 v161, vcc, 0, v153, vcc
	s_waitcnt vmcnt(1)
	v_mov_b32_e32 v161, v221
	s_and_b64 vcc, exec, s[40:41]
	s_waitcnt vmcnt(0)
	v_lshlrev_b32_e32 v160, 16, v161
	v_and_b32_e32 v161, 0xffff0000, v161
	s_cbranch_vccnz .LBB0_727
	v_or_b32_e32 v171, 0x3800, v170
	v_cvt_f32_u32_e32 v171, v171
	v_mul_f32_e32 v171, 0x38000000, v171
	v_sin_f32_e32 v172, v171
	v_cos_f32_e32 v174, v171
	v_pk_mul_f32 v[172:173], v[172:173], v[160:161] op_sel:[0,1] op_sel_hi:[0,0]
	v_pk_fma_f32 v[176:177], v[174:175], v[160:161], v[172:173]
	v_pk_fma_f32 v[160:161], v[174:175], v[160:161], v[172:173] op_sel_hi:[0,1,1] neg_lo:[0,0,1] neg_hi:[0,0,1]
	v_mov_b32_e32 v177, v161
	v_mov_b64_e32 v[160:161], v[176:177]
.LBB0_727:
	v_add_co_u32_e32 v152, vcc, 0xf000, v152
	s_nop 1
	v_addc_co_u32_e32 v153, vcc, 0, v153, vcc
	s_waitcnt vmcnt(0)
	v_mov_b32_e32 v153, v222
	s_and_b64 vcc, exec, s[40:41]
	s_waitcnt vmcnt(0)
	v_lshlrev_b32_e32 v152, 16, v153
	v_and_b32_e32 v153, 0xffff0000, v153
	s_cbranch_vccnz .LBB0_693
	v_or_b32_e32 v170, 0x3c00, v170
	v_cvt_f32_u32_e32 v170, v170
	v_mul_f32_e32 v171, 0x38000000, v170
	v_sin_f32_e32 v170, v171
	v_cos_f32_e32 v172, v171
	v_pk_mul_f32 v[170:171], v[170:171], v[152:153] op_sel:[0,1] op_sel_hi:[0,0]
	v_pk_fma_f32 v[174:175], v[172:173], v[152:153], v[170:171]
	v_pk_fma_f32 v[152:153], v[172:173], v[152:153], v[170:171] op_sel_hi:[0,1,1] neg_lo:[0,0,1] neg_hi:[0,0,1]
	v_mov_b32_e32 v152, v174
	s_branch .LBB0_693

; __device__ __forceinline__ float bf2f(bf16_t b) { return __uint_as_float(((unsigned)b) << 16); }
; __device__ __forceinline__ float2 twid(float turns) { return make_float2(__builtin_amdgcn_cosf(turns), -__builtin_amdgcn_sinf(turns)); }
;   __device__ __forceinline__ float2 operator()(int i) const { const float2 wv = unpk2(Wd[i]); return half ? cmul(wv, twid((float)(i & (L - 1)) * invTurn)) : wv; }
; template <int LOGN, int R, int DLOG, bool INV, int MODE, class F>
; __device__ __forceinline__ void fft_pass(float2* X, const F& f) {
;     ...
;   auto fetch = [&](int g, c32 (&dst)[RAD]) {
;     const int base = gbase(g);
; #pragma unroll
;     for (int j = 0; j < RAD; ++j) { if constexpr (MODE == 1) { const float2 sv = f(base + (j << DLOG)); dst[j] = (c32){sv.x, sv.y}; } }
;   };
;   c32 nxt[RAD];
;   if constexpr (MODE == 1) fetch(tid0, nxt);
;   __device__ __forceinline__ float2 operator()(int i) const {
;     const int ch = i >> lshift, t = i & (L - 1);
;     const float f = bf2f(hf[ch * chstride + t]), bw = bf2f(hb[ch * chstride + (t > 0 ? L - t : 0)]);
;     const float bwm = t > 0 ? bw : 0.f;
;     if (half == 0) return make_float2(f + bwm, 0.f);
;     const float2 tw = twid((float)t * invTurn); const float d = f - bwm; return make_float2(d * tw.x, d * tw.y);
;   }
.LBB0_950:
	v_mov_b32_e32 v34, v196
	s_xor_b64 s[52:53], s[14:15], -1
	v_bfe_i32 v0, v34, 10, 19
	v_and_b32_e32 v32, 0x3ff, v34
	v_mul_i32_i24_e32 v14, s80, v0
	v_or_b32_e32 v0, v14, v32
	v_ashrrev_i32_e32 v1, 31, v0
	v_lshl_add_u64 v[0:1], v[0:1], 1, s[36:37]
	v_lshlrev_b32_e32 v207, 1, v14
	v_lshl_add_u32 v208, v32, 1, v207
	v_sub_u32_e32 v209, v207, v208
	v_add_u32_e32 v209, v209, v207
	v_add_u32_e32 v209, 0x4000, v209
	v_cmp_eq_u32_e64 s[98:99], 0, v32
	v_mov_b32_e32 v210, v208
	v_add_u32_e32 v212, 0x800, v208
	v_add_u32_e32 v214, 0x1000, v208
	v_add_u32_e32 v216, 0x1800, v208
	v_add_u32_e32 v218, 0x2000, v208
	v_add_u32_e32 v220, 0x2800, v208
	v_add_u32_e32 v222, 0x3000, v208
	v_add_u32_e32 v224, 0x3800, v208
	v_subrev_u32_e32 v213, 0x800, v209
	v_subrev_u32_e32 v215, 0x1000, v209
	v_subrev_u32_e32 v217, 0x1800, v209
	v_subrev_u32_e32 v219, 0x2000, v209
	v_subrev_u32_e32 v221, 0x2800, v209
	v_subrev_u32_e32 v223, 0x3000, v209
	v_subrev_u32_e32 v225, 0x3800, v209
	v_cndmask_b32_e64 v211, v209, v207, s[98:99]
	global_load_ushort v210, v210, s[36:37]
	global_load_ushort v211, v211, s[92:93]
	global_load_ushort v212, v212, s[36:37]
	global_load_ushort v213, v213, s[92:93]
	global_load_ushort v214, v214, s[36:37]
	global_load_ushort v215, v215, s[92:93]
	global_load_ushort v216, v216, s[36:37]
	global_load_ushort v217, v217, s[92:93]
	global_load_ushort v218, v218, s[36:37]
	global_load_ushort v219, v219, s[92:93]
	global_load_ushort v220, v220, s[36:37]
	global_load_ushort v221, v221, s[92:93]
	global_load_ushort v222, v222, s[36:37]
	global_load_ushort v223, v223, s[92:93]
	global_load_ushort v224, v224, s[36:37]
	global_load_ushort v225, v225, s[92:93]
	s_waitcnt vmcnt(15)
	v_mov_b32_e32 v0, v210
	v_cmp_eq_u32_e32 vcc, 0, v32
	s_mov_b64 s[0:1], -1
	s_waitcnt vmcnt(0)
	v_lshlrev_b32_e32 v2, 16, v0
	v_sub_u32_e32 v0, 0x2000, v32
	v_cndmask_b32_e64 v0, v0, 0, vcc
	v_or_b32_e32 v0, v0, v14
	v_ashrrev_i32_e32 v1, 31, v0
	v_lshl_add_u64 v[0:1], v[0:1], 1, s[92:93]
	s_waitcnt vmcnt(14)
	v_mov_b32_e32 v0, v211
	s_waitcnt vmcnt(0)
	v_lshlrev_b32_e32 v0, 16, v0
	v_cndmask_b32_e64 v3, v0, 0, vcc
	s_and_b64 vcc, exec, s[52:53]
	s_cbranch_vccz .LBB0_952
	v_cvt_f32_u32_e32 v0, v32
	v_sub_f32_e32 v4, v2, v3
	s_mov_b64 s[0:1], 0
	v_mul_f32_e32 v1, 0x38800000, v0
	v_cos_f32_e32 v0, v1
	v_sin_f32_e64 v1, -v1
	s_nop 0
	v_pk_mul_f32 v[0:1], v[0:1], v[4:5] op_sel_hi:[1,0]

; __device__ __forceinline__ float bf2f(bf16_t b) { return __uint_as_float(((unsigned)b) << 16); }
; __device__ __forceinline__ float2 twid(float turns) { return make_float2(__builtin_amdgcn_cosf(turns), -__builtin_amdgcn_sinf(turns)); }
;   __device__ __forceinline__ float2 operator()(int i) const { const float2 wv = unpk2(Wd[i]); return half ? cmul(wv, twid((float)(i & (L - 1)) * invTurn)) : wv; }
;   __device__ __forceinline__ float2 operator()(int i) const {
;     const int ch = i >> lshift, t = i & (L - 1);
;     const float f = bf2f(hf[ch * chstride + t]), bw = bf2f(hb[ch * chstride + (t > 0 ? L - t : 0)]);
;     const float bwm = t > 0 ? bw : 0.f;
;     if (half == 0) return make_float2(f + bwm, 0.f);
;     const float2 tw = twid((float)t * invTurn); const float d = f - bwm; return make_float2(d * tw.x, d * tw.y);
;   }
.LBB0_954:
	v_ashrrev_i32_e32 v15, 31, v14
	v_lshl_add_u64 v[4:5], v[14:15], 0, v[32:33]
	v_lshl_add_u64 v[4:5], v[4:5], 1, s[36:37]
	s_waitcnt vmcnt(13)
	v_mov_b32_e32 v3, v212
	v_or_b32_e32 v2, 0x400, v32
	s_mov_b64 s[0:1], -1
	s_andn2_b64 vcc, exec, s[52:53]
	s_waitcnt vmcnt(0)
	v_lshlrev_b32_e32 v4, 16, v3
	v_sub_u32_e32 v3, v14, v2
	v_add_u32_e32 v6, 0x2000, v3
	v_ashrrev_i32_e32 v7, 31, v6
	v_lshl_add_u64 v[6:7], v[6:7], 1, s[92:93]
	s_waitcnt vmcnt(12)
	v_mov_b32_e32 v3, v213
	s_waitcnt vmcnt(0)
	v_lshlrev_b32_e32 v5, 16, v3
	v_cndmask_b32_e64 v3, 0, 1, s[52:53]
	v_cmp_ne_u32_e64 s[40:41], 1, v3
	s_cbranch_vccnz .LBB0_956
	v_cvt_f32_u32_e32 v2, v2
	v_sub_f32_e32 v6, v4, v5
	s_mov_b64 s[0:1], 0
	v_mul_f32_e32 v3, 0x38800000, v2
	v_cos_f32_e32 v2, v3
	v_sin_f32_e64 v3, -v3
	s_nop 0
	v_pk_mul_f32 v[2:3], v[2:3], v[6:7] op_sel_hi:[1,0]

; __device__ __forceinline__ float bf2f(bf16_t b) { return __uint_as_float(((unsigned)b) << 16); }
; __device__ __forceinline__ float2 twid(float turns) { return make_float2(__builtin_amdgcn_cosf(turns), -__builtin_amdgcn_sinf(turns)); }
;   __device__ __forceinline__ float2 operator()(int i) const { const float2 wv = unpk2(Wd[i]); return half ? cmul(wv, twid((float)(i & (L - 1)) * invTurn)) : wv; }
;   __device__ __forceinline__ float2 operator()(int i) const {
;     const int ch = i >> lshift, t = i & (L - 1);
;     const float f = bf2f(hf[ch * chstride + t]), bw = bf2f(hb[ch * chstride + (t > 0 ? L - t : 0)]);
;     const float bwm = t > 0 ? bw : 0.f;
;     if (half == 0) return make_float2(f + bwm, 0.f);
;     const float2 tw = twid((float)t * invTurn); const float d = f - bwm; return make_float2(d * tw.x, d * tw.y);
;   }
.LBB0_958:
	v_or_b32_e32 v4, 0x800, v32
	v_or_b32_e32 v6, v14, v4
	v_ashrrev_i32_e32 v7, 31, v6
	v_lshl_add_u64 v[6:7], v[6:7], 1, s[36:37]
	s_waitcnt vmcnt(11)
	v_mov_b32_e32 v5, v214
	s_mov_b64 s[0:1], -1
	s_and_b64 vcc, exec, s[40:41]
	s_waitcnt vmcnt(0)
	v_lshlrev_b32_e32 v6, 16, v5
	v_sub_u32_e32 v5, v14, v4
	v_add_u32_e32 v8, 0x2000, v5
	v_ashrrev_i32_e32 v9, 31, v8
	v_lshl_add_u64 v[8:9], v[8:9], 1, s[92:93]
	s_waitcnt vmcnt(10)
	v_mov_b32_e32 v5, v215
	s_waitcnt vmcnt(0)
	v_lshlrev_b32_e32 v7, 16, v5
	s_cbranch_vccnz .LBB0_960
	v_cvt_f32_u32_e32 v4, v4
	v_sub_f32_e32 v8, v6, v7
	s_mov_b64 s[0:1], 0
	v_mul_f32_e32 v5, 0x38800000, v4
	v_cos_f32_e32 v4, v5
	v_sin_f32_e64 v5, -v5
	s_nop 0
	v_pk_mul_f32 v[4:5], v[4:5], v[8:9] op_sel_hi:[1,0]

; __device__ __forceinline__ float bf2f(bf16_t b) { return __uint_as_float(((unsigned)b) << 16); }
; __device__ __forceinline__ float2 twid(float turns) { return make_float2(__builtin_amdgcn_cosf(turns), -__builtin_amdgcn_sinf(turns)); }
;   __device__ __forceinline__ float2 operator()(int i) const { const float2 wv = unpk2(Wd[i]); return half ? cmul(wv, twid((float)(i & (L - 1)) * invTurn)) : wv; }
;   __device__ __forceinline__ float2 operator()(int i) const {
;     const int ch = i >> lshift, t = i & (L - 1);
;     const float f = bf2f(hf[ch * chstride + t]), bw = bf2f(hb[ch * chstride + (t > 0 ? L - t : 0)]);
;     const float bwm = t > 0 ? bw : 0.f;
;     if (half == 0) return make_float2(f + bwm, 0.f);
;     const float2 tw = twid((float)t * invTurn); const float d = f - bwm; return make_float2(d * tw.x, d * tw.y);
;   }
.LBB0_962:
	v_or_b32_e32 v6, 0xc00, v32
	v_or_b32_e32 v8, v14, v6
	v_ashrrev_i32_e32 v9, 31, v8
	v_lshl_add_u64 v[8:9], v[8:9], 1, s[36:37]
	s_waitcnt vmcnt(9)
	v_mov_b32_e32 v7, v216
	s_mov_b64 s[0:1], -1
	s_and_b64 vcc, exec, s[40:41]
	s_waitcnt vmcnt(0)
	v_lshlrev_b32_e32 v8, 16, v7
	v_sub_u32_e32 v7, v14, v6
	v_add_u32_e32 v10, 0x2000, v7
	v_ashrrev_i32_e32 v11, 31, v10
	v_lshl_add_u64 v[10:11], v[10:11], 1, s[92:93]
	s_waitcnt vmcnt(8)
	v_mov_b32_e32 v7, v217
	s_waitcnt vmcnt(0)
	v_lshlrev_b32_e32 v9, 16, v7
	s_cbranch_vccnz .LBB0_964
	v_cvt_f32_u32_e32 v6, v6
	v_sub_f32_e32 v10, v8, v9
	s_mov_b64 s[0:1], 0
	v_mul_f32_e32 v7, 0x38800000, v6
	v_cos_f32_e32 v6, v7
	v_sin_f32_e64 v7, -v7
	s_nop 0
	v_pk_mul_f32 v[6:7], v[6:7], v[10:11] op_sel_hi:[1,0]

; __device__ __forceinline__ float bf2f(bf16_t b) { return __uint_as_float(((unsigned)b) << 16); }
; __device__ __forceinline__ float2 twid(float turns) { return make_float2(__builtin_amdgcn_cosf(turns), -__builtin_amdgcn_sinf(turns)); }
;   __device__ __forceinline__ float2 operator()(int i) const { const float2 wv = unpk2(Wd[i]); return half ? cmul(wv, twid((float)(i & (L - 1)) * invTurn)) : wv; }
;   __device__ __forceinline__ float2 operator()(int i) const {
;     const int ch = i >> lshift, t = i & (L - 1);
;     const float f = bf2f(hf[ch * chstride + t]), bw = bf2f(hb[ch * chstride + (t > 0 ? L - t : 0)]);
;     const float bwm = t > 0 ? bw : 0.f;
;     if (half == 0) return make_float2(f + bwm, 0.f);
;     const float2 tw = twid((float)t * invTurn); const float d = f - bwm; return make_float2(d * tw.x, d * tw.y);
;   }
.LBB0_966:
	v_or_b32_e32 v8, 0x1000, v32
	v_or_b32_e32 v10, v14, v8
	v_ashrrev_i32_e32 v11, 31, v10
	v_lshl_add_u64 v[10:11], v[10:11], 1, s[36:37]
	s_waitcnt vmcnt(7)
	v_mov_b32_e32 v9, v218
	s_mov_b64 s[0:1], -1
	s_and_b64 vcc, exec, s[40:41]
	s_waitcnt vmcnt(0)
	v_lshlrev_b32_e32 v10, 16, v9
	v_sub_u32_e32 v9, v14, v8
	v_add_u32_e32 v12, 0x2000, v9
	v_ashrrev_i32_e32 v13, 31, v12
	v_lshl_add_u64 v[12:13], v[12:13], 1, s[92:93]
	s_waitcnt vmcnt(6)
	v_mov_b32_e32 v9, v219
	s_waitcnt vmcnt(0)
	v_lshlrev_b32_e32 v11, 16, v9
	s_cbranch_vccnz .LBB0_968
	v_cvt_f32_u32_e32 v8, v8
	v_sub_f32_e32 v12, v10, v11
	s_mov_b64 s[0:1], 0
	v_mul_f32_e32 v9, 0x38800000, v8
	v_cos_f32_e32 v8, v9
	v_sin_f32_e64 v9, -v9
	s_nop 0
	v_pk_mul_f32 v[8:9], v[8:9], v[12:13] op_sel_hi:[1,0]

; __device__ __forceinline__ float bf2f(bf16_t b) { return __uint_as_float(((unsigned)b) << 16); }
; __device__ __forceinline__ float2 twid(float turns) { return make_float2(__builtin_amdgcn_cosf(turns), -__builtin_amdgcn_sinf(turns)); }
;   __device__ __forceinline__ float2 operator()(int i) const { const float2 wv = unpk2(Wd[i]); return half ? cmul(wv, twid((float)(i & (L - 1)) * invTurn)) : wv; }
;   __device__ __forceinline__ float2 operator()(int i) const {
;     const int ch = i >> lshift, t = i & (L - 1);
;     const float f = bf2f(hf[ch * chstride + t]), bw = bf2f(hb[ch * chstride + (t > 0 ? L - t : 0)]);
;     const float bwm = t > 0 ? bw : 0.f;
;     if (half == 0) return make_float2(f + bwm, 0.f);
;     const float2 tw = twid((float)t * invTurn); const float d = f - bwm; return make_float2(d * tw.x, d * tw.y);
;   }
.LBB0_970:
	v_or_b32_e32 v10, 0x1400, v32
	v_or_b32_e32 v12, v14, v10
	v_ashrrev_i32_e32 v13, 31, v12
	v_lshl_add_u64 v[12:13], v[12:13], 1, s[36:37]
	s_waitcnt vmcnt(5)
	v_mov_b32_e32 v11, v220
	s_mov_b64 s[0:1], -1
	s_and_b64 vcc, exec, s[40:41]
	s_waitcnt vmcnt(0)
	v_lshlrev_b32_e32 v12, 16, v11
	v_sub_u32_e32 v11, v14, v10
	v_add_u32_e32 v16, 0x2000, v11
	v_ashrrev_i32_e32 v17, 31, v16
	v_lshl_add_u64 v[16:17], v[16:17], 1, s[92:93]
	s_waitcnt vmcnt(4)
	v_mov_b32_e32 v11, v221
	s_waitcnt vmcnt(0)
	v_lshlrev_b32_e32 v13, 16, v11
	s_cbranch_vccnz .LBB0_972
	v_cvt_f32_u32_e32 v10, v10
	v_sub_f32_e32 v16, v12, v13
	s_mov_b64 s[0:1], 0
	v_mul_f32_e32 v11, 0x38800000, v10
	v_cos_f32_e32 v10, v11
	v_sin_f32_e64 v11, -v11
	s_nop 0
	v_pk_mul_f32 v[10:11], v[10:11], v[16:17] op_sel_hi:[1,0]

; __device__ __forceinline__ float bf2f(bf16_t b) { return __uint_as_float(((unsigned)b) << 16); }
; __device__ __forceinline__ float2 twid(float turns) { return make_float2(__builtin_amdgcn_cosf(turns), -__builtin_amdgcn_sinf(turns)); }
;   __device__ __forceinline__ float2 operator()(int i) const { const float2 wv = unpk2(Wd[i]); return half ? cmul(wv, twid((float)(i & (L - 1)) * invTurn)) : wv; }
;   __device__ __forceinline__ float2 operator()(int i) const {
;     const int ch = i >> lshift, t = i & (L - 1);
;     const float f = bf2f(hf[ch * chstride + t]), bw = bf2f(hb[ch * chstride + (t > 0 ? L - t : 0)]);
;     const float bwm = t > 0 ? bw : 0.f;
;     if (half == 0) return make_float2(f + bwm, 0.f);
;     const float2 tw = twid((float)t * invTurn); const float d = f - bwm; return make_float2(d * tw.x, d * tw.y);
;   }
.LBB0_974:
	v_or_b32_e32 v12, 0x1800, v32
	v_or_b32_e32 v16, v14, v12
	v_ashrrev_i32_e32 v17, 31, v16
	v_lshl_add_u64 v[16:17], v[16:17], 1, s[36:37]
	s_waitcnt vmcnt(3)
	v_mov_b32_e32 v13, v222
	s_mov_b64 s[0:1], -1
	s_and_b64 vcc, exec, s[40:41]
	s_waitcnt vmcnt(0)
	v_lshlrev_b32_e32 v15, 16, v13
	v_sub_u32_e32 v13, v14, v12
	v_add_u32_e32 v16, 0x2000, v13
	v_ashrrev_i32_e32 v17, 31, v16
	v_lshl_add_u64 v[16:17], v[16:17], 1, s[92:93]
	s_waitcnt vmcnt(2)
	v_mov_b32_e32 v13, v223
	s_waitcnt vmcnt(0)
	v_lshlrev_b32_e32 v16, 16, v13
	s_cbranch_vccnz .LBB0_976
	v_cvt_f32_u32_e32 v12, v12
	v_sub_f32_e32 v18, v15, v16
	s_mov_b64 s[0:1], 0
	v_mul_f32_e32 v13, 0x38800000, v12
	v_cos_f32_e32 v12, v13
	v_sin_f32_e64 v13, -v13
	s_nop 0
	v_pk_mul_f32 v[12:13], v[12:13], v[18:19] op_sel_hi:[1,0]

; __device__ __forceinline__ float bf2f(bf16_t b) { return __uint_as_float(((unsigned)b) << 16); }
; __device__ __forceinline__ float2 twid(float turns) { return make_float2(__builtin_amdgcn_cosf(turns), -__builtin_amdgcn_sinf(turns)); }
;   __device__ __forceinline__ float2 operator()(int i) const { const float2 wv = unpk2(Wd[i]); return half ? cmul(wv, twid((float)(i & (L - 1)) * invTurn)) : wv; }
;   __device__ __forceinline__ float2 operator()(int i) const {
;     const int ch = i >> lshift, t = i & (L - 1);
;     const float f = bf2f(hf[ch * chstride + t]), bw = bf2f(hb[ch * chstride + (t > 0 ? L - t : 0)]);
;     const float bwm = t > 0 ? bw : 0.f;
;     if (half == 0) return make_float2(f + bwm, 0.f);
;     const float2 tw = twid((float)t * invTurn); const float d = f - bwm; return make_float2(d * tw.x, d * tw.y);
;   }
.LBB0_978:
	v_or_b32_e32 v18, 0x1c00, v32
	v_or_b32_e32 v16, v14, v18
	v_ashrrev_i32_e32 v17, 31, v16
	v_lshl_add_u64 v[16:17], v[16:17], 1, s[36:37]
	s_waitcnt vmcnt(1)
	v_mov_b32_e32 v15, v224
	v_sub_u32_e32 v14, v14, v18
	v_add_u32_e32 v14, 0x2000, v14
	s_mov_b64 s[0:1], -1
	s_and_b64 vcc, exec, s[40:41]
	s_waitcnt vmcnt(0)
	v_lshlrev_b32_e32 v16, 16, v15
	v_ashrrev_i32_e32 v15, 31, v14
	v_lshl_add_u64 v[14:15], v[14:15], 1, s[92:93]
	s_waitcnt vmcnt(0)
	v_mov_b32_e32 v14, v225
	s_waitcnt vmcnt(0)
	v_lshlrev_b32_e32 v17, 16, v14
	s_cbranch_vccnz .LBB0_981
	v_cvt_f32_u32_e32 v14, v18
	v_sub_f32_e32 v18, v16, v17
	v_mul_f32_e32 v15, 0x38800000, v14
	v_cos_f32_e32 v14, v15
	v_sin_f32_e64 v15, -v15
	s_nop 0
	v_pk_mul_f32 v[14:15], v[14:15], v[18:19] op_sel_hi:[1,0]
	s_cbranch_execz .LBB0_982

; __device__ __forceinline__ float bf2f(bf16_t b) { return __uint_as_float(((unsigned)b) << 16); }
; __device__ __forceinline__ float2 twid(float turns) { return make_float2(__builtin_amdgcn_cosf(turns), -__builtin_amdgcn_sinf(turns)); }
;   __device__ __forceinline__ float2 operator()(int i) const { const float2 wv = unpk2(Wd[i]); return half ? cmul(wv, twid((float)(i & (L - 1)) * invTurn)) : wv; }
; template <int LOGN, int R, int DLOG, bool INV, int MODE, class F>
; __device__ __forceinline__ void fft_pass(float2* X, const F& f) {
;     ...
;   for (int g = tid0; g < NGR; g += 512) {
;     const int lo = g & (dmin - 1), base = gbase(g), pb = phys(base);
;     c32 v[RAD];
;     if constexpr (MODE == 1) {
; #pragma unroll
;       for (int j = 0; j < RAD; ++j) v[j] = nxt[j];
;       if (g + 512 < NGR) fetch(g + 512, nxt);
;   __device__ __forceinline__ float2 operator()(int i) const {
;     const int ch = i >> lshift, t = i & (L - 1);
;     const float f = bf2f(hf[ch * chstride + t]), bw = bf2f(hb[ch * chstride + (t > 0 ? L - t : 0)]);
;     const float bwm = t > 0 ? bw : 0.f;
;     if (half == 0) return make_float2(f + bwm, 0.f);
;     const float2 tw = twid((float)t * invTurn); const float d = f - bwm; return make_float2(d * tw.x, d * tw.y);
;   }
.LBB0_985:
	v_cmp_lt_i32_e64 s[0:1], s74, v34
	v_add_u32_e32 v35, 0x1000, v37
	s_and_saveexec_b64 s[20:21], s[0:1]
	s_xor_b64 s[20:21], exec, s[20:21]
	v_add_u32_e32 v35, 0x1000, v37
	s_or_saveexec_b64 s[20:21], s[20:21]
	v_add_u32_e32 v36, 0x200, v34
	v_mov_b32_e32 v23, v15
	v_mov_b32_e32 v22, v14
	v_mov_b32_e32 v31, v13
	v_mov_b32_e32 v30, v12
	v_mov_b32_e32 v29, v11
	v_mov_b32_e32 v28, v10
	v_mov_b32_e32 v27, v9
	v_mov_b32_e32 v26, v8
	v_mov_b32_e32 v25, v7
	v_mov_b32_e32 v24, v6
	v_mov_b32_e32 v21, v5
	v_mov_b32_e32 v20, v4
	v_mov_b32_e32 v19, v3
	v_mov_b32_e32 v18, v2
	v_mov_b32_e32 v17, v1
	v_mov_b32_e32 v16, v0
	s_xor_b64 exec, exec, s[20:21]
	s_cbranch_execz .LBB0_984
	v_ashrrev_i32_e32 v16, 13, v35
	v_and_b32_e32 v32, 0x3ff, v36
	v_mul_i32_i24_e32 v22, s80, v16
	v_or_b32_e32 v16, v22, v32
	v_ashrrev_i32_e32 v17, 31, v16
	v_lshl_add_u64 v[16:17], v[16:17], 1, s[36:37]
	v_lshlrev_b32_e32 v207, 1, v22
	v_lshl_add_u32 v208, v32, 1, v207
	v_sub_u32_e32 v209, v207, v208
	v_add_u32_e32 v209, v209, v207
	v_add_u32_e32 v209, 0x4000, v209
	v_cmp_eq_u32_e64 s[98:99], 0, v32
	v_mov_b32_e32 v210, v208
	v_add_u32_e32 v212, 0x800, v208
	v_add_u32_e32 v214, 0x1000, v208
	v_add_u32_e32 v216, 0x1800, v208
	v_add_u32_e32 v218, 0x2000, v208
	v_add_u32_e32 v220, 0x2800, v208
	v_add_u32_e32 v222, 0x3000, v208
	v_add_u32_e32 v224, 0x3800, v208
	v_subrev_u32_e32 v213, 0x800, v209
	v_subrev_u32_e32 v215, 0x1000, v209
	v_subrev_u32_e32 v217, 0x1800, v209
	v_subrev_u32_e32 v219, 0x2000, v209
	v_subrev_u32_e32 v221, 0x2800, v209
	v_subrev_u32_e32 v223, 0x3000, v209
	v_subrev_u32_e32 v225, 0x3800, v209
	v_cndmask_b32_e64 v211, v209, v207, s[98:99]
	global_load_ushort v210, v210, s[36:37]
	global_load_ushort v211, v211, s[92:93]
	global_load_ushort v212, v212, s[36:37]
	global_load_ushort v213, v213, s[92:93]
	global_load_ushort v214, v214, s[36:37]
	global_load_ushort v215, v215, s[92:93]
	global_load_ushort v216, v216, s[36:37]
	global_load_ushort v217, v217, s[92:93]
	global_load_ushort v218, v218, s[36:37]
	global_load_ushort v219, v219, s[92:93]
	global_load_ushort v220, v220, s[36:37]
	global_load_ushort v221, v221, s[92:93]
	global_load_ushort v222, v222, s[36:37]
	global_load_ushort v223, v223, s[92:93]
	global_load_ushort v224, v224, s[36:37]
	global_load_ushort v225, v225, s[92:93]
	s_waitcnt vmcnt(15)
	v_mov_b32_e32 v16, v210
	v_cmp_eq_u32_e32 vcc, 0, v32
	s_mov_b64 s[58:59], -1
	s_waitcnt vmcnt(0)
	v_lshlrev_b32_e32 v18, 16, v16
	v_sub_u32_e32 v16, 0x2000, v32
	v_cndmask_b32_e64 v16, v16, 0, vcc
	v_or_b32_e32 v16, v16, v22
	v_ashrrev_i32_e32 v17, 31, v16
	v_lshl_add_u64 v[16:17], v[16:17], 1, s[92:93]
	s_waitcnt vmcnt(14)
	v_mov_b32_e32 v16, v211
	s_waitcnt vmcnt(0)
	v_lshlrev_b32_e32 v16, 16, v16
	v_cndmask_b32_e64 v19, v16, 0, vcc
	s_and_b64 vcc, exec, s[52:53]
	s_cbranch_vccz .LBB0_990
	v_cvt_f32_u32_e32 v16, v32
	v_sub_f32_e32 v20, v18, v19
	s_mov_b64 s[58:59], 0
	v_mul_f32_e32 v17, 0x38800000, v16
	v_cos_f32_e32 v16, v17
	v_sin_f32_e64 v17, -v17
	s_nop 0
	v_pk_mul_f32 v[16:17], v[16:17], v[20:21] op_sel_hi:[1,0]

; __device__ __forceinline__ float bf2f(bf16_t b) { return __uint_as_float(((unsigned)b) << 16); }
; __device__ __forceinline__ float2 twid(float turns) { return make_float2(__builtin_amdgcn_cosf(turns), -__builtin_amdgcn_sinf(turns)); }
;   __device__ __forceinline__ float2 operator()(int i) const { const float2 wv = unpk2(Wd[i]); return half ? cmul(wv, twid((float)(i & (L - 1)) * invTurn)) : wv; }
;   __device__ __forceinline__ float2 operator()(int i) const {
;     const int ch = i >> lshift, t = i & (L - 1);
;     const float f = bf2f(hf[ch * chstride + t]), bw = bf2f(hb[ch * chstride + (t > 0 ? L - t : 0)]);
;     const float bwm = t > 0 ? bw : 0.f;
;     if (half == 0) return make_float2(f + bwm, 0.f);
;     const float2 tw = twid((float)t * invTurn); const float d = f - bwm; return make_float2(d * tw.x, d * tw.y);
;   }
.LBB0_992:
	v_ashrrev_i32_e32 v23, 31, v22
	v_lshl_add_u64 v[20:21], v[22:23], 0, v[32:33]
	v_lshl_add_u64 v[20:21], v[20:21], 1, s[36:37]
	s_waitcnt vmcnt(13)
	v_mov_b32_e32 v19, v212
	v_or_b32_e32 v18, 0x400, v32
	s_mov_b64 s[58:59], -1
	s_and_b64 vcc, exec, s[40:41]
	s_waitcnt vmcnt(0)
	v_lshlrev_b32_e32 v20, 16, v19
	v_sub_u32_e32 v19, v22, v18
	v_add_u32_e32 v24, 0x2000, v19
	v_ashrrev_i32_e32 v25, 31, v24
	v_lshl_add_u64 v[24:25], v[24:25], 1, s[92:93]
	s_waitcnt vmcnt(12)
	v_mov_b32_e32 v19, v213
	s_waitcnt vmcnt(0)
	v_lshlrev_b32_e32 v21, 16, v19
	s_cbranch_vccnz .LBB0_994
	v_cvt_f32_u32_e32 v18, v18
	v_sub_f32_e32 v24, v20, v21
	s_mov_b64 s[58:59], 0
	v_mul_f32_e32 v19, 0x38800000, v18
	v_cos_f32_e32 v18, v19
	v_sin_f32_e64 v19, -v19
	s_nop 0
	v_pk_mul_f32 v[18:19], v[18:19], v[24:25] op_sel_hi:[1,0]

; __device__ __forceinline__ float bf2f(bf16_t b) { return __uint_as_float(((unsigned)b) << 16); }
; __device__ __forceinline__ float2 twid(float turns) { return make_float2(__builtin_amdgcn_cosf(turns), -__builtin_amdgcn_sinf(turns)); }
;   __device__ __forceinline__ float2 operator()(int i) const { const float2 wv = unpk2(Wd[i]); return half ? cmul(wv, twid((float)(i & (L - 1)) * invTurn)) : wv; }
;   __device__ __forceinline__ float2 operator()(int i) const {
;     const int ch = i >> lshift, t = i & (L - 1);
;     const float f = bf2f(hf[ch * chstride + t]), bw = bf2f(hb[ch * chstride + (t > 0 ? L - t : 0)]);
;     const float bwm = t > 0 ? bw : 0.f;
;     if (half == 0) return make_float2(f + bwm, 0.f);
;     const float2 tw = twid((float)t * invTurn); const float d = f - bwm; return make_float2(d * tw.x, d * tw.y);
;   }
.LBB0_996:
	v_or_b32_e32 v20, 0x800, v32
	v_or_b32_e32 v24, v22, v20
	v_ashrrev_i32_e32 v25, 31, v24
	v_lshl_add_u64 v[24:25], v[24:25], 1, s[36:37]
	s_waitcnt vmcnt(11)
	v_mov_b32_e32 v21, v214
	s_mov_b64 s[58:59], -1
	s_and_b64 vcc, exec, s[40:41]
	s_waitcnt vmcnt(0)
	v_lshlrev_b32_e32 v23, 16, v21
	v_sub_u32_e32 v21, v22, v20
	v_add_u32_e32 v24, 0x2000, v21
	v_ashrrev_i32_e32 v25, 31, v24
	v_lshl_add_u64 v[24:25], v[24:25], 1, s[92:93]
	s_waitcnt vmcnt(10)
	v_mov_b32_e32 v21, v215
	s_waitcnt vmcnt(0)
	v_lshlrev_b32_e32 v24, 16, v21
	s_cbranch_vccnz .LBB0_998
	v_cvt_f32_u32_e32 v20, v20
	v_sub_f32_e32 v26, v23, v24
	s_mov_b64 s[58:59], 0
	v_mul_f32_e32 v21, 0x38800000, v20
	v_cos_f32_e32 v20, v21
	v_sin_f32_e64 v21, -v21
	s_nop 0
	v_pk_mul_f32 v[20:21], v[20:21], v[26:27] op_sel_hi:[1,0]

; __device__ __forceinline__ float bf2f(bf16_t b) { return __uint_as_float(((unsigned)b) << 16); }
; __device__ __forceinline__ float2 twid(float turns) { return make_float2(__builtin_amdgcn_cosf(turns), -__builtin_amdgcn_sinf(turns)); }
;   __device__ __forceinline__ float2 operator()(int i) const { const float2 wv = unpk2(Wd[i]); return half ? cmul(wv, twid((float)(i & (L - 1)) * invTurn)) : wv; }
;   __device__ __forceinline__ float2 operator()(int i) const {
;     const int ch = i >> lshift, t = i & (L - 1);
;     const float f = bf2f(hf[ch * chstride + t]), bw = bf2f(hb[ch * chstride + (t > 0 ? L - t : 0)]);
;     const float bwm = t > 0 ? bw : 0.f;
;     if (half == 0) return make_float2(f + bwm, 0.f);
;     const float2 tw = twid((float)t * invTurn); const float d = f - bwm; return make_float2(d * tw.x, d * tw.y);
;   }
.LBB0_1000:
	v_or_b32_e32 v24, 0xc00, v32
	v_or_b32_e32 v26, v22, v24
	v_ashrrev_i32_e32 v27, 31, v26
	v_lshl_add_u64 v[26:27], v[26:27], 1, s[36:37]
	v_sub_u32_e32 v25, v22, v24
	s_waitcnt vmcnt(9)
	v_mov_b32_e32 v23, v216
	v_add_u32_e32 v26, 0x2000, v25
	v_ashrrev_i32_e32 v27, 31, v26
	v_lshl_add_u64 v[26:27], v[26:27], 1, s[92:93]
	s_waitcnt vmcnt(8)
	v_mov_b32_e32 v25, v217
	s_mov_b64 s[58:59], -1
	s_and_b64 vcc, exec, s[40:41]
	s_waitcnt vmcnt(1)
	v_lshlrev_b32_e32 v23, 16, v23
	s_waitcnt vmcnt(0)
	v_lshlrev_b32_e32 v26, 16, v25
	s_cbranch_vccnz .LBB0_1002
	v_cvt_f32_u32_e32 v24, v24
	v_sub_f32_e32 v28, v23, v26
	s_mov_b64 s[58:59], 0
	v_mul_f32_e32 v25, 0x38800000, v24
	v_cos_f32_e32 v24, v25
	v_sin_f32_e64 v25, -v25
	s_nop 0
	v_pk_mul_f32 v[24:25], v[24:25], v[28:29] op_sel_hi:[1,0]

; __device__ __forceinline__ float bf2f(bf16_t b) { return __uint_as_float(((unsigned)b) << 16); }
; __device__ __forceinline__ float2 twid(float turns) { return make_float2(__builtin_amdgcn_cosf(turns), -__builtin_amdgcn_sinf(turns)); }
;   __device__ __forceinline__ float2 operator()(int i) const { const float2 wv = unpk2(Wd[i]); return half ? cmul(wv, twid((float)(i & (L - 1)) * invTurn)) : wv; }
;   __device__ __forceinline__ float2 operator()(int i) const {
;     const int ch = i >> lshift, t = i & (L - 1);
;     const float f = bf2f(hf[ch * chstride + t]), bw = bf2f(hb[ch * chstride + (t > 0 ? L - t : 0)]);
;     const float bwm = t > 0 ? bw : 0.f;
;     if (half == 0) return make_float2(f + bwm, 0.f);
;     const float2 tw = twid((float)t * invTurn); const float d = f - bwm; return make_float2(d * tw.x, d * tw.y);
;   }
.LBB0_1004:
	v_or_b32_e32 v26, 0x1000, v32
	v_or_b32_e32 v28, v22, v26
	v_ashrrev_i32_e32 v29, 31, v28
	v_lshl_add_u64 v[28:29], v[28:29], 1, s[36:37]
	v_sub_u32_e32 v27, v22, v26
	s_waitcnt vmcnt(7)
	v_mov_b32_e32 v23, v218
	v_add_u32_e32 v28, 0x2000, v27
	v_ashrrev_i32_e32 v29, 31, v28
	v_lshl_add_u64 v[28:29], v[28:29], 1, s[92:93]
	s_waitcnt vmcnt(6)
	v_mov_b32_e32 v27, v219
	s_mov_b64 s[58:59], -1
	s_and_b64 vcc, exec, s[40:41]
	s_waitcnt vmcnt(1)
	v_lshlrev_b32_e32 v23, 16, v23
	s_waitcnt vmcnt(0)
	v_lshlrev_b32_e32 v28, 16, v27
	s_cbranch_vccnz .LBB0_1006
	v_cvt_f32_u32_e32 v26, v26
	v_sub_f32_e32 v30, v23, v28
	s_mov_b64 s[58:59], 0
	v_mul_f32_e32 v27, 0x38800000, v26
	v_cos_f32_e32 v26, v27
	v_sin_f32_e64 v27, -v27
	s_nop 0
	v_pk_mul_f32 v[26:27], v[26:27], v[30:31] op_sel_hi:[1,0]

; __device__ __forceinline__ float bf2f(bf16_t b) { return __uint_as_float(((unsigned)b) << 16); }
; __device__ __forceinline__ float2 twid(float turns) { return make_float2(__builtin_amdgcn_cosf(turns), -__builtin_amdgcn_sinf(turns)); }
;   __device__ __forceinline__ float2 operator()(int i) const { const float2 wv = unpk2(Wd[i]); return half ? cmul(wv, twid((float)(i & (L - 1)) * invTurn)) : wv; }
;   __device__ __forceinline__ float2 operator()(int i) const {
;     const int ch = i >> lshift, t = i & (L - 1);
;     const float f = bf2f(hf[ch * chstride + t]), bw = bf2f(hb[ch * chstride + (t > 0 ? L - t : 0)]);
;     const float bwm = t > 0 ? bw : 0.f;
;     if (half == 0) return make_float2(f + bwm, 0.f);
;     const float2 tw = twid((float)t * invTurn); const float d = f - bwm; return make_float2(d * tw.x, d * tw.y);
;   }
.LBB0_1008:
	v_or_b32_e32 v28, 0x1400, v32
	v_or_b32_e32 v30, v22, v28
	v_ashrrev_i32_e32 v31, 31, v30
	v_lshl_add_u64 v[30:31], v[30:31], 1, s[36:37]
	v_sub_u32_e32 v29, v22, v28
	s_waitcnt vmcnt(5)
	v_mov_b32_e32 v23, v220
	v_add_u32_e32 v30, 0x2000, v29
	v_ashrrev_i32_e32 v31, 31, v30
	v_lshl_add_u64 v[30:31], v[30:31], 1, s[92:93]
	s_waitcnt vmcnt(4)
	v_mov_b32_e32 v29, v221
	s_mov_b64 s[58:59], -1
	s_and_b64 vcc, exec, s[40:41]
	s_waitcnt vmcnt(1)
	v_lshlrev_b32_e32 v23, 16, v23
	s_waitcnt vmcnt(0)
	v_lshlrev_b32_e32 v30, 16, v29
	s_cbranch_vccnz .LBB0_1010
	v_cvt_f32_u32_e32 v28, v28
	v_sub_f32_e32 v38, v23, v30
	s_mov_b64 s[58:59], 0
	v_mul_f32_e32 v29, 0x38800000, v28
	v_cos_f32_e32 v28, v29
	v_sin_f32_e64 v29, -v29
	s_nop 0
	v_pk_mul_f32 v[28:29], v[28:29], v[38:39] op_sel_hi:[1,0]

; __device__ __forceinline__ float bf2f(bf16_t b) { return __uint_as_float(((unsigned)b) << 16); }
; __device__ __forceinline__ float2 twid(float turns) { return make_float2(__builtin_amdgcn_cosf(turns), -__builtin_amdgcn_sinf(turns)); }
;   __device__ __forceinline__ float2 operator()(int i) const { const float2 wv = unpk2(Wd[i]); return half ? cmul(wv, twid((float)(i & (L - 1)) * invTurn)) : wv; }
;   __device__ __forceinline__ float2 operator()(int i) const {
;     const int ch = i >> lshift, t = i & (L - 1);
;     const float f = bf2f(hf[ch * chstride + t]), bw = bf2f(hb[ch * chstride + (t > 0 ? L - t : 0)]);
;     const float bwm = t > 0 ? bw : 0.f;
;     if (half == 0) return make_float2(f + bwm, 0.f);
;     const float2 tw = twid((float)t * invTurn); const float d = f - bwm; return make_float2(d * tw.x, d * tw.y);
;   }
.LBB0_1012:
	v_or_b32_e32 v30, 0x1800, v32
	v_or_b32_e32 v38, v22, v30
	v_ashrrev_i32_e32 v39, 31, v38
	v_lshl_add_u64 v[38:39], v[38:39], 1, s[36:37]
	v_sub_u32_e32 v31, v22, v30
	s_waitcnt vmcnt(3)
	v_mov_b32_e32 v23, v222
	v_add_u32_e32 v38, 0x2000, v31
	v_ashrrev_i32_e32 v39, 31, v38
	v_lshl_add_u64 v[38:39], v[38:39], 1, s[92:93]
	s_waitcnt vmcnt(2)
	v_mov_b32_e32 v31, v223
	s_mov_b64 s[58:59], -1
	s_and_b64 vcc, exec, s[40:41]
	s_waitcnt vmcnt(1)
	v_lshlrev_b32_e32 v23, 16, v23
	s_waitcnt vmcnt(0)
	v_lshlrev_b32_e32 v38, 16, v31
	s_cbranch_vccnz .LBB0_1014
	v_cvt_f32_u32_e32 v30, v30
	v_sub_f32_e32 v40, v23, v38
	s_mov_b64 s[58:59], 0
	v_mul_f32_e32 v31, 0x38800000, v30
	v_cos_f32_e32 v30, v31
	v_sin_f32_e64 v31, -v31
	s_nop 0
	v_pk_mul_f32 v[30:31], v[30:31], v[40:41] op_sel_hi:[1,0]

; __device__ __forceinline__ float bf2f(bf16_t b) { return __uint_as_float(((unsigned)b) << 16); }
; __device__ __forceinline__ float2 twid(float turns) { return make_float2(__builtin_amdgcn_cosf(turns), -__builtin_amdgcn_sinf(turns)); }
;   __device__ __forceinline__ float2 operator()(int i) const { const float2 wv = unpk2(Wd[i]); return half ? cmul(wv, twid((float)(i & (L - 1)) * invTurn)) : wv; }
;   __device__ __forceinline__ float2 operator()(int i) const {
;     const int ch = i >> lshift, t = i & (L - 1);
;     const float f = bf2f(hf[ch * chstride + t]), bw = bf2f(hb[ch * chstride + (t > 0 ? L - t : 0)]);
;     const float bwm = t > 0 ? bw : 0.f;
;     if (half == 0) return make_float2(f + bwm, 0.f);
;     const float2 tw = twid((float)t * invTurn); const float d = f - bwm; return make_float2(d * tw.x, d * tw.y);
;   }
.LBB0_1016:
	v_or_b32_e32 v39, 0x1c00, v32
	v_or_b32_e32 v40, v22, v39
	v_ashrrev_i32_e32 v41, 31, v40
	v_lshl_add_u64 v[40:41], v[40:41], 1, s[36:37]
	s_waitcnt vmcnt(1)
	v_mov_b32_e32 v23, v224
	v_sub_u32_e32 v22, v22, v39
	v_add_u32_e32 v22, 0x2000, v22
	s_mov_b64 s[58:59], -1
	s_and_b64 vcc, exec, s[40:41]
	s_waitcnt vmcnt(0)
	v_lshlrev_b32_e32 v32, 16, v23
	v_ashrrev_i32_e32 v23, 31, v22
	v_lshl_add_u64 v[22:23], v[22:23], 1, s[92:93]
	s_waitcnt vmcnt(0)
	v_mov_b32_e32 v22, v225
	s_waitcnt vmcnt(0)
	v_lshlrev_b32_e32 v38, 16, v22
	s_cbranch_vccnz .LBB0_1018
	v_cvt_f32_u32_e32 v22, v39
	v_sub_f32_e32 v40, v32, v38
	s_mov_b64 s[58:59], 0
	v_mul_f32_e32 v23, 0x38800000, v22
	v_cos_f32_e32 v22, v23
	v_sin_f32_e64 v23, -v23
	s_nop 0
	v_pk_mul_f32 v[22:23], v[22:23], v[40:41] op_sel_hi:[1,0]

; __device__ __forceinline__ float2 cmul(float2 a, float2 b) { return make_float2(a.x * b.x - a.y * b.y, a.x * b.y + a.y * b.x); }
; __device__ __forceinline__ float2 twid(float turns) { return make_float2(__builtin_amdgcn_cosf(turns), -__builtin_amdgcn_sinf(turns)); }
; template <int R, bool INV>
; __device__ __forceinline__ void butterflies(c32 (&v)[1 << R], float turns0) {
;   constexpr int RAD = 1 << R;
;   constexpr float TC[16] = {1.0f, 0.98078528040f, 0.92387953251f, 0.83146961230f, 0.70710678119f, 0.55557023302f, 0.38268343237f, 0.19509032202f,
;                             0.0f, -0.19509032202f, -0.38268343237f, -0.55557023302f, -0.70710678119f, -0.83146961230f, -0.92387953251f, -0.98078528040f};
;   constexpr float TS[16] = {0.0f, 0.19509032202f, 0.38268343237f, 0.55557023302f, 0.70710678119f, 0.83146961230f, 0.92387953251f, 0.98078528040f,
;                             1.0f, 0.98078528040f, 0.92387953251f, 0.83146961230f, 0.70710678119f, 0.55557023302f, 0.38268343237f, 0.19509032202f};
;   float2 tbs[R];
;   tbs[0] = twid(turns0);
;   if (INV) tbs[0].y = -tbs[0].y;
; #pragma unroll
;   for (int k = 1; k < R; ++k) tbs[k] = cmul(tbs[k - 1], tbs[k - 1]);
; #pragma unroll
;   for (int kk = 0; kk < R; ++kk) {
;     const int k = INV ? (R - 1 - kk) : kk;
;     const int hd = RAD >> (k + 1);
; #pragma unroll
;     for (int j = 0; j < RAD; ++j) {
;       if ((j & hd) == 0) {
;         const int m = (j & (hd - 1)) * (16 / hd);
;         const float2 c = make_float2(TC[m], INV ? TS[m] : -TS[m]);
;         const float2 twf = cmul(tbs[k], c);
;         const c32 tw = {twf.x, twf.y};
;         const c32 a = v[j], b = v[j + hd];
;         if (!INV) { v[j] = a + b; v[j + hd] = cmul_pk(a - b, tw); }
;         else { const c32 bt = cmul_pk(b, tw); v[j] = a + bt; v[j + hd] = a - bt; }
;       }
;     }
;   }
; }
; template <int LOGN>
; __device__ __forceinline__ void fft_last_to_regs(const float2* X, c32 (&kf)[32]) {
;   static_assert(LOGN == 14, "one radix-32 group per thread");
;   const c32* Xc = (const c32*)X;
;   int tid0 = threadIdx.x; asm volatile("" : "+v"(tid0));
;   const int pb = tid0 * 33;
;   c32 v[32];
; #pragma unroll
;   for (int j = 0; j < 32; ++j) v[j] = Xc[pb + j];
;   butterflies<5, false>(v, 0.f);
; #pragma unroll
;   for (int j = 0; j < 32; ++j) kf[j] = v[j];
;   __syncthreads();
; }
.LBB0_1023:
	s_or_b64 exec, exec, s[0:1]
	v_mov_b32_e32 v0, v196
	s_waitcnt lgkmcnt(0)
	s_barrier
	s_mov_b32 s7, s95
	v_mul_lo_u32 v0, v0, s61
	v_add_u32_e32 v32, 0, v0
	ds_read2_b64 v[0:3], v32 offset1:1
	ds_read2_b64 v[4:7], v32 offset0:2 offset1:3
	ds_read2_b64 v[8:11], v32 offset0:4 offset1:5
	ds_read2_b64 v[12:15], v32 offset0:6 offset1:7
	ds_read2_b64 v[16:19], v32 offset0:8 offset1:9
	ds_read2_b64 v[20:23], v32 offset0:10 offset1:11
	ds_read2_b64 v[24:27], v32 offset0:12 offset1:13
	ds_read2_b64 v[28:31], v32 offset0:14 offset1:15
	ds_read2_b64 v[34:37], v32 offset0:16 offset1:17
	ds_read2_b64 v[38:41], v32 offset0:18 offset1:19
	ds_read2_b64 v[42:45], v32 offset0:20 offset1:21
	ds_read2_b64 v[46:49], v32 offset0:22 offset1:23
	ds_read2_b64 v[50:53], v32 offset0:24 offset1:25
	ds_read2_b64 v[54:57], v32 offset0:26 offset1:27
	ds_read2_b64 v[58:61], v32 offset0:28 offset1:29
	ds_read2_b64 v[62:65], v32 offset0:30 offset1:31
	s_waitcnt lgkmcnt(7)
	v_pk_add_f32 v[66:67], v[0:1], v[34:35]
	v_pk_add_f32 v[34:35], v[0:1], v[34:35] neg_lo:[0,1] neg_hi:[0,1]
	v_mov_b64_e32 v[0:1], s[6:7]
	v_pk_mul_f32 v[68:69], v[34:35], v[0:1] op_sel:[0,0] op_sel_hi:[0,1]
	s_mov_b32 s0, s19
	s_mov_b32 s1, s30
	v_pk_fma_f32 v[34:35], v[34:35], v[0:1], v[68:69] op_sel:[1,1,0] op_sel_hi:[1,0,1] neg_lo:[0,1,0]
	v_pk_add_f32 v[68:69], v[2:3], v[36:37]
	v_pk_add_f32 v[2:3], v[2:3], v[36:37] neg_lo:[0,1] neg_hi:[0,1]
	v_mov_b64_e32 v[36:37], s[0:1]
	v_pk_mul_f32 v[70:71], v[2:3], v[36:37] op_sel:[0,0] op_sel_hi:[0,1]
	s_mov_b32 s0, s9
	s_mov_b32 s1, s76
	v_pk_fma_f32 v[36:37], v[2:3], v[36:37], v[70:71] op_sel:[1,1,0] op_sel_hi:[1,0,1] neg_lo:[0,1,0]
	s_waitcnt lgkmcnt(6)
	v_pk_add_f32 v[70:71], v[4:5], v[38:39]
	v_pk_add_f32 v[2:3], v[4:5], v[38:39] neg_lo:[0,1] neg_hi:[0,1]
	v_mov_b64_e32 v[4:5], s[0:1]
	v_pk_mul_f32 v[38:39], v[2:3], v[4:5] op_sel:[0,0] op_sel_hi:[0,1]
	s_mov_b32 s0, s57
	s_mov_b32 s1, s68
	v_pk_fma_f32 v[38:39], v[2:3], v[4:5], v[38:39] op_sel:[1,1,0] op_sel_hi:[1,0,1] neg_lo:[0,1,0]
	v_pk_add_f32 v[72:73], v[6:7], v[40:41]
	v_pk_add_f32 v[2:3], v[6:7], v[40:41] neg_lo:[0,1] neg_hi:[0,1]
	v_mov_b64_e32 v[6:7], s[0:1]
	v_pk_mul_f32 v[40:41], v[2:3], v[6:7] op_sel:[0,0] op_sel_hi:[0,1]
	s_mov_b32 s0, s73
	s_mov_b32 s1, s72
	v_pk_fma_f32 v[6:7], v[2:3], v[6:7], v[40:41] op_sel:[1,1,0] op_sel_hi:[1,0,1] neg_lo:[0,1,0]
	s_waitcnt lgkmcnt(5)
	v_pk_add_f32 v[40:41], v[8:9], v[42:43]
	v_pk_add_f32 v[2:3], v[8:9], v[42:43] neg_lo:[0,1] neg_hi:[0,1]
	v_mov_b64_e32 v[8:9], s[0:1]
	v_pk_mul_f32 v[42:43], v[2:3], v[8:9] op_sel:[0,0] op_sel_hi:[0,1]
	s_mov_b32 s0, s56
	s_mov_b32 s1, s16
	v_pk_fma_f32 v[42:43], v[2:3], v[8:9], v[42:43] op_sel:[1,1,0] op_sel_hi:[1,0,1] neg_lo:[0,1,0]
	v_pk_add_f32 v[74:75], v[10:11], v[44:45]
	v_pk_add_f32 v[2:3], v[10:11], v[44:45] neg_lo:[0,1] neg_hi:[0,1]
	v_mov_b64_e32 v[10:11], s[0:1]
	v_pk_mul_f32 v[44:45], v[2:3], v[10:11] op_sel:[0,0] op_sel_hi:[0,1]
	s_mov_b32 s0, s8
	s_mov_b32 s1, s10
	v_pk_fma_f32 v[10:11], v[2:3], v[10:11], v[44:45] op_sel:[1,1,0] op_sel_hi:[1,0,1] neg_lo:[0,1,0]
	s_waitcnt lgkmcnt(4)
	v_pk_add_f32 v[44:45], v[12:13], v[46:47]
	v_pk_add_f32 v[2:3], v[12:13], v[46:47] neg_lo:[0,1] neg_hi:[0,1]
	v_mov_b64_e32 v[12:13], s[0:1]
	v_pk_mul_f32 v[46:47], v[2:3], v[12:13] op_sel:[0,0] op_sel_hi:[0,1]
	s_mov_b32 s0, s18
	s_mov_b32 s1, s4
	v_pk_fma_f32 v[46:47], v[2:3], v[12:13], v[46:47] op_sel:[1,1,0] op_sel_hi:[1,0,1] neg_lo:[0,1,0]
	v_pk_add_f32 v[76:77], v[14:15], v[48:49]
	v_pk_add_f32 v[2:3], v[14:15], v[48:49] neg_lo:[0,1] neg_hi:[0,1]
	v_mov_b64_e32 v[14:15], s[0:1]
	v_pk_mul_f32 v[48:49], v[2:3], v[14:15] op_sel:[0,0] op_sel_hi:[0,1]
	s_mov_b32 s88, s94
	v_pk_fma_f32 v[14:15], v[2:3], v[14:15], v[48:49] op_sel:[1,1,0] op_sel_hi:[1,0,1] neg_lo:[0,1,0]
	s_waitcnt lgkmcnt(3)
	v_pk_add_f32 v[48:49], v[16:17], v[50:51]
	v_pk_add_f32 v[16:17], v[16:17], v[50:51] neg_lo:[0,1] neg_hi:[0,1]
	v_mov_b64_e32 v[2:3], s[88:89]
	v_pk_mul_f32 v[50:51], v[16:17], v[2:3] op_sel:[0,0] op_sel_hi:[0,1]
	s_mov_b32 s31, s4
	v_pk_fma_f32 v[16:17], v[16:17], v[2:3], v[50:51] op_sel:[1,1,0] op_sel_hi:[1,0,1] neg_lo:[0,1,0]
	v_pk_add_f32 v[50:51], v[18:19], v[52:53]
	v_pk_add_f32 v[18:19], v[18:19], v[52:53] neg_lo:[0,1] neg_hi:[0,1]
	v_mov_b64_e32 v[52:53], s[30:31]
	v_pk_mul_f32 v[78:79], v[18:19], v[52:53] op_sel:[0,0] op_sel_hi:[0,1]
	s_mov_b32 s77, s10
	v_pk_fma_f32 v[18:19], v[18:19], v[52:53], v[78:79] op_sel:[1,1,0] op_sel_hi:[1,0,1] neg_lo:[0,1,0]
	s_waitcnt lgkmcnt(2)
	v_pk_add_f32 v[52:53], v[20:21], v[54:55]
	v_pk_add_f32 v[20:21], v[20:21], v[54:55] neg_lo:[0,1] neg_hi:[0,1]
	v_mov_b64_e32 v[54:55], s[76:77]
	v_pk_mul_f32 v[78:79], v[20:21], v[54:55] op_sel:[0,0] op_sel_hi:[0,1]
	s_mov_b32 s69, s16
	v_pk_fma_f32 v[20:21], v[20:21], v[54:55], v[78:79] op_sel:[1,1,0] op_sel_hi:[1,0,1] neg_lo:[0,1,0]
	v_pk_add_f32 v[78:79], v[22:23], v[56:57]
	v_pk_add_f32 v[22:23], v[22:23], v[56:57] neg_lo:[0,1] neg_hi:[0,1]
	v_mov_b64_e32 v[56:57], s[68:69]
	v_pk_mul_f32 v[80:81], v[22:23], v[56:57] op_sel:[0,0] op_sel_hi:[0,1]
	s_mov_b32 s0, s72
	s_mov_b32 s1, s72
	v_pk_fma_f32 v[22:23], v[22:23], v[56:57], v[80:81] op_sel:[1,1,0] op_sel_hi:[1,0,1] neg_lo:[0,1,0]
	s_waitcnt lgkmcnt(1)
	v_pk_add_f32 v[56:57], v[24:25], v[58:59]
	v_pk_add_f32 v[24:25], v[24:25], v[58:59] neg_lo:[0,1] neg_hi:[0,1]
	v_mov_b64_e32 v[58:59], s[0:1]
	v_pk_mul_f32 v[80:81], v[24:25], v[58:59] op_sel:[0,0] op_sel_hi:[0,1]
	s_mov_b32 s17, s68
	v_pk_fma_f32 v[24:25], v[24:25], v[58:59], v[80:81] op_sel:[1,1,0] op_sel_hi:[1,0,1] neg_lo:[0,1,0]
	v_pk_add_f32 v[80:81], v[26:27], v[60:61]
	v_pk_add_f32 v[26:27], v[26:27], v[60:61] neg_lo:[0,1] neg_hi:[0,1]
	v_mov_b64_e32 v[60:61], s[16:17]
	v_pk_mul_f32 v[82:83], v[26:27], v[60:61] op_sel:[0,0] op_sel_hi:[0,1]
	s_mov_b32 s11, s76
	v_pk_fma_f32 v[26:27], v[26:27], v[60:61], v[82:83] op_sel:[1,1,0] op_sel_hi:[1,0,1] neg_lo:[0,1,0]
	s_waitcnt lgkmcnt(0)
	v_pk_add_f32 v[60:61], v[28:29], v[62:63]
	v_pk_add_f32 v[28:29], v[28:29], v[62:63] neg_lo:[0,1] neg_hi:[0,1]
	v_mov_b64_e32 v[62:63], s[10:11]
	v_pk_mul_f32 v[82:83], v[28:29], v[62:63] op_sel:[0,0] op_sel_hi:[0,1]
	s_mov_b32 s5, s30
	v_pk_fma_f32 v[28:29], v[28:29], v[62:63], v[82:83] op_sel:[1,1,0] op_sel_hi:[1,0,1] neg_lo:[0,1,0]
	v_pk_add_f32 v[82:83], v[30:31], v[64:65]
	v_pk_add_f32 v[30:31], v[30:31], v[64:65] neg_lo:[0,1] neg_hi:[0,1]
	v_mov_b64_e32 v[64:65], s[4:5]
	v_pk_mul_f32 v[84:85], v[30:31], v[64:65] op_sel:[0,0] op_sel_hi:[0,1]
	v_mov_b32_e32 v130, v196
	v_pk_fma_f32 v[30:31], v[30:31], v[64:65], v[84:85] op_sel:[1,1,0] op_sel_hi:[1,0,1] neg_lo:[0,1,0]
	v_pk_add_f32 v[64:65], v[66:67], v[48:49]
	v_pk_add_f32 v[48:49], v[66:67], v[48:49] neg_lo:[0,1] neg_hi:[0,1]
	s_nop 0
	v_pk_mul_f32 v[66:67], v[48:49], v[0:1] op_sel:[0,0] op_sel_hi:[0,1]
	s_barrier
; __device__ __forceinline__ float2 cmul(float2 a, float2 b) { return make_float2(a.x * b.x - a.y * b.y, a.x * b.y + a.y * b.x); }
; template <int R, bool INV>
; __device__ __forceinline__ void butterflies(c32 (&v)[1 << R], float turns0) {
;     ...
; #pragma unroll
;   for (int k = 1; k < R; ++k) tbs[k] = cmul(tbs[k - 1], tbs[k - 1]);
; #pragma unroll
;   for (int kk = 0; kk < R; ++kk) {
;     const int k = INV ? (R - 1 - kk) : kk;
;     const int hd = RAD >> (k + 1);
; #pragma unroll
;     for (int j = 0; j < RAD; ++j) {
;       if ((j & hd) == 0) {
;         const int m = (j & (hd - 1)) * (16 / hd);
;         const float2 c = make_float2(TC[m], INV ? TS[m] : -TS[m]);
;         const float2 twf = cmul(tbs[k], c);
;         const c32 tw = {twf.x, twf.y};
;         const c32 a = v[j], b = v[j + hd];
;         if (!INV) { v[j] = a + b; v[j + hd] = cmul_pk(a - b, tw); }
;         else { const c32 bt = cmul_pk(b, tw); v[j] = a + bt; v[j + hd] = a - bt; }
;       }
;     }
;   }
	v_pk_fma_f32 v[48:49], v[48:49], v[0:1], v[66:67] op_sel:[1,1,0] op_sel_hi:[1,0,1] neg_lo:[0,1,0]
	v_pk_add_f32 v[66:67], v[68:69], v[50:51]
	v_pk_add_f32 v[50:51], v[68:69], v[50:51] neg_lo:[0,1] neg_hi:[0,1]
	s_nop 0
	v_pk_mul_f32 v[68:69], v[50:51], v[4:5] op_sel:[0,0] op_sel_hi:[0,1]
	s_and_b64 vcc, exec, s[40:41]
	v_pk_fma_f32 v[50:51], v[50:51], v[4:5], v[68:69] op_sel:[1,1,0] op_sel_hi:[1,0,1] neg_lo:[0,1,0]
	v_pk_add_f32 v[68:69], v[70:71], v[52:53]
	v_pk_add_f32 v[52:53], v[70:71], v[52:53] neg_lo:[0,1] neg_hi:[0,1]
	v_lshlrev_b32_e32 v32, 3, v130
	v_pk_mul_f32 v[70:71], v[52:53], v[8:9] op_sel:[0,0] op_sel_hi:[0,1]
	s_nop 0
	v_pk_fma_f32 v[52:53], v[52:53], v[8:9], v[70:71] op_sel:[1,1,0] op_sel_hi:[1,0,1] neg_lo:[0,1,0]
	v_pk_add_f32 v[70:71], v[72:73], v[78:79]
	v_pk_add_f32 v[72:73], v[72:73], v[78:79] neg_lo:[0,1] neg_hi:[0,1]
	s_nop 0
	v_pk_mul_f32 v[78:79], v[72:73], v[12:13] op_sel:[0,0] op_sel_hi:[0,1]
	s_nop 0
	v_pk_fma_f32 v[72:73], v[72:73], v[12:13], v[78:79] op_sel:[1,1,0] op_sel_hi:[1,0,1] neg_lo:[0,1,0]
	v_pk_add_f32 v[78:79], v[40:41], v[56:57]
	v_pk_add_f32 v[40:41], v[40:41], v[56:57] neg_lo:[0,1] neg_hi:[0,1]
	s_nop 0
	v_pk_mul_f32 v[56:57], v[40:41], v[2:3] op_sel:[0,0] op_sel_hi:[0,1]
	s_nop 0
	v_pk_fma_f32 v[40:41], v[40:41], v[2:3], v[56:57] op_sel:[1,1,0] op_sel_hi:[1,0,1] neg_lo:[0,1,0]
	v_pk_add_f32 v[56:57], v[74:75], v[80:81]
	v_pk_add_f32 v[74:75], v[74:75], v[80:81] neg_lo:[0,1] neg_hi:[0,1]
	v_pk_add_f32 v[84:85], v[48:49], v[40:41]
	v_pk_mul_f32 v[80:81], v[74:75], v[54:55] op_sel:[0,0] op_sel_hi:[0,1]
	v_pk_add_f32 v[40:41], v[48:49], v[40:41] neg_lo:[0,1] neg_hi:[0,1]
	v_pk_fma_f32 v[74:75], v[74:75], v[54:55], v[80:81] op_sel:[1,1,0] op_sel_hi:[1,0,1] neg_lo:[0,1,0]
	v_pk_add_f32 v[80:81], v[44:45], v[60:61]
	v_pk_add_f32 v[44:45], v[44:45], v[60:61] neg_lo:[0,1] neg_hi:[0,1]
	v_pk_mul_f32 v[48:49], v[40:41], v[0:1] op_sel:[0,0] op_sel_hi:[0,1]
	s_nop 0
	v_pk_mul_f32 v[60:61], v[44:45], v[58:59] op_sel:[0,0] op_sel_hi:[0,1]
	v_pk_fma_f32 v[40:41], v[40:41], v[0:1], v[48:49] op_sel:[1,1,0] op_sel_hi:[1,0,1] neg_lo:[0,1,0]
	v_pk_add_f32 v[48:49], v[50:51], v[74:75]
	v_pk_fma_f32 v[44:45], v[44:45], v[58:59], v[60:61] op_sel:[1,1,0] op_sel_hi:[1,0,1] neg_lo:[0,1,0]
	v_pk_add_f32 v[60:61], v[76:77], v[82:83]
	v_pk_add_f32 v[76:77], v[76:77], v[82:83] neg_lo:[0,1] neg_hi:[0,1]
	v_pk_add_f32 v[50:51], v[50:51], v[74:75] neg_lo:[0,1] neg_hi:[0,1]
	v_pk_mul_f32 v[82:83], v[76:77], v[62:63] op_sel:[0,0] op_sel_hi:[0,1]
	v_pk_add_f32 v[86:87], v[52:53], v[44:45]
	v_pk_fma_f32 v[76:77], v[76:77], v[62:63], v[82:83] op_sel:[1,1,0] op_sel_hi:[1,0,1] neg_lo:[0,1,0]
	v_pk_add_f32 v[82:83], v[34:35], v[16:17]
	v_pk_add_f32 v[16:17], v[34:35], v[16:17] neg_lo:[0,1] neg_hi:[0,1]
	v_pk_add_f32 v[44:45], v[52:53], v[44:45] neg_lo:[0,1] neg_hi:[0,1]
	v_pk_mul_f32 v[34:35], v[16:17], v[0:1] op_sel:[0,0] op_sel_hi:[0,1]
	s_nop 0
	v_pk_fma_f32 v[16:17], v[16:17], v[0:1], v[34:35] op_sel:[1,1,0] op_sel_hi:[1,0,1] neg_lo:[0,1,0]
	v_pk_add_f32 v[34:35], v[36:37], v[18:19]
	v_pk_add_f32 v[18:19], v[36:37], v[18:19] neg_lo:[0,1] neg_hi:[0,1]
	v_pk_mul_f32 v[52:53], v[44:45], v[2:3] op_sel:[0,0] op_sel_hi:[0,1]
	s_nop 0
	v_pk_mul_f32 v[36:37], v[18:19], v[4:5] op_sel:[0,0] op_sel_hi:[0,1]
	v_pk_fma_f32 v[44:45], v[44:45], v[2:3], v[52:53] op_sel:[1,1,0] op_sel_hi:[1,0,1] neg_lo:[0,1,0]
	v_pk_add_f32 v[52:53], v[72:73], v[76:77]
	v_pk_fma_f32 v[4:5], v[18:19], v[4:5], v[36:37] op_sel:[1,1,0] op_sel_hi:[1,0,1] neg_lo:[0,1,0]
	v_pk_add_f32 v[18:19], v[38:39], v[20:21]
	v_pk_add_f32 v[20:21], v[38:39], v[20:21] neg_lo:[0,1] neg_hi:[0,1]
	v_pk_add_f32 v[88:89], v[40:41], v[44:45]
	v_pk_mul_f32 v[36:37], v[20:21], v[8:9] op_sel:[0,0] op_sel_hi:[0,1]
	s_nop 0
	v_pk_fma_f32 v[20:21], v[20:21], v[8:9], v[36:37] op_sel:[1,1,0] op_sel_hi:[1,0,1] neg_lo:[0,1,0]
	v_pk_add_f32 v[36:37], v[6:7], v[22:23]
	v_pk_add_f32 v[6:7], v[6:7], v[22:23] neg_lo:[0,1] neg_hi:[0,1]
	s_nop 0
	v_pk_mul_f32 v[22:23], v[6:7], v[12:13] op_sel:[0,0] op_sel_hi:[0,1]
	s_nop 0
	v_pk_fma_f32 v[6:7], v[6:7], v[12:13], v[22:23] op_sel:[1,1,0] op_sel_hi:[1,0,1] neg_lo:[0,1,0]
	v_pk_add_f32 v[12:13], v[42:43], v[24:25]
	v_pk_add_f32 v[22:23], v[42:43], v[24:25] neg_lo:[0,1] neg_hi:[0,1]
	v_pk_add_f32 v[42:43], v[64:65], v[78:79] neg_lo:[0,1] neg_hi:[0,1]
	v_pk_mul_f32 v[24:25], v[22:23], v[2:3] op_sel:[0,0] op_sel_hi:[0,1]
	v_pk_add_f32 v[100:101], v[82:83], v[12:13]
	v_pk_fma_f32 v[22:23], v[22:23], v[2:3], v[24:25] op_sel:[1,1,0] op_sel_hi:[1,0,1] neg_lo:[0,1,0]
	v_pk_add_f32 v[24:25], v[10:11], v[26:27]
	v_pk_add_f32 v[10:11], v[10:11], v[26:27] neg_lo:[0,1] neg_hi:[0,1]
	v_pk_add_f32 v[104:105], v[34:35], v[24:25]
	v_pk_mul_f32 v[26:27], v[10:11], v[54:55] op_sel:[0,0] op_sel_hi:[0,1]
	v_pk_add_f32 v[24:25], v[34:35], v[24:25] neg_lo:[0,1] neg_hi:[0,1]
	v_pk_fma_f32 v[10:11], v[10:11], v[54:55], v[26:27] op_sel:[1,1,0] op_sel_hi:[1,0,1] neg_lo:[0,1,0]
	v_pk_add_f32 v[26:27], v[46:47], v[28:29]
	v_pk_add_f32 v[28:29], v[46:47], v[28:29] neg_lo:[0,1] neg_hi:[0,1]
	v_pk_mul_f32 v[34:35], v[24:25], v[8:9] op_sel:[0,0] op_sel_hi:[0,1]
	v_pk_mul_f32 v[46:47], v[42:43], v[0:1] op_sel:[0,0] op_sel_hi:[0,1]
	v_pk_add_f32 v[54:55], v[66:67], v[56:57] neg_lo:[0,1] neg_hi:[0,1]
	v_pk_mul_f32 v[38:39], v[28:29], v[58:59] op_sel:[0,0] op_sel_hi:[0,1]
	v_pk_fma_f32 v[24:25], v[24:25], v[8:9], v[34:35] op_sel:[1,1,0] op_sel_hi:[1,0,1] neg_lo:[0,1,0]
	v_pk_add_f32 v[34:35], v[18:19], v[26:27]
	v_pk_fma_f32 v[28:29], v[28:29], v[58:59], v[38:39] op_sel:[1,1,0] op_sel_hi:[1,0,1] neg_lo:[0,1,0]
	v_pk_add_f32 v[38:39], v[14:15], v[30:31]
	v_pk_add_f32 v[18:19], v[18:19], v[26:27] neg_lo:[0,1] neg_hi:[0,1]
; __device__ __forceinline__ float2 cmul(float2 a, float2 b) { return make_float2(a.x * b.x - a.y * b.y, a.x * b.y + a.y * b.x); }
; __device__ __forceinline__ float2 twid(float turns) { return make_float2(__builtin_amdgcn_cosf(turns), -__builtin_amdgcn_sinf(turns)); }
; template <int R, bool INV>
; __device__ __forceinline__ void butterflies(c32 (&v)[1 << R], float turns0) {
;   constexpr int RAD = 1 << R;
;   constexpr float TC[16] = {1.0f, 0.98078528040f, 0.92387953251f, 0.83146961230f, 0.70710678119f, 0.55557023302f, 0.38268343237f, 0.19509032202f,
;                             0.0f, -0.19509032202f, -0.38268343237f, -0.55557023302f, -0.70710678119f, -0.83146961230f, -0.92387953251f, -0.98078528040f};
;   constexpr float TS[16] = {0.0f, 0.19509032202f, 0.38268343237f, 0.55557023302f, 0.70710678119f, 0.83146961230f, 0.92387953251f, 0.98078528040f,
;                             1.0f, 0.98078528040f, 0.92387953251f, 0.83146961230f, 0.70710678119f, 0.55557023302f, 0.38268343237f, 0.19509032202f};
;   float2 tbs[R];
;   tbs[0] = twid(turns0);
;   if (INV) tbs[0].y = -tbs[0].y;
; #pragma unroll
;   for (int k = 1; k < R; ++k) tbs[k] = cmul(tbs[k - 1], tbs[k - 1]);
; #pragma unroll
;   for (int kk = 0; kk < R; ++kk) {
;     const int k = INV ? (R - 1 - kk) : kk;
;     const int hd = RAD >> (k + 1);
; #pragma unroll
;     for (int j = 0; j < RAD; ++j) {
;       if ((j & hd) == 0) {
;         const int m = (j & (hd - 1)) * (16 / hd);
;         const float2 c = make_float2(TC[m], INV ? TS[m] : -TS[m]);
;         const float2 twf = cmul(tbs[k], c);
;         const c32 tw = {twf.x, twf.y};
;         const c32 a = v[j], b = v[j + hd];
;         if (!INV) { v[j] = a + b; v[j + hd] = cmul_pk(a - b, tw); }
;         else { const c32 bt = cmul_pk(b, tw); v[j] = a + bt; v[j + hd] = a - bt; }
;       }
;     }
;   }
; }
; template <int LOGN>
; __device__ __forceinline__ void fft_last_to_regs(const float2* X, c32 (&kf)[32]) {
;     ...
;   for (int j = 0; j < 32; ++j) v[j] = Xc[pb + j];
;   butterflies<5, false>(v, 0.f);
	v_pk_add_f32 v[14:15], v[14:15], v[30:31] neg_lo:[0,1] neg_hi:[0,1]
	v_pk_mul_f32 v[26:27], v[18:19], v[2:3] op_sel:[0,0] op_sel_hi:[0,1]
	v_pk_fma_f32 v[42:43], v[42:43], v[0:1], v[46:47] op_sel:[1,1,0] op_sel_hi:[1,0,1] neg_lo:[0,1,0]
	v_pk_add_f32 v[46:47], v[66:67], v[56:57]
	v_pk_mul_f32 v[30:31], v[14:15], v[62:63] op_sel:[0,0] op_sel_hi:[0,1]
	v_pk_fma_f32 v[18:19], v[18:19], v[2:3], v[26:27] op_sel:[1,1,0] op_sel_hi:[1,0,1] neg_lo:[0,1,0]
	v_pk_add_f32 v[26:27], v[36:37], v[38:39]
	v_pk_add_f32 v[36:37], v[36:37], v[38:39] neg_lo:[0,1] neg_hi:[0,1]
	v_pk_fma_f32 v[14:15], v[14:15], v[62:63], v[30:31] op_sel:[1,1,0] op_sel_hi:[1,0,1] neg_lo:[0,1,0]
	v_pk_add_f32 v[30:31], v[64:65], v[78:79]
	v_pk_mul_f32 v[38:39], v[36:37], v[58:59] op_sel:[0,0] op_sel_hi:[0,1]
	v_pk_add_f32 v[62:63], v[68:69], v[80:81] neg_lo:[0,1] neg_hi:[0,1]
	v_pk_fma_f32 v[36:37], v[36:37], v[58:59], v[38:39] op_sel:[1,1,0] op_sel_hi:[1,0,1] neg_lo:[0,1,0]
	v_pk_add_f32 v[38:39], v[16:17], v[22:23]
	v_pk_mul_f32 v[64:65], v[62:63], v[2:3] op_sel:[0,0] op_sel_hi:[0,1]
	v_pk_add_f32 v[16:17], v[16:17], v[22:23] neg_lo:[0,1] neg_hi:[0,1]
	v_pk_fma_f32 v[62:63], v[62:63], v[2:3], v[64:65] op_sel:[1,1,0] op_sel_hi:[1,0,1] neg_lo:[0,1,0]
	v_pk_add_f32 v[64:65], v[70:71], v[60:61]
	v_pk_mul_f32 v[22:23], v[16:17], v[0:1] op_sel:[0,0] op_sel_hi:[0,1]
	v_pk_add_f32 v[60:61], v[70:71], v[60:61] neg_lo:[0,1] neg_hi:[0,1]
	v_pk_fma_f32 v[16:17], v[16:17], v[0:1], v[22:23] op_sel:[1,1,0] op_sel_hi:[1,0,1] neg_lo:[0,1,0]
	v_pk_add_f32 v[22:23], v[4:5], v[10:11]
	v_pk_mul_f32 v[66:67], v[60:61], v[58:59] op_sel:[0,0] op_sel_hi:[0,1]
	v_pk_add_f32 v[4:5], v[4:5], v[10:11] neg_lo:[0,1] neg_hi:[0,1]
	v_pk_mul_f32 v[56:57], v[54:55], v[8:9] op_sel:[0,0] op_sel_hi:[0,1]
	v_pk_fma_f32 v[60:61], v[60:61], v[58:59], v[66:67] op_sel:[1,1,0] op_sel_hi:[1,0,1] neg_lo:[0,1,0]
	v_pk_mul_f32 v[66:67], v[50:51], v[8:9] op_sel:[0,0] op_sel_hi:[0,1]
	v_pk_add_f32 v[12:13], v[82:83], v[12:13] neg_lo:[0,1] neg_hi:[0,1]
	v_pk_mul_f32 v[10:11], v[4:5], v[8:9] op_sel:[0,0] op_sel_hi:[0,1]
	v_pk_fma_f32 v[54:55], v[54:55], v[8:9], v[56:57] op_sel:[1,1,0] op_sel_hi:[1,0,1] neg_lo:[0,1,0]
	v_pk_fma_f32 v[50:51], v[50:51], v[8:9], v[66:67] op_sel:[1,1,0] op_sel_hi:[1,0,1] neg_lo:[0,1,0]
	v_pk_add_f32 v[56:57], v[68:69], v[80:81]
	v_pk_fma_f32 v[4:5], v[4:5], v[8:9], v[10:11] op_sel:[1,1,0] op_sel_hi:[1,0,1] neg_lo:[0,1,0]
	v_pk_add_f32 v[8:9], v[20:21], v[28:29]
	v_pk_add_f32 v[10:11], v[20:21], v[28:29] neg_lo:[0,1] neg_hi:[0,1]
	v_pk_add_f32 v[66:67], v[72:73], v[76:77] neg_lo:[0,1] neg_hi:[0,1]
	v_pk_mul_f32 v[20:21], v[10:11], v[2:3] op_sel:[0,0] op_sel_hi:[0,1]
	v_pk_add_f32 v[80:81], v[84:85], v[86:87]
	v_pk_fma_f32 v[10:11], v[10:11], v[2:3], v[20:21] op_sel:[1,1,0] op_sel_hi:[1,0,1] neg_lo:[0,1,0]
	v_pk_add_f32 v[20:21], v[6:7], v[14:15]
	v_pk_add_f32 v[6:7], v[6:7], v[14:15] neg_lo:[0,1] neg_hi:[0,1]
	v_pk_mul_f32 v[68:69], v[66:67], v[58:59] op_sel:[0,0] op_sel_hi:[0,1]
	v_pk_add_f32 v[102:103], v[104:105], v[26:27]
	v_pk_mul_f32 v[14:15], v[6:7], v[58:59] op_sel:[0,0] op_sel_hi:[0,1]
	v_pk_fma_f32 v[96:97], v[66:67], v[58:59], v[68:69] op_sel:[1,1,0] op_sel_hi:[1,0,1] neg_lo:[0,1,0]
	v_pk_mul_f32 v[66:67], v[12:13], v[0:1] op_sel:[0,0] op_sel_hi:[0,1]
	v_pk_add_f32 v[70:71], v[46:47], v[64:65]
	v_pk_fma_f32 v[6:7], v[6:7], v[58:59], v[14:15] op_sel:[1,1,0] op_sel_hi:[1,0,1] neg_lo:[0,1,0]
	v_pk_add_f32 v[14:15], v[30:31], v[56:57] neg_lo:[0,1] neg_hi:[0,1]
	v_pk_fma_f32 v[12:13], v[12:13], v[0:1], v[66:67] op_sel:[1,1,0] op_sel_hi:[1,0,1] neg_lo:[0,1,0]
	v_pk_add_f32 v[94:95], v[50:51], v[96:97]
	v_pk_mul_f32 v[28:29], v[14:15], v[0:1] op_sel:[0,0] op_sel_hi:[0,1]
	v_pk_add_f32 v[66:67], v[30:31], v[56:57]
	v_pk_fma_f32 v[68:69], v[14:15], v[0:1], v[28:29] op_sel:[1,1,0] op_sel_hi:[1,0,1] neg_lo:[0,1,0]
	v_pk_add_f32 v[14:15], v[46:47], v[64:65] neg_lo:[0,1] neg_hi:[0,1]
	v_pk_add_f32 v[112:113], v[38:39], v[8:9]
	v_pk_mul_f32 v[28:29], v[14:15], v[2:3] op_sel:[0,0] op_sel_hi:[0,1]
	v_pk_add_f32 v[8:9], v[38:39], v[8:9] neg_lo:[0,1] neg_hi:[0,1]
	v_pk_fma_f32 v[74:75], v[14:15], v[2:3], v[28:29] op_sel:[1,1,0] op_sel_hi:[1,0,1] neg_lo:[0,1,0]
	v_pk_add_f32 v[14:15], v[42:43], v[62:63] neg_lo:[0,1] neg_hi:[0,1]
	v_pk_add_f32 v[126:127], v[4:5], v[6:7]
	v_pk_mul_f32 v[28:29], v[14:15], v[0:1] op_sel:[0,0] op_sel_hi:[0,1]
	v_pk_add_f32 v[4:5], v[4:5], v[6:7] neg_lo:[0,1] neg_hi:[0,1]
	v_pk_fma_f32 v[76:77], v[14:15], v[0:1], v[28:29] op_sel:[1,1,0] op_sel_hi:[1,0,1] neg_lo:[0,1,0]
	v_pk_add_f32 v[14:15], v[54:55], v[60:61] neg_lo:[0,1] neg_hi:[0,1]
	v_pk_mul_f32 v[6:7], v[4:5], v[2:3] op_sel:[0,0] op_sel_hi:[0,1]
	v_pk_add_f32 v[72:73], v[42:43], v[62:63]
	v_pk_mul_f32 v[28:29], v[14:15], v[2:3] op_sel:[0,0] op_sel_hi:[0,1]
	v_pk_fma_f32 v[128:129], v[4:5], v[2:3], v[6:7] op_sel:[1,1,0] op_sel_hi:[1,0,1] neg_lo:[0,1,0]
	v_pk_add_f32 v[78:79], v[54:55], v[60:61]
	v_pk_fma_f32 v[82:83], v[14:15], v[2:3], v[28:29] op_sel:[1,1,0] op_sel_hi:[1,0,1] neg_lo:[0,1,0]
	v_pk_add_f32 v[14:15], v[84:85], v[86:87] neg_lo:[0,1] neg_hi:[0,1]
	v_pk_add_f32 v[86:87], v[48:49], v[52:53]
	v_pk_mul_f32 v[28:29], v[14:15], v[0:1] op_sel:[0,0] op_sel_hi:[0,1]
	v_pk_add_f32 v[110:111], v[24:25], v[36:37]
	v_pk_fma_f32 v[84:85], v[14:15], v[0:1], v[28:29] op_sel:[1,1,0] op_sel_hi:[1,0,1] neg_lo:[0,1,0]
	v_pk_add_f32 v[14:15], v[48:49], v[52:53] neg_lo:[0,1] neg_hi:[0,1]
	v_pk_add_f32 v[118:119], v[22:23], v[20:21]
	v_pk_mul_f32 v[28:29], v[14:15], v[2:3] op_sel:[0,0] op_sel_hi:[0,1]
	v_pk_add_f32 v[120:121], v[16:17], v[10:11]
	v_pk_fma_f32 v[90:91], v[14:15], v[2:3], v[28:29] op_sel:[1,1,0] op_sel_hi:[1,0,1] neg_lo:[0,1,0]
; __device__ __forceinline__ float2 cmul(float2 a, float2 b) { return make_float2(a.x * b.x - a.y * b.y, a.x * b.y + a.y * b.x); }
; template <int R, bool INV>
; __device__ __forceinline__ void butterflies(c32 (&v)[1 << R], float turns0) {
;   constexpr int RAD = 1 << R;
;   constexpr float TC[16] = {1.0f, 0.98078528040f, 0.92387953251f, 0.83146961230f, 0.70710678119f, 0.55557023302f, 0.38268343237f, 0.19509032202f,
;                             0.0f, -0.19509032202f, -0.38268343237f, -0.55557023302f, -0.70710678119f, -0.83146961230f, -0.92387953251f, -0.98078528040f};
;   constexpr float TS[16] = {0.0f, 0.19509032202f, 0.38268343237f, 0.55557023302f, 0.70710678119f, 0.83146961230f, 0.92387953251f, 0.98078528040f,
;                             1.0f, 0.98078528040f, 0.92387953251f, 0.83146961230f, 0.70710678119f, 0.55557023302f, 0.38268343237f, 0.19509032202f};
;   float2 tbs[R];
;   tbs[0] = twid(turns0);
;   if (INV) tbs[0].y = -tbs[0].y;
; #pragma unroll
;   for (int k = 1; k < R; ++k) tbs[k] = cmul(tbs[k - 1], tbs[k - 1]);
; #pragma unroll
;   for (int kk = 0; kk < R; ++kk) {
;     const int k = INV ? (R - 1 - kk) : kk;
;     const int hd = RAD >> (k + 1);
; #pragma unroll
;     for (int j = 0; j < RAD; ++j) {
;       if ((j & hd) == 0) {
;         const int m = (j & (hd - 1)) * (16 / hd);
;         const float2 c = make_float2(TC[m], INV ? TS[m] : -TS[m]);
;         const float2 twf = cmul(tbs[k], c);
;         const c32 tw = {twf.x, twf.y};
;         const c32 a = v[j], b = v[j + hd];
;         if (!INV) { v[j] = a + b; v[j + hd] = cmul_pk(a - b, tw); }
;         else { const c32 bt = cmul_pk(b, tw); v[j] = a + bt; v[j + hd] = a - bt; }
;       }
;     }
;   }
; }
; template <int LOGN, int R, int DLOG, bool INV, int MODE, class F>
; __device__ __forceinline__ void fft_pass(float2* X, const F& f) {
;     ...
;   auto fetch = [&](int g, c32 (&dst)[RAD]) {
;     const int base = gbase(g);
; #pragma unroll
;     for (int j = 0; j < RAD; ++j) { if constexpr (MODE == 1) { const float2 sv = f(base + (j << DLOG)); dst[j] = (c32){sv.x, sv.y}; } }
;   };
;   c32 nxt[RAD];
;   if constexpr (MODE == 1) fetch(tid0, nxt);
;   __device__ __forceinline__ float2 operator()(int i) const { const float2 wv = unpk2(Wd[i]); return half ? cmul(wv, twid((float)(i & (L - 1)) * invTurn)) : wv; }
	v_pk_add_f32 v[14:15], v[40:41], v[44:45] neg_lo:[0,1] neg_hi:[0,1]
	s_nop 0
	v_pk_mul_f32 v[28:29], v[14:15], v[0:1] op_sel:[0,0] op_sel_hi:[0,1]
	s_nop 0
	v_pk_fma_f32 v[92:93], v[14:15], v[0:1], v[28:29] op_sel:[1,1,0] op_sel_hi:[1,0,1] neg_lo:[0,1,0]
	v_pk_add_f32 v[14:15], v[50:51], v[96:97] neg_lo:[0,1] neg_hi:[0,1]
	v_pk_add_f32 v[96:97], v[100:101], v[34:35]
	v_pk_mul_f32 v[28:29], v[14:15], v[2:3] op_sel:[0,0] op_sel_hi:[0,1]
	s_nop 0
	v_pk_fma_f32 v[98:99], v[14:15], v[2:3], v[28:29] op_sel:[1,1,0] op_sel_hi:[1,0,1] neg_lo:[0,1,0]
	v_pk_add_f32 v[14:15], v[100:101], v[34:35] neg_lo:[0,1] neg_hi:[0,1]
	s_nop 0
	v_pk_mul_f32 v[28:29], v[14:15], v[0:1] op_sel:[0,0] op_sel_hi:[0,1]
	s_nop 0
	v_pk_fma_f32 v[100:101], v[14:15], v[0:1], v[28:29] op_sel:[1,1,0] op_sel_hi:[1,0,1] neg_lo:[0,1,0]
	v_pk_add_f32 v[14:15], v[104:105], v[26:27] neg_lo:[0,1] neg_hi:[0,1]
	v_pk_add_f32 v[104:105], v[12:13], v[18:19]
	v_pk_add_f32 v[12:13], v[12:13], v[18:19] neg_lo:[0,1] neg_hi:[0,1]
	v_pk_mul_f32 v[26:27], v[14:15], v[2:3] op_sel:[0,0] op_sel_hi:[0,1]
	s_nop 0
	v_pk_fma_f32 v[106:107], v[14:15], v[2:3], v[26:27] op_sel:[1,1,0] op_sel_hi:[1,0,1] neg_lo:[0,1,0]
	v_pk_mul_f32 v[14:15], v[12:13], v[0:1] op_sel:[0,0] op_sel_hi:[0,1]
	s_nop 0
	v_pk_fma_f32 v[108:109], v[12:13], v[0:1], v[14:15] op_sel:[1,1,0] op_sel_hi:[1,0,1] neg_lo:[0,1,0]
	v_pk_add_f32 v[12:13], v[24:25], v[36:37] neg_lo:[0,1] neg_hi:[0,1]
	s_nop 0
	v_pk_mul_f32 v[14:15], v[12:13], v[2:3] op_sel:[0,0] op_sel_hi:[0,1]
	s_nop 0
	v_pk_fma_f32 v[114:115], v[12:13], v[2:3], v[14:15] op_sel:[1,1,0] op_sel_hi:[1,0,1] neg_lo:[0,1,0]
	v_pk_mul_f32 v[12:13], v[8:9], v[0:1] op_sel:[0,0] op_sel_hi:[0,1]
	s_nop 0
	v_pk_fma_f32 v[116:117], v[8:9], v[0:1], v[12:13] op_sel:[1,1,0] op_sel_hi:[1,0,1] neg_lo:[0,1,0]
	v_pk_add_f32 v[8:9], v[22:23], v[20:21] neg_lo:[0,1] neg_hi:[0,1]
	s_nop 0
	v_pk_mul_f32 v[12:13], v[8:9], v[2:3] op_sel:[0,0] op_sel_hi:[0,1]
	s_nop 0
	v_pk_fma_f32 v[122:123], v[8:9], v[2:3], v[12:13] op_sel:[1,1,0] op_sel_hi:[1,0,1] neg_lo:[0,1,0]
	v_pk_add_f32 v[2:3], v[66:67], v[70:71] neg_lo:[0,1] neg_hi:[0,1]
	v_pk_add_f32 v[8:9], v[16:17], v[10:11] neg_lo:[0,1] neg_hi:[0,1]
	v_pk_mul_f32 v[4:5], v[2:3], v[0:1] op_sel:[0,0] op_sel_hi:[0,1]
	v_and_b32_e32 v16, 0x3ff, v130
	v_pk_fma_f32 v[64:65], v[2:3], v[0:1], v[4:5] op_sel:[1,1,0] op_sel_hi:[1,0,1] neg_lo:[0,1,0]
	v_pk_add_f32 v[2:3], v[68:69], v[74:75] neg_lo:[0,1] neg_hi:[0,1]
	v_pk_mul_f32 v[10:11], v[8:9], v[0:1] op_sel:[0,0] op_sel_hi:[0,1]
	s_nop 0
	v_pk_mul_f32 v[4:5], v[2:3], v[0:1] op_sel:[0,0] op_sel_hi:[0,1]
	v_pk_fma_f32 v[124:125], v[8:9], v[0:1], v[10:11] op_sel:[1,1,0] op_sel_hi:[1,0,1] neg_lo:[0,1,0]
	s_nop 0
	v_pk_fma_f32 v[62:63], v[2:3], v[0:1], v[4:5] op_sel:[1,1,0] op_sel_hi:[1,0,1] neg_lo:[0,1,0]
	v_pk_add_f32 v[2:3], v[72:73], v[78:79] neg_lo:[0,1] neg_hi:[0,1]
	s_nop 0
	v_pk_mul_f32 v[4:5], v[2:3], v[0:1] op_sel:[0,0] op_sel_hi:[0,1]
	s_nop 0
	v_pk_fma_f32 v[60:61], v[2:3], v[0:1], v[4:5] op_sel:[1,1,0] op_sel_hi:[1,0,1] neg_lo:[0,1,0]
	v_pk_add_f32 v[2:3], v[76:77], v[82:83] neg_lo:[0,1] neg_hi:[0,1]
	s_nop 0
	v_pk_mul_f32 v[4:5], v[2:3], v[0:1] op_sel:[0,0] op_sel_hi:[0,1]
	s_nop 0
	v_pk_fma_f32 v[58:59], v[2:3], v[0:1], v[4:5] op_sel:[1,1,0] op_sel_hi:[1,0,1] neg_lo:[0,1,0]
	v_pk_add_f32 v[2:3], v[80:81], v[86:87] neg_lo:[0,1] neg_hi:[0,1]
	s_nop 0
	v_pk_mul_f32 v[4:5], v[2:3], v[0:1] op_sel:[0,0] op_sel_hi:[0,1]
	s_nop 0
	v_pk_fma_f32 v[56:57], v[2:3], v[0:1], v[4:5] op_sel:[1,1,0] op_sel_hi:[1,0,1] neg_lo:[0,1,0]
	v_pk_add_f32 v[2:3], v[84:85], v[90:91] neg_lo:[0,1] neg_hi:[0,1]
	s_nop 0
	v_pk_mul_f32 v[4:5], v[2:3], v[0:1] op_sel:[0,0] op_sel_hi:[0,1]
	s_nop 0
	v_pk_fma_f32 v[54:55], v[2:3], v[0:1], v[4:5] op_sel:[1,1,0] op_sel_hi:[1,0,1] neg_lo:[0,1,0]
	v_pk_add_f32 v[2:3], v[88:89], v[94:95] neg_lo:[0,1] neg_hi:[0,1]
	s_nop 0
	v_pk_mul_f32 v[4:5], v[2:3], v[0:1] op_sel:[0,0] op_sel_hi:[0,1]
	s_nop 0
	v_pk_fma_f32 v[52:53], v[2:3], v[0:1], v[4:5] op_sel:[1,1,0] op_sel_hi:[1,0,1] neg_lo:[0,1,0]
	v_pk_add_f32 v[2:3], v[92:93], v[98:99] neg_lo:[0,1] neg_hi:[0,1]
	s_nop 0
	v_pk_mul_f32 v[4:5], v[2:3], v[0:1] op_sel:[0,0] op_sel_hi:[0,1]
	s_nop 0
	v_pk_fma_f32 v[50:51], v[2:3], v[0:1], v[4:5] op_sel:[1,1,0] op_sel_hi:[1,0,1] neg_lo:[0,1,0]
	v_pk_add_f32 v[2:3], v[96:97], v[102:103] neg_lo:[0,1] neg_hi:[0,1]
	s_nop 0
	v_pk_mul_f32 v[4:5], v[2:3], v[0:1] op_sel:[0,0] op_sel_hi:[0,1]
	s_nop 0
	v_pk_fma_f32 v[48:49], v[2:3], v[0:1], v[4:5] op_sel:[1,1,0] op_sel_hi:[1,0,1] neg_lo:[0,1,0]
	v_pk_add_f32 v[2:3], v[100:101], v[106:107] neg_lo:[0,1] neg_hi:[0,1]
	s_nop 0
	v_pk_mul_f32 v[4:5], v[2:3], v[0:1] op_sel:[0,0] op_sel_hi:[0,1]
	s_nop 0
	v_pk_fma_f32 v[46:47], v[2:3], v[0:1], v[4:5] op_sel:[1,1,0] op_sel_hi:[1,0,1] neg_lo:[0,1,0]
	v_pk_add_f32 v[2:3], v[104:105], v[110:111] neg_lo:[0,1] neg_hi:[0,1]
	s_nop 0
	v_pk_mul_f32 v[4:5], v[2:3], v[0:1] op_sel:[0,0] op_sel_hi:[0,1]
	s_nop 0
	v_pk_fma_f32 v[44:45], v[2:3], v[0:1], v[4:5] op_sel:[1,1,0] op_sel_hi:[1,0,1] neg_lo:[0,1,0]
	v_pk_add_f32 v[2:3], v[108:109], v[114:115] neg_lo:[0,1] neg_hi:[0,1]
	s_nop 0
	v_pk_mul_f32 v[4:5], v[2:3], v[0:1] op_sel:[0,0] op_sel_hi:[0,1]
	s_nop 0
	v_pk_fma_f32 v[42:43], v[2:3], v[0:1], v[4:5] op_sel:[1,1,0] op_sel_hi:[1,0,1] neg_lo:[0,1,0]
	v_pk_add_f32 v[2:3], v[112:113], v[118:119] neg_lo:[0,1] neg_hi:[0,1]
	s_nop 0
	v_pk_mul_f32 v[4:5], v[2:3], v[0:1] op_sel:[0,0] op_sel_hi:[0,1]
	s_nop 0
	v_pk_fma_f32 v[40:41], v[2:3], v[0:1], v[4:5] op_sel:[1,1,0] op_sel_hi:[1,0,1] neg_lo:[0,1,0]
	v_pk_add_f32 v[2:3], v[116:117], v[122:123] neg_lo:[0,1] neg_hi:[0,1]
	s_nop 0
	v_pk_mul_f32 v[4:5], v[2:3], v[0:1] op_sel:[0,0] op_sel_hi:[0,1]
	s_nop 0
	v_pk_fma_f32 v[38:39], v[2:3], v[0:1], v[4:5] op_sel:[1,1,0] op_sel_hi:[1,0,1] neg_lo:[0,1,0]
	v_pk_add_f32 v[2:3], v[120:121], v[126:127] neg_lo:[0,1] neg_hi:[0,1]
	s_nop 0
	v_pk_mul_f32 v[4:5], v[2:3], v[0:1] op_sel:[0,0] op_sel_hi:[0,1]
	s_nop 0
	v_pk_fma_f32 v[36:37], v[2:3], v[0:1], v[4:5] op_sel:[1,1,0] op_sel_hi:[1,0,1] neg_lo:[0,1,0]
	v_pk_add_f32 v[2:3], v[124:125], v[128:129] neg_lo:[0,1] neg_hi:[0,1]
	s_nop 0
	v_pk_mul_f32 v[4:5], v[2:3], v[0:1] op_sel:[0,0] op_sel_hi:[0,1]
	s_nop 0
	v_pk_fma_f32 v[34:35], v[2:3], v[0:1], v[4:5] op_sel:[1,1,0] op_sel_hi:[1,0,1] neg_lo:[0,1,0]
	v_and_or_b32 v0, v32, s79, v16
	v_ashrrev_i32_e32 v1, 31, v0
	v_lshl_add_u64 v[14:15], v[0:1], 2, s[34:35]
	v_lshlrev_b32_e32 v207, 2, v0
	v_add_u32_e32 v208, 0x1000, v207
	v_add_u32_e32 v209, 0x2000, v207
	v_add_u32_e32 v210, 0x3000, v207
	v_add_u32_e32 v211, 0x4000, v207
	v_add_u32_e32 v212, 0x5000, v207
	v_add_u32_e32 v213, 0x6000, v207
	v_add_u32_e32 v214, 0x7000, v207
	global_load_dword v207, v207, s[34:35]
	global_load_dword v208, v208, s[34:35]
	global_load_dword v209, v209, s[34:35]
	global_load_dword v210, v210, s[34:35]
	global_load_dword v211, v211, s[34:35]
	global_load_dword v212, v212, s[34:35]
	global_load_dword v213, v213, s[34:35]
	global_load_dword v214, v214, s[34:35]
	s_waitcnt vmcnt(7)
; __device__ __forceinline__ float2 cmul(float2 a, float2 b) { return make_float2(a.x * b.x - a.y * b.y, a.x * b.y + a.y * b.x); }
; __device__ __forceinline__ float2 twid(float turns) { return make_float2(__builtin_amdgcn_cosf(turns), -__builtin_amdgcn_sinf(turns)); }
; __device__ __forceinline__ float2 unpk2(unsigned w) { return make_float2(bflo(w), bfhi(w)); }
; template <int LOGN, int R, int DLOG, bool INV, int MODE, class F>
; __device__ __forceinline__ void fft_pass(float2* X, const F& f) {
;     ...
;   auto fetch = [&](int g, c32 (&dst)[RAD]) {
;     const int base = gbase(g);
; #pragma unroll
;     for (int j = 0; j < RAD; ++j) { if constexpr (MODE == 1) { const float2 sv = f(base + (j << DLOG)); dst[j] = (c32){sv.x, sv.y}; } }
;   };
;   c32 nxt[RAD];
;   if constexpr (MODE == 1) fetch(tid0, nxt);
;   __device__ __forceinline__ float2 operator()(int i) const { const float2 wv = unpk2(Wd[i]); return half ? cmul(wv, twid((float)(i & (L - 1)) * invTurn)) : wv; }
	v_mov_b32_e32 v1, v207
	s_waitcnt vmcnt(0)
	v_lshlrev_b32_e32 v0, 16, v1
	v_and_b32_e32 v1, 0xffff0000, v1
	s_cbranch_vccnz .LBB0_1025
	v_cvt_f32_u32_e32 v2, v16
	v_mul_f32_e32 v3, 0x38800000, v2
	v_sin_f32_e32 v2, v3
	v_cos_f32_e32 v4, v3
	v_pk_mul_f32 v[2:3], v[2:3], v[0:1] op_sel:[0,1] op_sel_hi:[0,0]
	v_pk_fma_f32 v[6:7], v[4:5], v[0:1], v[2:3]
	v_pk_fma_f32 v[0:1], v[4:5], v[0:1], v[2:3] op_sel_hi:[0,1,1] neg_lo:[0,0,1] neg_hi:[0,0,1]
	v_mov_b32_e32 v7, v1
	v_mov_b64_e32 v[0:1], v[6:7]
.LBB0_1025:
	v_add_co_u32_e32 v2, vcc, 0x1000, v14
	s_nop 1
	v_addc_co_u32_e32 v3, vcc, 0, v15, vcc
	s_waitcnt vmcnt(6)
	v_mov_b32_e32 v3, v208
	s_and_b64 vcc, exec, s[40:41]
	s_waitcnt vmcnt(0)
	v_lshlrev_b32_e32 v2, 16, v3
	v_and_b32_e32 v3, 0xffff0000, v3
	s_cbranch_vccnz .LBB0_1027
	v_or_b32_e32 v4, 0x400, v16
	v_cvt_f32_u32_e32 v4, v4
	v_mul_f32_e32 v5, 0x38800000, v4
	v_sin_f32_e32 v4, v5
	v_cos_f32_e32 v6, v5
	v_pk_mul_f32 v[4:5], v[4:5], v[2:3] op_sel:[0,1] op_sel_hi:[0,0]
	v_pk_fma_f32 v[8:9], v[6:7], v[2:3], v[4:5]
	v_pk_fma_f32 v[2:3], v[6:7], v[2:3], v[4:5] op_sel_hi:[0,1,1] neg_lo:[0,0,1] neg_hi:[0,0,1]
	v_mov_b32_e32 v9, v3
	v_mov_b64_e32 v[2:3], v[8:9]
.LBB0_1027:
	v_add_co_u32_e32 v4, vcc, 0x2000, v14
	s_nop 1
	v_addc_co_u32_e32 v5, vcc, 0, v15, vcc
	s_waitcnt vmcnt(5)
	v_mov_b32_e32 v5, v209
	s_and_b64 vcc, exec, s[40:41]
	s_waitcnt vmcnt(0)
	v_lshlrev_b32_e32 v4, 16, v5
	v_and_b32_e32 v5, 0xffff0000, v5
	s_cbranch_vccnz .LBB0_1029
	v_or_b32_e32 v6, 0x800, v16
	v_cvt_f32_u32_e32 v6, v6
	v_mul_f32_e32 v7, 0x38800000, v6
	v_sin_f32_e32 v6, v7
	v_cos_f32_e32 v8, v7
	v_pk_mul_f32 v[6:7], v[6:7], v[4:5] op_sel:[0,1] op_sel_hi:[0,0]
	v_pk_fma_f32 v[10:11], v[8:9], v[4:5], v[6:7]
	v_pk_fma_f32 v[4:5], v[8:9], v[4:5], v[6:7] op_sel_hi:[0,1,1] neg_lo:[0,0,1] neg_hi:[0,0,1]
	v_mov_b32_e32 v11, v5
	v_mov_b64_e32 v[4:5], v[10:11]
.LBB0_1029:
	v_add_co_u32_e32 v6, vcc, 0x3000, v14
	s_nop 1
	v_addc_co_u32_e32 v7, vcc, 0, v15, vcc
	s_waitcnt vmcnt(4)
	v_mov_b32_e32 v7, v210
	s_and_b64 vcc, exec, s[40:41]
	s_waitcnt vmcnt(0)
	v_lshlrev_b32_e32 v6, 16, v7
	v_and_b32_e32 v7, 0xffff0000, v7
	s_cbranch_vccnz .LBB0_1031
	v_or_b32_e32 v8, 0xc00, v16
	v_cvt_f32_u32_e32 v8, v8
	v_mul_f32_e32 v9, 0x38800000, v8
	v_sin_f32_e32 v8, v9
	v_cos_f32_e32 v10, v9
	v_pk_mul_f32 v[8:9], v[8:9], v[6:7] op_sel:[0,1] op_sel_hi:[0,0]
	v_pk_fma_f32 v[12:13], v[10:11], v[6:7], v[8:9]
	v_pk_fma_f32 v[6:7], v[10:11], v[6:7], v[8:9] op_sel_hi:[0,1,1] neg_lo:[0,0,1] neg_hi:[0,0,1]
	v_mov_b32_e32 v13, v7
	v_mov_b64_e32 v[6:7], v[12:13]
.LBB0_1031:
	v_add_co_u32_e32 v8, vcc, 0x4000, v14
	s_nop 1
	v_addc_co_u32_e32 v9, vcc, 0, v15, vcc
	s_waitcnt vmcnt(3)
	v_mov_b32_e32 v9, v211
	s_and_b64 vcc, exec, s[40:41]
	s_waitcnt vmcnt(0)
	v_lshlrev_b32_e32 v8, 16, v9
	v_and_b32_e32 v9, 0xffff0000, v9
	s_cbranch_vccnz .LBB0_1033
	v_or_b32_e32 v10, 0x1000, v16
	v_cvt_f32_u32_e32 v10, v10
	v_mul_f32_e32 v11, 0x38800000, v10
	v_sin_f32_e32 v10, v11
	v_cos_f32_e32 v12, v11
	v_pk_mul_f32 v[10:11], v[10:11], v[8:9] op_sel:[0,1] op_sel_hi:[0,0]
	v_pk_fma_f32 v[18:19], v[12:13], v[8:9], v[10:11]
	v_pk_fma_f32 v[8:9], v[12:13], v[8:9], v[10:11] op_sel_hi:[0,1,1] neg_lo:[0,0,1] neg_hi:[0,0,1]
	v_mov_b32_e32 v19, v9
	v_mov_b64_e32 v[8:9], v[18:19]
.LBB0_1033:
	v_add_co_u32_e32 v10, vcc, 0x5000, v14
	s_nop 1
	v_addc_co_u32_e32 v11, vcc, 0, v15, vcc
	s_waitcnt vmcnt(2)
	v_mov_b32_e32 v11, v212
	s_and_b64 vcc, exec, s[40:41]
	s_waitcnt vmcnt(0)
	v_lshlrev_b32_e32 v10, 16, v11
	v_and_b32_e32 v11, 0xffff0000, v11
	s_cbranch_vccnz .LBB0_1035
	v_or_b32_e32 v12, 0x1400, v16
	v_cvt_f32_u32_e32 v12, v12
	v_mul_f32_e32 v13, 0x38800000, v12
	v_sin_f32_e32 v12, v13
	v_cos_f32_e32 v18, v13
	v_pk_mul_f32 v[12:13], v[12:13], v[10:11] op_sel:[0,1] op_sel_hi:[0,0]
	v_pk_fma_f32 v[20:21], v[18:19], v[10:11], v[12:13]
	v_pk_fma_f32 v[10:11], v[18:19], v[10:11], v[12:13] op_sel_hi:[0,1,1] neg_lo:[0,0,1] neg_hi:[0,0,1]
	v_mov_b32_e32 v21, v11
	v_mov_b64_e32 v[10:11], v[20:21]
.LBB0_1035:
	v_add_co_u32_e32 v12, vcc, 0x6000, v14
	s_nop 1
	v_addc_co_u32_e32 v13, vcc, 0, v15, vcc
	s_waitcnt vmcnt(1)
	v_mov_b32_e32 v13, v213
	s_and_b64 vcc, exec, s[40:41]
	s_waitcnt vmcnt(0)
	v_lshlrev_b32_e32 v12, 16, v13
	v_and_b32_e32 v13, 0xffff0000, v13
	s_cbranch_vccnz .LBB0_1037
	v_or_b32_e32 v17, 0x1800, v16
	v_cvt_f32_u32_e32 v17, v17
	v_mul_f32_e32 v17, 0x38800000, v17
	v_sin_f32_e32 v18, v17
	v_cos_f32_e32 v20, v17
	v_pk_mul_f32 v[18:19], v[18:19], v[12:13] op_sel:[0,1] op_sel_hi:[0,0]
	v_pk_fma_f32 v[22:23], v[20:21], v[12:13], v[18:19]
	v_pk_fma_f32 v[12:13], v[20:21], v[12:13], v[18:19] op_sel_hi:[0,1,1] neg_lo:[0,0,1] neg_hi:[0,0,1]
	v_mov_b32_e32 v23, v13
	v_mov_b64_e32 v[12:13], v[22:23]
.LBB0_1037:
	v_add_co_u32_e32 v14, vcc, 0x7000, v14
	s_nop 1
	v_addc_co_u32_e32 v15, vcc, 0, v15, vcc
	s_waitcnt vmcnt(0)
	v_mov_b32_e32 v15, v214
	s_and_b64 vcc, exec, s[40:41]
	s_waitcnt vmcnt(0)
	v_lshlrev_b32_e32 v14, 16, v15
	v_and_b32_e32 v15, 0xffff0000, v15
	s_cbranch_vccnz .LBB0_1039
	v_or_b32_e32 v16, 0x1c00, v16
	v_cvt_f32_u32_e32 v16, v16
	v_mul_f32_e32 v17, 0x38800000, v16
	v_sin_f32_e32 v16, v17
	v_cos_f32_e32 v18, v17
	v_pk_mul_f32 v[16:17], v[16:17], v[14:15] op_sel:[0,1] op_sel_hi:[0,0]
	v_pk_fma_f32 v[20:21], v[18:19], v[14:15], v[16:17]
	v_pk_fma_f32 v[14:15], v[18:19], v[14:15], v[16:17] op_sel_hi:[0,1,1] neg_lo:[0,0,1] neg_hi:[0,0,1]
	v_mov_b32_e32 v21, v15
	v_mov_b64_e32 v[14:15], v[20:21]

; __device__ __forceinline__ float2 cmul(float2 a, float2 b) { return make_float2(a.x * b.x - a.y * b.y, a.x * b.y + a.y * b.x); }
; __device__ __forceinline__ float2 twid(float turns) { return make_float2(__builtin_amdgcn_cosf(turns), -__builtin_amdgcn_sinf(turns)); }
; __device__ __forceinline__ float2 unpk2(unsigned w) { return make_float2(bflo(w), bfhi(w)); }
; template <int LOGN, int R, int DLOG, bool INV, int MODE, class F>
; __device__ __forceinline__ void fft_pass(float2* X, const F& f) {
;     ...
;   auto fetch = [&](int g, c32 (&dst)[RAD]) {
;     const int base = gbase(g);
; #pragma unroll
;     for (int j = 0; j < RAD; ++j) { if constexpr (MODE == 1) { const float2 sv = f(base + (j << DLOG)); dst[j] = (c32){sv.x, sv.y}; } }
;   };
;     ...
;   for (int g = tid0; g < NGR; g += 512) {
;     const int lo = g & (dmin - 1), base = gbase(g), pb = phys(base);
;     c32 v[RAD];
;     if constexpr (MODE == 1) {
; #pragma unroll
;       for (int j = 0; j < RAD; ++j) v[j] = nxt[j];
;       if (g + 512 < NGR) fetch(g + 512, nxt);
;   __device__ __forceinline__ float2 operator()(int i) const { const float2 wv = unpk2(Wd[i]); return half ? cmul(wv, twid((float)(i & (L - 1)) * invTurn)) : wv; }
.LBB0_1042:
	v_cmp_lt_i32_e64 s[0:1], s74, v130
	v_add_u32_e32 v131, 0x1000, v32
	s_and_saveexec_b64 s[54:55], s[0:1]
	s_xor_b64 s[54:55], exec, s[54:55]
	v_add_u32_e32 v131, 0x1000, v32
	s_or_saveexec_b64 s[54:55], s[54:55]
	v_mov_b64_e32 v[30:31], v[14:15]
	v_add_u32_e32 v132, 0x200, v130
	v_mov_b64_e32 v[28:29], v[12:13]
	v_mov_b64_e32 v[26:27], v[10:11]
	v_mov_b64_e32 v[24:25], v[8:9]
	v_mov_b64_e32 v[22:23], v[6:7]
	v_mov_b64_e32 v[20:21], v[4:5]
	v_mov_b64_e32 v[18:19], v[2:3]
	v_mov_b64_e32 v[16:17], v[0:1]
	s_xor_b64 exec, exec, s[54:55]
	s_cbranch_execz .LBB0_1041
	v_and_b32_e32 v133, 0x3ff, v132
	v_and_or_b32 v16, v131, s79, v133
	v_ashrrev_i32_e32 v17, 31, v16
	v_lshl_add_u64 v[30:31], v[16:17], 2, s[34:35]
	v_lshlrev_b32_e32 v207, 2, v16
	v_add_u32_e32 v208, 0x1000, v207
	v_add_u32_e32 v209, 0x2000, v207
	v_add_u32_e32 v210, 0x3000, v207
	v_add_u32_e32 v211, 0x4000, v207
	v_add_u32_e32 v212, 0x5000, v207
	v_add_u32_e32 v213, 0x6000, v207
	v_add_u32_e32 v214, 0x7000, v207
	global_load_dword v207, v207, s[34:35]
	global_load_dword v208, v208, s[34:35]
	global_load_dword v209, v209, s[34:35]
	global_load_dword v210, v210, s[34:35]
	global_load_dword v211, v211, s[34:35]
	global_load_dword v212, v212, s[34:35]
	global_load_dword v213, v213, s[34:35]
	global_load_dword v214, v214, s[34:35]
	s_waitcnt vmcnt(7)
	v_mov_b32_e32 v17, v207
	s_and_b64 vcc, exec, s[40:41]
	s_waitcnt vmcnt(0)
	v_lshlrev_b32_e32 v16, 16, v17
	v_and_b32_e32 v17, 0xffff0000, v17
	s_cbranch_vccnz .LBB0_1047
	v_cvt_f32_u32_e32 v18, v133
	v_mul_f32_e32 v19, 0x38800000, v18
	v_sin_f32_e32 v18, v19
	v_cos_f32_e32 v20, v19
	v_pk_mul_f32 v[18:19], v[18:19], v[16:17] op_sel:[0,1] op_sel_hi:[0,0]
	v_pk_fma_f32 v[22:23], v[20:21], v[16:17], v[18:19]
	v_pk_fma_f32 v[16:17], v[20:21], v[16:17], v[18:19] op_sel_hi:[0,1,1] neg_lo:[0,0,1] neg_hi:[0,0,1]
	v_mov_b32_e32 v23, v17
	v_mov_b64_e32 v[16:17], v[22:23]
.LBB0_1047:
	v_add_co_u32_e32 v18, vcc, 0x1000, v30
	s_nop 1
	v_addc_co_u32_e32 v19, vcc, 0, v31, vcc
	s_waitcnt vmcnt(6)
	v_mov_b32_e32 v19, v208
	s_and_b64 vcc, exec, s[40:41]
	s_waitcnt vmcnt(0)
	v_lshlrev_b32_e32 v18, 16, v19
	v_and_b32_e32 v19, 0xffff0000, v19
	s_cbranch_vccnz .LBB0_1049
	v_or_b32_e32 v20, 0x400, v133
	v_cvt_f32_u32_e32 v20, v20
	v_mul_f32_e32 v21, 0x38800000, v20
	v_sin_f32_e32 v20, v21
	v_cos_f32_e32 v22, v21
	v_pk_mul_f32 v[20:21], v[20:21], v[18:19] op_sel:[0,1] op_sel_hi:[0,0]
	v_pk_fma_f32 v[24:25], v[22:23], v[18:19], v[20:21]
	v_pk_fma_f32 v[18:19], v[22:23], v[18:19], v[20:21] op_sel_hi:[0,1,1] neg_lo:[0,0,1] neg_hi:[0,0,1]
	v_mov_b32_e32 v25, v19
	v_mov_b64_e32 v[18:19], v[24:25]
.LBB0_1049:
	v_add_co_u32_e32 v20, vcc, 0x2000, v30
	s_nop 1
	v_addc_co_u32_e32 v21, vcc, 0, v31, vcc
	s_waitcnt vmcnt(5)
	v_mov_b32_e32 v21, v209
	s_and_b64 vcc, exec, s[40:41]
	s_waitcnt vmcnt(0)
	v_lshlrev_b32_e32 v20, 16, v21
	v_and_b32_e32 v21, 0xffff0000, v21
	s_cbranch_vccnz .LBB0_1051
	v_or_b32_e32 v22, 0x800, v133
	v_cvt_f32_u32_e32 v22, v22
	v_mul_f32_e32 v23, 0x38800000, v22
	v_sin_f32_e32 v22, v23
	v_cos_f32_e32 v24, v23
	v_pk_mul_f32 v[22:23], v[22:23], v[20:21] op_sel:[0,1] op_sel_hi:[0,0]
	v_pk_fma_f32 v[26:27], v[24:25], v[20:21], v[22:23]
	v_pk_fma_f32 v[20:21], v[24:25], v[20:21], v[22:23] op_sel_hi:[0,1,1] neg_lo:[0,0,1] neg_hi:[0,0,1]
	v_mov_b32_e32 v27, v21
	v_mov_b64_e32 v[20:21], v[26:27]
.LBB0_1051:
	v_add_co_u32_e32 v22, vcc, 0x3000, v30
	s_nop 1
	v_addc_co_u32_e32 v23, vcc, 0, v31, vcc
	s_waitcnt vmcnt(4)
	v_mov_b32_e32 v23, v210
	s_and_b64 vcc, exec, s[40:41]
	s_waitcnt vmcnt(0)
	v_lshlrev_b32_e32 v22, 16, v23
	v_and_b32_e32 v23, 0xffff0000, v23
	s_cbranch_vccnz .LBB0_1053
	v_or_b32_e32 v24, 0xc00, v133
	v_cvt_f32_u32_e32 v24, v24
	v_mul_f32_e32 v25, 0x38800000, v24
	v_sin_f32_e32 v24, v25
	v_cos_f32_e32 v26, v25
	v_pk_mul_f32 v[24:25], v[24:25], v[22:23] op_sel:[0,1] op_sel_hi:[0,0]
	v_pk_fma_f32 v[28:29], v[26:27], v[22:23], v[24:25]
	v_pk_fma_f32 v[22:23], v[26:27], v[22:23], v[24:25] op_sel_hi:[0,1,1] neg_lo:[0,0,1] neg_hi:[0,0,1]
	v_mov_b32_e32 v29, v23
	v_mov_b64_e32 v[22:23], v[28:29]
.LBB0_1053:
	v_add_co_u32_e32 v24, vcc, 0x4000, v30
	s_nop 1
	v_addc_co_u32_e32 v25, vcc, 0, v31, vcc
	s_waitcnt vmcnt(3)
	v_mov_b32_e32 v25, v211
	s_and_b64 vcc, exec, s[40:41]
	s_waitcnt vmcnt(0)
	v_lshlrev_b32_e32 v24, 16, v25
	v_and_b32_e32 v25, 0xffff0000, v25
	s_cbranch_vccnz .LBB0_1055
	v_or_b32_e32 v26, 0x1000, v133
	v_cvt_f32_u32_e32 v26, v26
	v_mul_f32_e32 v27, 0x38800000, v26
	v_sin_f32_e32 v26, v27
	v_cos_f32_e32 v28, v27
	v_pk_mul_f32 v[26:27], v[26:27], v[24:25] op_sel:[0,1] op_sel_hi:[0,0]
	v_pk_fma_f32 v[134:135], v[28:29], v[24:25], v[26:27]
	v_pk_fma_f32 v[24:25], v[28:29], v[24:25], v[26:27] op_sel_hi:[0,1,1] neg_lo:[0,0,1] neg_hi:[0,0,1]
	v_mov_b32_e32 v135, v25
	v_mov_b64_e32 v[24:25], v[134:135]
.LBB0_1055:
	v_add_co_u32_e32 v26, vcc, 0x5000, v30
	s_nop 1
	v_addc_co_u32_e32 v27, vcc, 0, v31, vcc
	s_waitcnt vmcnt(2)
	v_mov_b32_e32 v27, v212
	s_and_b64 vcc, exec, s[40:41]
	s_waitcnt vmcnt(0)
	v_lshlrev_b32_e32 v26, 16, v27
	v_and_b32_e32 v27, 0xffff0000, v27
	s_cbranch_vccnz .LBB0_1057
	v_or_b32_e32 v28, 0x1400, v133
	v_cvt_f32_u32_e32 v28, v28
	v_mul_f32_e32 v29, 0x38800000, v28
	v_sin_f32_e32 v28, v29
	v_cos_f32_e32 v134, v29
	v_pk_mul_f32 v[28:29], v[28:29], v[26:27] op_sel:[0,1] op_sel_hi:[0,0]
	v_pk_fma_f32 v[136:137], v[134:135], v[26:27], v[28:29]
	v_pk_fma_f32 v[26:27], v[134:135], v[26:27], v[28:29] op_sel_hi:[0,1,1] neg_lo:[0,0,1] neg_hi:[0,0,1]
	v_mov_b32_e32 v137, v27
	v_mov_b64_e32 v[26:27], v[136:137]
.LBB0_1057:
	v_add_co_u32_e32 v28, vcc, 0x6000, v30
	s_nop 1
	v_addc_co_u32_e32 v29, vcc, 0, v31, vcc
	s_waitcnt vmcnt(1)
	v_mov_b32_e32 v29, v213
	s_and_b64 vcc, exec, s[40:41]
	s_waitcnt vmcnt(0)
	v_lshlrev_b32_e32 v28, 16, v29
	v_and_b32_e32 v29, 0xffff0000, v29
	s_cbranch_vccnz .LBB0_1059
	v_or_b32_e32 v134, 0x1800, v133
	v_cvt_f32_u32_e32 v134, v134
	v_mul_f32_e32 v135, 0x38800000, v134
	v_sin_f32_e32 v134, v135
	v_cos_f32_e32 v136, v135
	v_pk_mul_f32 v[134:135], v[134:135], v[28:29] op_sel:[0,1] op_sel_hi:[0,0]
	v_pk_fma_f32 v[138:139], v[136:137], v[28:29], v[134:135]
	v_pk_fma_f32 v[28:29], v[136:137], v[28:29], v[134:135] op_sel_hi:[0,1,1] neg_lo:[0,0,1] neg_hi:[0,0,1]
	v_mov_b32_e32 v139, v29
	v_mov_b64_e32 v[28:29], v[138:139]
.LBB0_1059:
	v_add_co_u32_e32 v30, vcc, 0x7000, v30
	s_nop 1
	v_addc_co_u32_e32 v31, vcc, 0, v31, vcc
	s_waitcnt vmcnt(0)
	v_mov_b32_e32 v31, v214
	s_and_b64 vcc, exec, s[40:41]
	s_waitcnt vmcnt(0)
	v_lshlrev_b32_e32 v30, 16, v31
	v_and_b32_e32 v31, 0xffff0000, v31
	s_cbranch_vccnz .LBB0_1041
	v_or_b32_e32 v133, 0x1c00, v133
	v_cvt_f32_u32_e32 v133, v133
	v_mul_f32_e32 v133, 0x38800000, v133
	v_sin_f32_e32 v134, v133
	v_cos_f32_e32 v136, v133
	v_pk_mul_f32 v[134:135], v[134:135], v[30:31] op_sel:[0,1] op_sel_hi:[0,0]
	v_pk_fma_f32 v[138:139], v[136:137], v[30:31], v[134:135]
	v_pk_fma_f32 v[30:31], v[136:137], v[30:31], v[134:135] op_sel_hi:[0,1,1] neg_lo:[0,0,1] neg_hi:[0,0,1]
	v_mov_b32_e32 v139, v31
	v_mov_b64_e32 v[30:31], v[138:139]
	s_branch .LBB0_1041
